# GEMM ph4 DMA wait relaxed vmcnt(6) to vmcnt(10) with per-phase vmcnt(10) at ph5 and ph6 (deeper prefetch in second half)
# baseline (speedup 1.0000x reference)
; #define G_STAGE(bufoff, gbase) do { _Pragma("unroll") for (int _i = 0; _i < 2; ++_i) \
;     __builtin_amdgcn_global_load_lds((const unsigned*)((const char*)(gbase) + voff[_i]), (GLAS unsigned*)(lds + (bufoff) + ldsw + _i * 8192), 16, 0, 0); } while (0)
; #define G_LDA(dst, b, h) do { _Pragma("unroll") for (int m = 0; m < 4; ++m) _Pragma("unroll") for (int k = 0; k < 2; ++k) \
;     dst[m][k] = *(const GLAS bf16x8*)(lds + G_SA(b, h) + aoff + m * 2048 + k * 1024); } while (0)
; #define G_LDB(dst, b, h) do { _Pragma("unroll") for (int n = 0; n < 2; ++n) _Pragma("unroll") for (int k = 0; k < 2; ++k) \
;     dst[n][k] = *(const GLAS bf16x8*)(lds + G_SB(b, h) + boff + n * 2048 + k * 1024); } while (0)
; #define G_MMA(ai, bj, At_, Bt_) do { __builtin_amdgcn_s_setprio(1); \
;     _Pragma("unroll") for (int m = 0; m < 4; ++m) _Pragma("unroll") for (int n = 0; n < 2; ++n) _Pragma("unroll") for (int k = 0; k < 2; ++k) \
;       acc[ai][bj][m][n] = __builtin_amdgcn_mfma_f32_16x16x32_bf16(Bt_[n][k], At_[m][k], acc[ai][bj][m][n], 0, 0, 0); \
;     __builtin_amdgcn_s_setprio(0); } while (0)
; #define G_WAIT_L(n) asm volatile("s_waitcnt lgkmcnt(" #n ")" ::: "memory")
; #define G_BAR __builtin_amdgcn_s_barrier()
; #define G_SCHED __builtin_amdgcn_sched_barrier(0)
; __device__ __forceinline__ void gemm_phase(const Params& p, int l, const bf16_t* __restrict__ A, const bf16_t* __restrict__ Bt, int M, int N, int K,
;                            int epi, bf16_t* __restrict__ outp, char* smem, int wvi) {
;     ...
;       for (int t = 0; t < nt; t += 2) {
;         const bool lastt = (t == nt - 2);
;         const char* a1 = cA + (size_t)(t + 1) * kstep;
;         const char* a2 = lastt ? nA : cA + (size_t)(t + 2) * kstep; const char* b2 = lastt ? nB : cB + (size_t)(t + 2) * kstep;
;         const char* a3 = a2 + kstep; const char* b3 = b2 + kstep;
;         G_LDB(B0, 0, 0); G_SCHED; G_LDA(At, 0, 0); G_STAGE(G_SA(1, 1), a1 + hstep);
;         G_WAIT_L(8); G_BAR; G_WAIT_L(0); G_MMA(0, 0, At, B0); G_BAR; G_SCHED;
;         G_LDB(B1, 0, 1); G_STAGE(G_SB(0, 0), b2);
;         G_BAR; G_WAIT_L(0); G_MMA(0, 1, At, B1); G_BAR;
;         G_LDA(At, 0, 1); G_STAGE(G_SA(0, 0), a2);
;         G_BAR; G_WAIT_L(0); G_MMA(1, 0, At, B0); G_BAR; G_SCHED;
.LBB0_121:
	s_add_u32 s2, s10, 0x100
	s_addc_u32 s3, s11, 0
	s_add_i32 s34, 0, 0x10000
	s_cmp_eq_u32 s67, 40
	s_cselect_b32 s15, s5, s3
	s_cselect_b32 s14, s4, s2
	s_cselect_b32 s13, s53, s63
	s_cselect_b32 s12, s31, s55
	v_lshl_add_u64 v[190:191], s[10:11], 0, v[132:133]
	s_add_i32 m0, s22, 0xc000
	ds_read_b128 v[156:159], v138
	ds_read_b128 v[160:163], v138 offset:1024
	ds_read_b128 v[164:167], v138 offset:2048
	ds_read_b128 v[168:171], v138 offset:3072
	ds_read_b128 v[172:175], v138 offset:4096
	ds_read_b128 v[182:185], v138 offset:5120
	ds_read_b128 v[186:189], v138 offset:6144
	ds_read_b128 v[214:217], v138 offset:7168
	global_load_lds_dwordx4 v[190:191], off
	v_lshl_add_u64 v[190:191], s[10:11], 0, v[134:135]
	s_add_i32 m0, s22, 0xe000
	s_nop 0
	global_load_lds_dwordx4 v[190:191], off
	s_waitcnt lgkmcnt(8)
	s_barrier
	s_waitcnt lgkmcnt(0)
	s_waitcnt lgkmcnt(0)
	v_mfma_f32_16x16x32_bf16 v[20:23], v[140:143], v[156:159], v[20:23]
	v_mfma_f32_16x16x32_bf16 v[28:31], v[148:151], v[156:159], v[28:31]
	v_mfma_f32_16x16x32_bf16 v[12:15], v[140:143], v[164:167], v[12:15]
	v_mfma_f32_16x16x32_bf16 v[24:27], v[148:151], v[164:167], v[24:27]
	v_mfma_f32_16x16x32_bf16 v[4:7], v[140:143], v[172:175], v[4:7]
	v_mfma_f32_16x16x32_bf16 v[16:19], v[148:151], v[172:175], v[16:19]
	v_mfma_f32_16x16x32_bf16 v[0:3], v[140:143], v[186:189], v[0:3]
	v_mfma_f32_16x16x32_bf16 v[8:11], v[148:151], v[186:189], v[8:11]
	v_mfma_f32_16x16x32_bf16 v[20:23], v[144:147], v[160:163], v[20:23]
	v_mfma_f32_16x16x32_bf16 v[28:31], v[152:155], v[160:163], v[28:31]
	v_mfma_f32_16x16x32_bf16 v[12:15], v[144:147], v[168:171], v[12:15]
	v_mfma_f32_16x16x32_bf16 v[24:27], v[152:155], v[168:171], v[24:27]
	v_mfma_f32_16x16x32_bf16 v[4:7], v[144:147], v[182:185], v[4:7]
	v_mfma_f32_16x16x32_bf16 v[16:19], v[152:155], v[182:185], v[16:19]
	v_mfma_f32_16x16x32_bf16 v[0:3], v[144:147], v[214:217], v[0:3]
	v_mfma_f32_16x16x32_bf16 v[8:11], v[152:155], v[214:217], v[8:11]
	s_barrier
	s_add_i32 s35, 0, 0x14000
	s_add_i32 s10, s34, s58
	v_add_u32_e32 v139, s35, v137
	v_lshl_add_u64 v[190:191], s[12:13], 0, v[176:177]
	s_mov_b32 m0, s10
	ds_read_b128 v[218:221], v139
	ds_read_b128 v[222:225], v139 offset:1024
	ds_read_b128 v[226:229], v139 offset:2048
	ds_read_b128 v[230:233], v139 offset:3072
	global_load_lds_dwordx4 v[190:191], off
	v_lshl_add_u64 v[234:235], s[12:13], 0, v[128:129]
	s_add_i32 m0, s10, 0x2000
	s_nop 0
	global_load_lds_dwordx4 v[234:235], off
	s_barrier
	s_waitcnt lgkmcnt(0)
	s_waitcnt lgkmcnt(0)
	v_mfma_f32_16x16x32_bf16 v[80:83], v[218:221], v[156:159], v[80:83]
	v_mfma_f32_16x16x32_bf16 v[92:95], v[226:229], v[156:159], v[92:95]
	v_mfma_f32_16x16x32_bf16 v[64:67], v[218:221], v[164:167], v[64:67]
	v_mfma_f32_16x16x32_bf16 v[84:87], v[226:229], v[164:167], v[84:87]
	v_mfma_f32_16x16x32_bf16 v[52:55], v[218:221], v[172:175], v[52:55]
	v_mfma_f32_16x16x32_bf16 v[76:79], v[226:229], v[172:175], v[76:79]
	v_mfma_f32_16x16x32_bf16 v[40:43], v[218:221], v[186:189], v[40:43]
	v_mfma_f32_16x16x32_bf16 v[60:63], v[226:229], v[186:189], v[60:63]
	v_mfma_f32_16x16x32_bf16 v[80:83], v[222:225], v[160:163], v[80:83]
	v_mfma_f32_16x16x32_bf16 v[92:95], v[230:233], v[160:163], v[92:95]
	v_mfma_f32_16x16x32_bf16 v[64:67], v[222:225], v[168:171], v[64:67]
	v_mfma_f32_16x16x32_bf16 v[84:87], v[230:233], v[168:171], v[84:87]
	v_mfma_f32_16x16x32_bf16 v[52:55], v[222:225], v[182:185], v[52:55]
	v_mfma_f32_16x16x32_bf16 v[76:79], v[230:233], v[182:185], v[76:79]
	v_mfma_f32_16x16x32_bf16 v[40:43], v[222:225], v[214:217], v[40:43]
	v_mfma_f32_16x16x32_bf16 v[60:63], v[230:233], v[214:217], v[60:63]
	s_mov_b32 m0, s22
	v_lshl_add_u64 v[236:237], s[14:15], 0, v[176:177]
	s_barrier
	ds_read_b128 v[156:159], v138 offset:16384
	ds_read_b128 v[160:163], v138 offset:17408
	ds_read_b128 v[164:167], v138 offset:18432
	ds_read_b128 v[168:171], v138 offset:19456
	ds_read_b128 v[172:175], v138 offset:20480
	ds_read_b128 v[182:185], v138 offset:21504
	ds_read_b128 v[186:189], v138 offset:22528
	ds_read_b128 v[214:217], v138 offset:23552
	global_load_lds_dwordx4 v[236:237], off
	v_lshl_add_u64 v[238:239], s[14:15], 0, v[128:129]
	s_mov_b32 m0, s23
	s_nop 0
	global_load_lds_dwordx4 v[238:239], off
	s_waitcnt vmcnt(10)
	s_barrier
	s_waitcnt lgkmcnt(0)
	s_waitcnt lgkmcnt(0)
	v_mfma_f32_16x16x32_bf16 v[68:71], v[140:143], v[156:159], v[68:71]
	v_mfma_f32_16x16x32_bf16 v[88:91], v[148:151], v[156:159], v[88:91]
	v_mfma_f32_16x16x32_bf16 v[48:51], v[140:143], v[164:167], v[48:51]
	v_mfma_f32_16x16x32_bf16 v[72:75], v[148:151], v[164:167], v[72:75]
	v_mfma_f32_16x16x32_bf16 v[36:39], v[140:143], v[172:175], v[36:39]
	v_mfma_f32_16x16x32_bf16 v[56:59], v[148:151], v[172:175], v[56:59]
	v_mfma_f32_16x16x32_bf16 v[32:35], v[140:143], v[186:189], v[32:35]
	v_mfma_f32_16x16x32_bf16 v[44:47], v[148:151], v[186:189], v[44:47]
	v_mfma_f32_16x16x32_bf16 v[68:71], v[144:147], v[160:163], v[68:71]
	v_mfma_f32_16x16x32_bf16 v[88:91], v[152:155], v[160:163], v[88:91]
	v_mfma_f32_16x16x32_bf16 v[48:51], v[144:147], v[168:171], v[48:51]
	v_mfma_f32_16x16x32_bf16 v[72:75], v[152:155], v[168:171], v[72:75]
	v_mfma_f32_16x16x32_bf16 v[36:39], v[144:147], v[182:185], v[36:39]
	v_mfma_f32_16x16x32_bf16 v[56:59], v[152:155], v[182:185], v[56:59]
	v_mfma_f32_16x16x32_bf16 v[32:35], v[144:147], v[214:217], v[32:35]
	v_mfma_f32_16x16x32_bf16 v[44:47], v[152:155], v[214:217], v[44:47]
	s_barrier
; #define G_STAGE(bufoff, gbase) do { _Pragma("unroll") for (int _i = 0; _i < 2; ++_i) \
;     __builtin_amdgcn_global_load_lds((const unsigned*)((const char*)(gbase) + voff[_i]), (GLAS unsigned*)(lds + (bufoff) + ldsw + _i * 8192), 16, 0, 0); } while (0)
; #define G_LDA(dst, b, h) do { _Pragma("unroll") for (int m = 0; m < 4; ++m) _Pragma("unroll") for (int k = 0; k < 2; ++k) \
;     dst[m][k] = *(const GLAS bf16x8*)(lds + G_SA(b, h) + aoff + m * 2048 + k * 1024); } while (0)
; #define G_LDB(dst, b, h) do { _Pragma("unroll") for (int n = 0; n < 2; ++n) _Pragma("unroll") for (int k = 0; k < 2; ++k) \
;     dst[n][k] = *(const GLAS bf16x8*)(lds + G_SB(b, h) + boff + n * 2048 + k * 1024); } while (0)
; #define G_MMA(ai, bj, At_, Bt_) do { __builtin_amdgcn_s_setprio(1); \
;     _Pragma("unroll") for (int m = 0; m < 4; ++m) _Pragma("unroll") for (int n = 0; n < 2; ++n) _Pragma("unroll") for (int k = 0; k < 2; ++k) \
;       acc[ai][bj][m][n] = __builtin_amdgcn_mfma_f32_16x16x32_bf16(Bt_[n][k], At_[m][k], acc[ai][bj][m][n], 0, 0, 0); \
;     __builtin_amdgcn_s_setprio(0); } while (0)
; #define G_WAIT_V(n) asm volatile("s_waitcnt vmcnt(" #n ")" ::: "memory")
; #define G_WAIT_L(n) asm volatile("s_waitcnt lgkmcnt(" #n ")" ::: "memory")
; #define G_BAR __builtin_amdgcn_s_barrier()
; #define G_SCHED __builtin_amdgcn_sched_barrier(0)
; __device__ __forceinline__ void gemm_phase(const Params& p, int l, const bf16_t* __restrict__ A, const bf16_t* __restrict__ Bt, int M, int N, int K,
;                            int epi, bf16_t* __restrict__ outp, char* smem, int wvi) {
;     ...
;         G_STAGE(G_SB(0, 1), b2 + hstep);
;         G_WAIT_V(6); G_BAR; G_MMA(1, 1, At, B1); G_BAR;
;         G_LDB(B0, 1, 0); G_SCHED; G_LDA(At, 1, 0); G_STAGE(G_SA(0, 1), a2 + hstep);
;         G_WAIT_L(8); G_BAR; G_WAIT_L(0); G_MMA(0, 0, At, B0); G_BAR; G_SCHED;
;         G_LDB(B1, 1, 1); G_STAGE(G_SB(1, 0), b3);
;         G_BAR; G_WAIT_L(0); G_MMA(0, 1, At, B1); G_BAR;
;         G_LDA(At, 1, 1); G_STAGE(G_SA(1, 0), a3);
;         G_BAR; G_WAIT_L(0); G_MMA(1, 0, At, B0); G_BAR; G_SCHED;
	s_add_u32 s10, s12, 0xb0000
	s_addc_u32 s11, s13, 0
	s_add_i32 s34, s35, s58
	v_lshl_add_u64 v[140:141], s[10:11], 0, v[176:177]
	s_mov_b32 m0, s34
	s_nop 0
	global_load_lds_dwordx4 v[140:141], off
	v_lshl_add_u64 v[140:141], s[10:11], 0, v[128:129]
	s_add_i32 m0, s34, 0x2000
	s_nop 0
	global_load_lds_dwordx4 v[140:141], off
	v_add_u32_e32 v139, 0x18000, v137
	ds_read_b128 v[140:143], v139
	ds_read_b128 v[144:147], v139 offset:1024
	ds_read_b128 v[148:151], v139 offset:2048
	ds_read_b128 v[152:155], v139 offset:3072
	s_waitcnt vmcnt(10)
	s_barrier
	v_mfma_f32_16x16x32_bf16 v[120:123], v[218:221], v[156:159], v[120:123]
	v_mfma_f32_16x16x32_bf16 v[124:127], v[226:229], v[156:159], v[124:127]
	v_mfma_f32_16x16x32_bf16 v[112:115], v[218:221], v[164:167], v[112:115]
	v_mfma_f32_16x16x32_bf16 v[116:119], v[226:229], v[164:167], v[116:119]
	v_mfma_f32_16x16x32_bf16 v[104:107], v[218:221], v[172:175], v[104:107]
	v_mfma_f32_16x16x32_bf16 v[108:111], v[226:229], v[172:175], v[108:111]
	v_mfma_f32_16x16x32_bf16 v[96:99], v[218:221], v[186:189], v[96:99]
	v_mfma_f32_16x16x32_bf16 v[100:103], v[226:229], v[186:189], v[100:103]
	v_mfma_f32_16x16x32_bf16 v[120:123], v[222:225], v[160:163], v[120:123]
	v_mfma_f32_16x16x32_bf16 v[124:127], v[230:233], v[160:163], v[124:127]
	v_mfma_f32_16x16x32_bf16 v[112:115], v[222:225], v[168:171], v[112:115]
	v_mfma_f32_16x16x32_bf16 v[116:119], v[230:233], v[168:171], v[116:119]
	v_mfma_f32_16x16x32_bf16 v[104:107], v[222:225], v[182:185], v[104:107]
	v_mfma_f32_16x16x32_bf16 v[108:111], v[230:233], v[182:185], v[108:111]
	v_mfma_f32_16x16x32_bf16 v[96:99], v[222:225], v[214:217], v[96:99]
	v_mfma_f32_16x16x32_bf16 v[100:103], v[230:233], v[214:217], v[100:103]
	s_add_i32 s34, 0, 0x18000
	s_barrier
	s_add_u32 s10, s14, 0xb0000
	s_addc_u32 s11, s15, 0
	s_mov_b32 m0, s24
	v_lshl_add_u64 v[218:219], s[10:11], 0, v[176:177]
	ds_read_b128 v[156:159], v138 offset:32768
	ds_read_b128 v[160:163], v138 offset:33792
	ds_read_b128 v[164:167], v138 offset:34816
	ds_read_b128 v[168:171], v138 offset:35840
	ds_read_b128 v[172:175], v138 offset:36864
	ds_read_b128 v[182:185], v138 offset:37888
	ds_read_b128 v[186:189], v138 offset:38912
	ds_read_b128 v[214:217], v138 offset:39936
	global_load_lds_dwordx4 v[218:219], off
	v_lshl_add_u64 v[218:219], s[10:11], 0, v[128:129]
	s_mov_b32 m0, s25
	s_nop 0
	global_load_lds_dwordx4 v[218:219], off
	s_waitcnt lgkmcnt(8)
	s_waitcnt vmcnt(10)
	s_barrier
	s_waitcnt lgkmcnt(0)
	s_waitcnt lgkmcnt(0)
	v_mfma_f32_16x16x32_bf16 v[20:23], v[140:143], v[156:159], v[20:23]
	v_mfma_f32_16x16x32_bf16 v[28:31], v[148:151], v[156:159], v[28:31]
	v_mfma_f32_16x16x32_bf16 v[12:15], v[140:143], v[164:167], v[12:15]
	v_mfma_f32_16x16x32_bf16 v[24:27], v[148:151], v[164:167], v[24:27]
	v_mfma_f32_16x16x32_bf16 v[4:7], v[140:143], v[172:175], v[4:7]
	v_mfma_f32_16x16x32_bf16 v[16:19], v[148:151], v[172:175], v[16:19]
	v_mfma_f32_16x16x32_bf16 v[0:3], v[140:143], v[186:189], v[0:3]
	v_mfma_f32_16x16x32_bf16 v[8:11], v[148:151], v[186:189], v[8:11]
	v_mfma_f32_16x16x32_bf16 v[20:23], v[144:147], v[160:163], v[20:23]
	v_mfma_f32_16x16x32_bf16 v[28:31], v[152:155], v[160:163], v[28:31]
	v_mfma_f32_16x16x32_bf16 v[12:15], v[144:147], v[168:171], v[12:15]
	v_mfma_f32_16x16x32_bf16 v[24:27], v[152:155], v[168:171], v[24:27]
	v_mfma_f32_16x16x32_bf16 v[4:7], v[144:147], v[182:185], v[4:7]
	v_mfma_f32_16x16x32_bf16 v[16:19], v[152:155], v[182:185], v[16:19]
	v_mfma_f32_16x16x32_bf16 v[0:3], v[144:147], v[214:217], v[0:3]
	v_mfma_f32_16x16x32_bf16 v[8:11], v[152:155], v[214:217], v[8:11]
	s_barrier
	s_add_i32 s14, 0, 0x1c000
	s_add_i32 s10, s34, s58
	v_add_u32_e32 v139, s14, v137
	v_lshl_add_u64 v[190:191], v[190:191], 0, s[64:65]
	s_mov_b32 m0, s10
	ds_read_b128 v[218:221], v139
	ds_read_b128 v[222:225], v139 offset:1024
	ds_read_b128 v[226:229], v139 offset:2048
	ds_read_b128 v[230:233], v139 offset:3072
	global_load_lds_dwordx4 v[190:191], off
	v_lshl_add_u64 v[190:191], v[234:235], 0, s[64:65]
	s_add_i32 m0, s10, 0x2000
	s_nop 0
	global_load_lds_dwordx4 v[190:191], off
	s_waitcnt vmcnt(10)
	s_barrier
	s_waitcnt lgkmcnt(0)
	s_waitcnt lgkmcnt(0)
	v_mfma_f32_16x16x32_bf16 v[80:83], v[218:221], v[156:159], v[80:83]
	v_mfma_f32_16x16x32_bf16 v[92:95], v[226:229], v[156:159], v[92:95]
	v_mfma_f32_16x16x32_bf16 v[64:67], v[218:221], v[164:167], v[64:67]
	v_mfma_f32_16x16x32_bf16 v[84:87], v[226:229], v[164:167], v[84:87]
	v_mfma_f32_16x16x32_bf16 v[52:55], v[218:221], v[172:175], v[52:55]
	v_mfma_f32_16x16x32_bf16 v[76:79], v[226:229], v[172:175], v[76:79]
	v_mfma_f32_16x16x32_bf16 v[40:43], v[218:221], v[186:189], v[40:43]
	v_mfma_f32_16x16x32_bf16 v[60:63], v[226:229], v[186:189], v[60:63]
	v_mfma_f32_16x16x32_bf16 v[80:83], v[222:225], v[160:163], v[80:83]
	v_mfma_f32_16x16x32_bf16 v[92:95], v[230:233], v[160:163], v[92:95]
	v_mfma_f32_16x16x32_bf16 v[64:67], v[222:225], v[168:171], v[64:67]
	v_mfma_f32_16x16x32_bf16 v[84:87], v[230:233], v[168:171], v[84:87]
	v_mfma_f32_16x16x32_bf16 v[52:55], v[222:225], v[182:185], v[52:55]
	v_mfma_f32_16x16x32_bf16 v[76:79], v[230:233], v[182:185], v[76:79]
	v_mfma_f32_16x16x32_bf16 v[40:43], v[222:225], v[214:217], v[40:43]
	v_mfma_f32_16x16x32_bf16 v[60:63], v[230:233], v[214:217], v[60:63]
	s_mov_b32 m0, s0
	v_lshl_add_u64 v[190:191], v[236:237], 0, s[64:65]
	s_barrier
	ds_read_b128 v[156:159], v138 offset:49152
	ds_read_b128 v[160:163], v138 offset:50176
	ds_read_b128 v[164:167], v138 offset:51200
	ds_read_b128 v[168:171], v138 offset:52224
	ds_read_b128 v[172:175], v138 offset:53248
	ds_read_b128 v[182:185], v138 offset:54272
	ds_read_b128 v[186:189], v138 offset:55296
	ds_read_b128 v[214:217], v138 offset:56320
	global_load_lds_dwordx4 v[190:191], off
	v_lshl_add_u64 v[190:191], v[238:239], 0, s[64:65]
	s_mov_b32 m0, s1
	s_nop 0
	global_load_lds_dwordx4 v[190:191], off
	s_waitcnt vmcnt(10)
	s_barrier
; __device__ __forceinline__ u32x4 mk4(unsigned a, unsigned b, unsigned c, unsigned d) { return (u32x4){a, b, c, d}; }
; #define G_STAGE(bufoff, gbase) do { _Pragma("unroll") for (int _i = 0; _i < 2; ++_i) \
;     __builtin_amdgcn_global_load_lds((const unsigned*)((const char*)(gbase) + voff[_i]), (GLAS unsigned*)(lds + (bufoff) + ldsw + _i * 8192), 16, 0, 0); } while (0)
; #define G_MMA(ai, bj, At_, Bt_) do { __builtin_amdgcn_s_setprio(1); \
;     _Pragma("unroll") for (int m = 0; m < 4; ++m) _Pragma("unroll") for (int n = 0; n < 2; ++n) _Pragma("unroll") for (int k = 0; k < 2; ++k) \
;       acc[ai][bj][m][n] = __builtin_amdgcn_mfma_f32_16x16x32_bf16(Bt_[n][k], At_[m][k], acc[ai][bj][m][n], 0, 0, 0); \
;     __builtin_amdgcn_s_setprio(0); } while (0)
; #define G_WAIT_V(n) asm volatile("s_waitcnt vmcnt(" #n ")" ::: "memory")
; #define G_BAR __builtin_amdgcn_s_barrier()
; __device__ __forceinline__ void gemm_phase(const Params& p, int l, const bf16_t* __restrict__ A, const bf16_t* __restrict__ Bt, int M, int N, int K,
;                            int epi, bf16_t* __restrict__ outp, char* smem, int wvi) {
;     ...
;         G_STAGE(G_SB(1, 1), b3 + hstep);
;         G_WAIT_V(6); G_BAR; G_MMA(1, 1, At, B1); G_BAR;
;       }
;       const int brow = pm * GBM, bcol = pn * GBM;
;     const int r0 = brow + wr * 64 + fr;
;     if (epi == EPI_PLAIN) {
; #pragma unroll
;       for (int ai = 0; ai < 2; ++ai)
; #pragma unroll
;         for (int m = 0; m < 4; ++m) {
;           bf16_t* rp = outp + (size_t)(r0 + ai * GHALF + m * 16) * N + bcol + wc * 32 + fq * 8;
; #pragma unroll
;           for (int bj = 0; bj < 2; ++bj) {
;             const f32x4 v0 = acc[ai][bj][m][0], v1 = acc[ai][bj][m][1];
;             *reinterpret_cast<u32x4*>(rp + bj * GHALF) = mk4(pk2(v0[0], v0[1]), pk2(v0[2], v0[3]), pk2(v1[0], v1[1]), pk2(v1[2], v1[3]));
;           }
;         }
	s_waitcnt lgkmcnt(0)
	s_waitcnt lgkmcnt(0)
	v_mfma_f32_16x16x32_bf16 v[68:71], v[140:143], v[156:159], v[68:71]
	v_mfma_f32_16x16x32_bf16 v[88:91], v[148:151], v[156:159], v[88:91]
	v_mfma_f32_16x16x32_bf16 v[48:51], v[140:143], v[164:167], v[48:51]
	v_mfma_f32_16x16x32_bf16 v[72:75], v[148:151], v[164:167], v[72:75]
	v_mfma_f32_16x16x32_bf16 v[36:39], v[140:143], v[172:175], v[36:39]
	v_mfma_f32_16x16x32_bf16 v[56:59], v[148:151], v[172:175], v[56:59]
	v_mfma_f32_16x16x32_bf16 v[32:35], v[140:143], v[186:189], v[32:35]
	v_mfma_f32_16x16x32_bf16 v[44:47], v[148:151], v[186:189], v[44:47]
	v_mfma_f32_16x16x32_bf16 v[68:71], v[144:147], v[160:163], v[68:71]
	v_mfma_f32_16x16x32_bf16 v[88:91], v[152:155], v[160:163], v[88:91]
	v_mfma_f32_16x16x32_bf16 v[48:51], v[144:147], v[168:171], v[48:51]
	v_mfma_f32_16x16x32_bf16 v[72:75], v[152:155], v[168:171], v[72:75]
	v_mfma_f32_16x16x32_bf16 v[36:39], v[144:147], v[182:185], v[36:39]
	v_mfma_f32_16x16x32_bf16 v[56:59], v[152:155], v[182:185], v[56:59]
	v_mfma_f32_16x16x32_bf16 v[32:35], v[144:147], v[214:217], v[32:35]
	v_mfma_f32_16x16x32_bf16 v[44:47], v[152:155], v[214:217], v[44:47]
	s_barrier
	s_add_u32 s10, s12, 0xb0080
	s_addc_u32 s11, s13, 0
	s_add_i32 s12, s14, s58
	v_lshl_add_u64 v[140:141], s[10:11], 0, v[176:177]
	s_mov_b32 m0, s12
	s_nop 0
	global_load_lds_dwordx4 v[140:141], off
	v_lshl_add_u64 v[140:141], s[10:11], 0, v[128:129]
	s_add_i32 m0, s12, 0x2000
	s_nop 0
	global_load_lds_dwordx4 v[140:141], off
	v_add_u32_e32 v139, 0x10000, v137
	ds_read_b128 v[140:143], v139
	ds_read_b128 v[144:147], v139 offset:1024
	ds_read_b128 v[148:151], v139 offset:2048
	ds_read_b128 v[152:155], v139 offset:3072
	s_waitcnt vmcnt(6)
	s_barrier
	v_mfma_f32_16x16x32_bf16 v[120:123], v[218:221], v[156:159], v[120:123]
	v_mfma_f32_16x16x32_bf16 v[124:127], v[226:229], v[156:159], v[124:127]
	v_mfma_f32_16x16x32_bf16 v[112:115], v[218:221], v[164:167], v[112:115]
	v_mfma_f32_16x16x32_bf16 v[116:119], v[226:229], v[164:167], v[116:119]
	v_mfma_f32_16x16x32_bf16 v[104:107], v[218:221], v[172:175], v[104:107]
	v_mfma_f32_16x16x32_bf16 v[108:111], v[226:229], v[172:175], v[108:111]
	v_mfma_f32_16x16x32_bf16 v[96:99], v[218:221], v[186:189], v[96:99]
	v_mfma_f32_16x16x32_bf16 v[100:103], v[226:229], v[186:189], v[100:103]
	v_mfma_f32_16x16x32_bf16 v[120:123], v[222:225], v[160:163], v[120:123]
	v_mfma_f32_16x16x32_bf16 v[124:127], v[230:233], v[160:163], v[124:127]
	v_mfma_f32_16x16x32_bf16 v[112:115], v[222:225], v[168:171], v[112:115]
	v_mfma_f32_16x16x32_bf16 v[116:119], v[230:233], v[168:171], v[116:119]
	v_mfma_f32_16x16x32_bf16 v[104:107], v[222:225], v[182:185], v[104:107]
	v_mfma_f32_16x16x32_bf16 v[108:111], v[230:233], v[182:185], v[108:111]
	v_mfma_f32_16x16x32_bf16 v[96:99], v[222:225], v[214:217], v[96:99]
	v_mfma_f32_16x16x32_bf16 v[100:103], v[230:233], v[214:217], v[100:103]
	s_add_i32 s67, s67, 2
	s_add_u32 s55, s55, 0x100
	s_addc_u32 s63, s63, 0
	s_cmp_gt_u32 s67, 41
	s_mov_b64 s[10:11], s[2:3]
	s_barrier
	s_cbranch_scc0 .LBB0_121
	s_lshl_b32 s2, s30, 8
	v_lshl_add_u32 v250, s29, 8, v136
	s_ashr_i32 s3, s2, 31
	v_ashrrev_i32_e32 v251, 31, v250
	v_lshl_add_u64 v[252:253], s[2:3], 1, v[130:131]
	v_lshlrev_b64 v[254:255], 11, v[250:251]
	v_lshl_add_u64 v[254:255], v[252:253], 0, v[254:255]
	v_cvt_pk_bf16_f32 v20, v20, v21
	v_cvt_pk_bf16_f32 v21, v22, v23
	v_cvt_pk_bf16_f32 v22, v28, v29
	v_cvt_pk_bf16_f32 v23, v30, v31
	global_store_dwordx4 v[254:255], v[20:23], off
	v_cvt_pk_bf16_f32 v12, v12, v13
	v_cvt_pk_bf16_f32 v13, v14, v15
	v_cvt_pk_bf16_f32 v20, v80, v81
	v_cvt_pk_bf16_f32 v21, v82, v83
	v_cvt_pk_bf16_f32 v22, v92, v93
	v_cvt_pk_bf16_f32 v23, v94, v95
	global_store_dwordx4 v[254:255], v[20:23], off offset:256
	v_cvt_pk_bf16_f32 v14, v24, v25
	v_cvt_pk_bf16_f32 v15, v26, v27
	v_or_b32_e32 v20, 16, v250
	v_ashrrev_i32_e32 v21, 31, v20
	v_lshlrev_b64 v[20:21], 11, v[20:21]
	v_lshl_add_u64 v[20:21], v[252:253], 0, v[20:21]
	global_store_dwordx4 v[20:21], v[12:15], off
	v_cvt_pk_bf16_f32 v4, v4, v5
	v_cvt_pk_bf16_f32 v5, v6, v7
	v_cvt_pk_bf16_f32 v12, v64, v65
	v_cvt_pk_bf16_f32 v13, v66, v67
	v_cvt_pk_bf16_f32 v14, v84, v85
	v_cvt_pk_bf16_f32 v15, v86, v87
	global_store_dwordx4 v[20:21], v[12:15], off offset:256
	v_cvt_pk_bf16_f32 v6, v16, v17
	v_cvt_pk_bf16_f32 v7, v18, v19
	v_or_b32_e32 v12, 32, v250
	v_ashrrev_i32_e32 v13, 31, v12
	v_lshlrev_b64 v[12:13], 11, v[12:13]
	v_lshl_add_u64 v[12:13], v[252:253], 0, v[12:13]
	global_store_dwordx4 v[12:13], v[4:7], off
	v_cvt_pk_bf16_f32 v0, v0, v1
	v_cvt_pk_bf16_f32 v1, v2, v3
	v_cvt_pk_bf16_f32 v4, v52, v53
	v_cvt_pk_bf16_f32 v5, v54, v55
	v_cvt_pk_bf16_f32 v6, v76, v77
	v_cvt_pk_bf16_f32 v7, v78, v79
	global_store_dwordx4 v[12:13], v[4:7], off offset:256
	v_cvt_pk_bf16_f32 v2, v8, v9
	v_cvt_pk_bf16_f32 v3, v10, v11
	v_or_b32_e32 v4, 48, v250
	v_ashrrev_i32_e32 v5, 31, v4
	v_lshlrev_b64 v[4:5], 11, v[4:5]
	v_lshl_add_u64 v[4:5], v[252:253], 0, v[4:5]
	global_store_dwordx4 v[4:5], v[0:3], off
	s_mov_b64 s[2:3], 0x40000
	v_readlane_b32 s63, v244, 19
	v_cvt_pk_bf16_f32 v0, v40, v41
	v_cvt_pk_bf16_f32 v1, v42, v43
	v_cvt_pk_bf16_f32 v2, v60, v61
	v_cvt_pk_bf16_f32 v3, v62, v63
	global_store_dwordx4 v[4:5], v[0:3], off offset:256
	v_lshl_add_u64 v[4:5], v[254:255], 0, s[2:3]
	s_mov_b32 s2, 0x40000
	v_add_co_u32_e32 v6, vcc, s2, v254
	v_cvt_pk_bf16_f32 v0, v68, v69
; __device__ __forceinline__ u32x4 mk4(unsigned a, unsigned b, unsigned c, unsigned d) { return (u32x4){a, b, c, d}; }
; __device__ __forceinline__ f32x4 zero4() { float z = 0.f; asm volatile("" : "+v"(z)); return (f32x4){z, z, z, z}; }
; __device__ __forceinline__ void gemm_phase(const Params& p, int l, const bf16_t* __restrict__ A, const bf16_t* __restrict__ Bt, int M, int N, int K,
;                            int epi, bf16_t* __restrict__ outp, char* smem, int wvi) {
;     ...
;           bf16_t* rp = outp + (size_t)(r0 + ai * GHALF + m * 16) * N + bcol + wc * 32 + fq * 8;
; #pragma unroll
;           for (int bj = 0; bj < 2; ++bj) {
;             const f32x4 v0 = acc[ai][bj][m][0], v1 = acc[ai][bj][m][1];
;             *reinterpret_cast<u32x4*>(rp + bj * GHALF) = mk4(pk2(v0[0], v0[1]), pk2(v0[2], v0[3]), pk2(v1[0], v1[1]), pk2(v1[2], v1[3]));
;           }
;         }
;     ...
;       if (!has_next) break;
; #pragma unroll
;       for (int a = 0; a < 2; ++a)
; #pragma unroll
;         for (int b = 0; b < 2; ++b)
; #pragma unroll
;           for (int m = 0; m < 4; ++m)
; #pragma unroll
;             for (int n = 0; n < 2; ++n) acc[a][b][m][n] = zero4();
;       Lw = Ln; pm = npm; pn = npn; cA = nA; cB = nB;
	v_cvt_pk_bf16_f32 v1, v70, v71
	v_cvt_pk_bf16_f32 v2, v88, v89
	v_cvt_pk_bf16_f32 v3, v90, v91
	v_addc_co_u32_e32 v7, vcc, 0, v255, vcc
	global_store_dwordx4 v[6:7], v[0:3], off
	s_mov_b64 s[2:3], 0x48000
	v_readlane_b32 s67, v244, 20
	v_cvt_pk_bf16_f32 v0, v120, v121
	v_cvt_pk_bf16_f32 v1, v122, v123
	v_cvt_pk_bf16_f32 v2, v124, v125
	v_cvt_pk_bf16_f32 v3, v126, v127
	global_store_dwordx4 v[4:5], v[0:3], off offset:256
	v_lshl_add_u64 v[4:5], v[254:255], 0, s[2:3]
	s_mov_b32 s2, 0x48000
	v_add_co_u32_e32 v6, vcc, s2, v254
	v_cvt_pk_bf16_f32 v0, v48, v49
	v_cvt_pk_bf16_f32 v1, v50, v51
	v_cvt_pk_bf16_f32 v2, v72, v73
	v_cvt_pk_bf16_f32 v3, v74, v75
	v_addc_co_u32_e32 v7, vcc, 0, v255, vcc
	global_store_dwordx4 v[6:7], v[0:3], off
	s_mov_b64 s[2:3], 0x50000
	s_movk_i32 s53, 0x440
	v_cvt_pk_bf16_f32 v0, v112, v113
	v_cvt_pk_bf16_f32 v1, v114, v115
	v_cvt_pk_bf16_f32 v2, v116, v117
	v_cvt_pk_bf16_f32 v3, v118, v119
	global_store_dwordx4 v[4:5], v[0:3], off offset:256
	v_lshl_add_u64 v[4:5], v[254:255], 0, s[2:3]
	s_mov_b32 s2, 0x50000
	v_add_co_u32_e32 v6, vcc, s2, v254
	v_cvt_pk_bf16_f32 v0, v36, v37
	v_cvt_pk_bf16_f32 v1, v38, v39
	v_cvt_pk_bf16_f32 v2, v56, v57
	v_cvt_pk_bf16_f32 v3, v58, v59
	v_addc_co_u32_e32 v7, vcc, 0, v255, vcc
	global_store_dwordx4 v[6:7], v[0:3], off
	s_mov_b64 s[2:3], 0x58000
	v_readlane_b32 s55, v244, 31
	v_cvt_pk_bf16_f32 v0, v104, v105
	v_cvt_pk_bf16_f32 v1, v106, v107
	v_cvt_pk_bf16_f32 v2, v108, v109
	v_cvt_pk_bf16_f32 v3, v110, v111
	global_store_dwordx4 v[4:5], v[0:3], off offset:256
	v_lshl_add_u64 v[4:5], v[254:255], 0, s[2:3]
	s_mov_b32 s2, 0x58000
	v_add_co_u32_e32 v6, vcc, s2, v254
	v_cvt_pk_bf16_f32 v0, v32, v33
	v_cvt_pk_bf16_f32 v1, v34, v35
	v_cvt_pk_bf16_f32 v2, v44, v45
	v_cvt_pk_bf16_f32 v3, v46, v47
	v_addc_co_u32_e32 v7, vcc, 0, v255, vcc
	global_store_dwordx4 v[6:7], v[0:3], off
	s_mov_b64 s[2:3], -1
	s_and_b64 vcc, exec, s[8:9]
	v_cvt_pk_bf16_f32 v0, v96, v97
	v_cvt_pk_bf16_f32 v1, v98, v99
	v_cvt_pk_bf16_f32 v2, v100, v101
	v_cvt_pk_bf16_f32 v3, v102, v103
	global_store_dwordx4 v[4:5], v[0:3], off offset:256
	s_cbranch_vccz .LBB0_117
	v_mov_b32_e32 v20, v177
	v_mov_b32_e32 v28, v177
	v_mov_b32_e32 v12, v177
	v_mov_b32_e32 v24, v177
	v_mov_b32_e32 v4, v177
	v_mov_b32_e32 v16, v177
	v_mov_b32_e32 v0, v177
	v_mov_b32_e32 v8, v177
	v_mov_b32_e32 v80, v177
	v_mov_b32_e32 v92, v177
	v_mov_b32_e32 v64, v177
	v_mov_b32_e32 v84, v177
	v_mov_b32_e32 v52, v177
	v_mov_b32_e32 v76, v177
	v_mov_b32_e32 v40, v177
	v_mov_b32_e32 v60, v177
	v_mov_b32_e32 v68, v177
	v_mov_b32_e32 v88, v177
	v_mov_b32_e32 v48, v177
	v_mov_b32_e32 v72, v177
	v_mov_b32_e32 v36, v177
	v_mov_b32_e32 v56, v177
	v_mov_b32_e32 v32, v177
	v_mov_b32_e32 v44, v177
	v_mov_b32_e32 v120, v177
	v_mov_b32_e32 v124, v177
	v_mov_b32_e32 v112, v177
	v_mov_b32_e32 v116, v177
	v_mov_b32_e32 v104, v177
	v_mov_b32_e32 v108, v177
	v_mov_b32_e32 v96, v177
	v_mov_b32_e32 v100, v177
	s_nop 0
	v_mov_b32_e32 v21, v20
	v_mov_b32_e32 v22, v20
	v_mov_b32_e32 v23, v20
	v_mov_b32_e32 v29, v28
	v_mov_b32_e32 v30, v28
	v_mov_b32_e32 v31, v28
	v_mov_b32_e32 v13, v12
	v_mov_b32_e32 v14, v12
	v_mov_b32_e32 v15, v12
	v_mov_b32_e32 v25, v24
	v_mov_b32_e32 v26, v24
	v_mov_b32_e32 v27, v24
	v_mov_b32_e32 v5, v4
	v_mov_b32_e32 v6, v4
	v_mov_b32_e32 v7, v4
	v_mov_b32_e32 v17, v16
	v_mov_b32_e32 v18, v16
	v_mov_b32_e32 v19, v16
	s_nop 0
	v_mov_b32_e32 v1, v0
	v_mov_b32_e32 v2, v0
	v_mov_b32_e32 v3, v0
	v_mov_b32_e32 v9, v8
	v_mov_b32_e32 v10, v8
	v_mov_b32_e32 v11, v8
	v_mov_b32_e32 v81, v80
	v_mov_b32_e32 v82, v80
	v_mov_b32_e32 v83, v80
	v_mov_b32_e32 v93, v92
	v_mov_b32_e32 v94, v92
	v_mov_b32_e32 v95, v92
	v_mov_b32_e32 v65, v64
	v_mov_b32_e32 v66, v64
	v_mov_b32_e32 v67, v64
	v_mov_b32_e32 v85, v84
	v_mov_b32_e32 v86, v84
	v_mov_b32_e32 v87, v84
	s_nop 0
	v_mov_b32_e32 v53, v52
	v_mov_b32_e32 v54, v52
	v_mov_b32_e32 v55, v52
	v_mov_b32_e32 v77, v76
	v_mov_b32_e32 v78, v76
	v_mov_b32_e32 v79, v76
	v_mov_b32_e32 v41, v40
	v_mov_b32_e32 v42, v40
	v_mov_b32_e32 v43, v40
	v_mov_b32_e32 v61, v60
	v_mov_b32_e32 v62, v60
	v_mov_b32_e32 v63, v60
	v_mov_b32_e32 v69, v68
	v_mov_b32_e32 v70, v68
	v_mov_b32_e32 v71, v68
	v_mov_b32_e32 v89, v88
	v_mov_b32_e32 v90, v88
	v_mov_b32_e32 v91, v88
	s_nop 0
	v_mov_b32_e32 v49, v48
	v_mov_b32_e32 v50, v48
	v_mov_b32_e32 v51, v48
	v_mov_b32_e32 v73, v72
	v_mov_b32_e32 v74, v72
	v_mov_b32_e32 v75, v72
	v_mov_b32_e32 v37, v36
	v_mov_b32_e32 v38, v36
	v_mov_b32_e32 v39, v36
	v_mov_b32_e32 v57, v56
	v_mov_b32_e32 v58, v56
	v_mov_b32_e32 v59, v56
	v_mov_b32_e32 v33, v32
	v_mov_b32_e32 v34, v32
	v_mov_b32_e32 v35, v32
	v_mov_b32_e32 v45, v44
	v_mov_b32_e32 v46, v44
	v_mov_b32_e32 v47, v44
	s_nop 0
	v_mov_b32_e32 v121, v120
	v_mov_b32_e32 v122, v120
	v_mov_b32_e32 v123, v120
	v_mov_b32_e32 v125, v124
	v_mov_b32_e32 v126, v124
	v_mov_b32_e32 v127, v124
	v_mov_b32_e32 v113, v112
	v_mov_b32_e32 v114, v112
	v_mov_b32_e32 v115, v112
	v_mov_b32_e32 v117, v116
	v_mov_b32_e32 v118, v116
	v_mov_b32_e32 v119, v116
	v_mov_b32_e32 v105, v104
	v_mov_b32_e32 v106, v104
	v_mov_b32_e32 v107, v104
	v_mov_b32_e32 v109, v108
	v_mov_b32_e32 v110, v108
	v_mov_b32_e32 v111, v108
	s_mov_b64 s[2:3], 0
	v_mov_b32_e32 v97, v96
	v_mov_b32_e32 v98, v96
	v_mov_b32_e32 v99, v96
	v_mov_b32_e32 v101, v100
	v_mov_b32_e32 v102, v100
	v_mov_b32_e32 v103, v100
	s_branch .LBB0_117

; #define G_STAGE(bufoff, gbase) do { _Pragma("unroll") for (int _i = 0; _i < 2; ++_i) \
;     __builtin_amdgcn_global_load_lds((const unsigned*)((const char*)(gbase) + voff[_i]), (GLAS unsigned*)(lds + (bufoff) + ldsw + _i * 8192), 16, 0, 0); } while (0)
; #define G_LDA(dst, b, h) do { _Pragma("unroll") for (int m = 0; m < 4; ++m) _Pragma("unroll") for (int k = 0; k < 2; ++k) \
;     dst[m][k] = *(const GLAS bf16x8*)(lds + G_SA(b, h) + aoff + m * 2048 + k * 1024); } while (0)
; #define G_LDB(dst, b, h) do { _Pragma("unroll") for (int n = 0; n < 2; ++n) _Pragma("unroll") for (int k = 0; k < 2; ++k) \
;     dst[n][k] = *(const GLAS bf16x8*)(lds + G_SB(b, h) + boff + n * 2048 + k * 1024); } while (0)
; #define G_MMA(ai, bj, At_, Bt_) do { __builtin_amdgcn_s_setprio(1); \
;     _Pragma("unroll") for (int m = 0; m < 4; ++m) _Pragma("unroll") for (int n = 0; n < 2; ++n) _Pragma("unroll") for (int k = 0; k < 2; ++k) \
;       acc[ai][bj][m][n] = __builtin_amdgcn_mfma_f32_16x16x32_bf16(Bt_[n][k], At_[m][k], acc[ai][bj][m][n], 0, 0, 0); \
;     __builtin_amdgcn_s_setprio(0); } while (0)
; #define G_WAIT_L(n) asm volatile("s_waitcnt lgkmcnt(" #n ")" ::: "memory")
; #define G_BAR __builtin_amdgcn_s_barrier()
; #define G_SCHED __builtin_amdgcn_sched_barrier(0)
; __device__ __forceinline__ void gemm_phase(const Params& p, int l, const bf16_t* __restrict__ A, const bf16_t* __restrict__ Bt, int M, int N, int K,
;                            int epi, bf16_t* __restrict__ outp, char* smem, int wvi) {
;     ...
;       for (int t = 0; t < nt; t += 2) {
;         const bool lastt = (t == nt - 2);
;         const char* a1 = cA + (size_t)(t + 1) * kstep;
;         const char* a2 = lastt ? nA : cA + (size_t)(t + 2) * kstep; const char* b2 = lastt ? nB : cB + (size_t)(t + 2) * kstep;
;         const char* a3 = a2 + kstep; const char* b3 = b2 + kstep;
;         G_LDB(B0, 0, 0); G_SCHED; G_LDA(At, 0, 0); G_STAGE(G_SA(1, 1), a1 + hstep);
;         G_WAIT_L(8); G_BAR; G_WAIT_L(0); G_MMA(0, 0, At, B0); G_BAR; G_SCHED;
;         G_LDB(B1, 0, 1); G_STAGE(G_SB(0, 0), b2);
;         G_BAR; G_WAIT_L(0); G_MMA(0, 1, At, B1); G_BAR;
;         G_LDA(At, 0, 1); G_STAGE(G_SA(0, 0), a2);
;         G_BAR; G_WAIT_L(0); G_MMA(1, 0, At, B0); G_BAR; G_SCHED;
.LBB0_320:
	s_add_u32 s2, s10, 0x100
	s_addc_u32 s3, s11, 0
	s_add_i32 s23, 0, 0x10000
	s_cmp_eq_u32 s22, 12
	s_cselect_b32 s29, s9, s3
	s_cselect_b32 s28, s8, s2
	s_cselect_b32 s93, s5, s21
	s_cselect_b32 s92, s1, s7
	v_lshl_add_u64 v[136:137], s[10:11], 0, v[132:133]
	s_add_i32 m0, s17, 0xc000
	ds_read_b128 v[158:161], v140
	ds_read_b128 v[162:165], v140 offset:1024
	ds_read_b128 v[166:169], v140 offset:2048
	ds_read_b128 v[170:173], v140 offset:3072
	ds_read_b128 v[182:185], v140 offset:4096
	ds_read_b128 v[186:189], v140 offset:5120
	ds_read_b128 v[214:217], v140 offset:6144
	ds_read_b128 v[218:221], v140 offset:7168
	global_load_lds_dwordx4 v[136:137], off
	v_lshl_add_u64 v[136:137], s[10:11], 0, v[134:135]
	s_add_i32 m0, s17, 0xe000
	s_nop 0
	global_load_lds_dwordx4 v[136:137], off
	s_waitcnt lgkmcnt(8)
	s_barrier
	s_waitcnt lgkmcnt(0)
	s_waitcnt lgkmcnt(0)
	v_mfma_f32_16x16x32_bf16 v[120:123], v[142:145], v[158:161], v[120:123]
	v_mfma_f32_16x16x32_bf16 v[124:127], v[150:153], v[158:161], v[124:127]
	v_mfma_f32_16x16x32_bf16 v[104:107], v[142:145], v[166:169], v[104:107]
	v_mfma_f32_16x16x32_bf16 v[108:111], v[150:153], v[166:169], v[108:111]
	v_mfma_f32_16x16x32_bf16 v[88:91], v[142:145], v[182:185], v[88:91]
	v_mfma_f32_16x16x32_bf16 v[92:95], v[150:153], v[182:185], v[92:95]
	v_mfma_f32_16x16x32_bf16 v[72:75], v[142:145], v[214:217], v[72:75]
	v_mfma_f32_16x16x32_bf16 v[76:79], v[150:153], v[214:217], v[76:79]
	v_mfma_f32_16x16x32_bf16 v[120:123], v[146:149], v[162:165], v[120:123]
	v_mfma_f32_16x16x32_bf16 v[124:127], v[154:157], v[162:165], v[124:127]
	v_mfma_f32_16x16x32_bf16 v[104:107], v[146:149], v[170:173], v[104:107]
	v_mfma_f32_16x16x32_bf16 v[108:111], v[154:157], v[170:173], v[108:111]
	v_mfma_f32_16x16x32_bf16 v[88:91], v[146:149], v[186:189], v[88:91]
	v_mfma_f32_16x16x32_bf16 v[92:95], v[154:157], v[186:189], v[92:95]
	v_mfma_f32_16x16x32_bf16 v[72:75], v[146:149], v[218:221], v[72:75]
	v_mfma_f32_16x16x32_bf16 v[76:79], v[154:157], v[218:221], v[76:79]
	s_barrier
	s_add_i32 s24, 0, 0x14000
	v_add_u32_e32 v136, s24, v139
	s_add_i32 s10, s23, s58
	ds_read_b128 v[222:225], v136
	ds_read_b128 v[226:229], v136 offset:1024
	ds_read_b128 v[230:233], v136 offset:2048
	ds_read_b128 v[234:237], v136 offset:3072
	v_lshl_add_u64 v[136:137], s[92:93], 0, v[176:177]
	s_mov_b32 m0, s10
	v_lshl_add_u64 v[174:175], s[92:93], 0, v[128:129]
	global_load_lds_dwordx4 v[136:137], off
	s_add_i32 m0, s10, 0x2000
	s_nop 0
	global_load_lds_dwordx4 v[174:175], off
	s_barrier
	s_waitcnt lgkmcnt(0)
	s_waitcnt lgkmcnt(0)
	v_mfma_f32_16x16x32_bf16 v[112:115], v[222:225], v[158:161], v[112:115]
	v_mfma_f32_16x16x32_bf16 v[116:119], v[230:233], v[158:161], v[116:119]
	v_mfma_f32_16x16x32_bf16 v[96:99], v[222:225], v[166:169], v[96:99]
	v_mfma_f32_16x16x32_bf16 v[100:103], v[230:233], v[166:169], v[100:103]
	v_mfma_f32_16x16x32_bf16 v[80:83], v[222:225], v[182:185], v[80:83]
	v_mfma_f32_16x16x32_bf16 v[84:87], v[230:233], v[182:185], v[84:87]
	v_mfma_f32_16x16x32_bf16 v[64:67], v[222:225], v[214:217], v[64:67]
	v_mfma_f32_16x16x32_bf16 v[68:71], v[230:233], v[214:217], v[68:71]
	v_mfma_f32_16x16x32_bf16 v[112:115], v[226:229], v[162:165], v[112:115]
	v_mfma_f32_16x16x32_bf16 v[116:119], v[234:237], v[162:165], v[116:119]
	v_mfma_f32_16x16x32_bf16 v[96:99], v[226:229], v[170:173], v[96:99]
	v_mfma_f32_16x16x32_bf16 v[100:103], v[234:237], v[170:173], v[100:103]
	v_mfma_f32_16x16x32_bf16 v[80:83], v[226:229], v[186:189], v[80:83]
	v_mfma_f32_16x16x32_bf16 v[84:87], v[234:237], v[186:189], v[84:87]
	v_mfma_f32_16x16x32_bf16 v[64:67], v[226:229], v[218:221], v[64:67]
	v_mfma_f32_16x16x32_bf16 v[68:71], v[234:237], v[218:221], v[68:71]
	s_mov_b32 m0, s17
	v_lshl_add_u64 v[190:191], s[28:29], 0, v[176:177]
	s_barrier
	ds_read_b128 v[158:161], v140 offset:16384
	ds_read_b128 v[162:165], v140 offset:17408
	ds_read_b128 v[166:169], v140 offset:18432
	ds_read_b128 v[170:173], v140 offset:19456
	ds_read_b128 v[182:185], v140 offset:20480
	ds_read_b128 v[186:189], v140 offset:21504
	ds_read_b128 v[214:217], v140 offset:22528
	ds_read_b128 v[218:221], v140 offset:23552
	global_load_lds_dwordx4 v[190:191], off
	v_lshl_add_u64 v[238:239], s[28:29], 0, v[128:129]
	s_mov_b32 m0, s89
	s_nop 0
	global_load_lds_dwordx4 v[238:239], off
	s_waitcnt vmcnt(10)
	s_barrier
	s_waitcnt lgkmcnt(0)
	s_waitcnt lgkmcnt(0)
	v_mfma_f32_16x16x32_bf16 v[56:59], v[142:145], v[158:161], v[56:59]
	v_mfma_f32_16x16x32_bf16 v[60:63], v[150:153], v[158:161], v[60:63]
	v_mfma_f32_16x16x32_bf16 v[40:43], v[142:145], v[166:169], v[40:43]
	v_mfma_f32_16x16x32_bf16 v[44:47], v[150:153], v[166:169], v[44:47]
	v_mfma_f32_16x16x32_bf16 v[24:27], v[142:145], v[182:185], v[24:27]
	v_mfma_f32_16x16x32_bf16 v[28:31], v[150:153], v[182:185], v[28:31]
	v_mfma_f32_16x16x32_bf16 v[8:11], v[142:145], v[214:217], v[8:11]
	v_mfma_f32_16x16x32_bf16 v[12:15], v[150:153], v[214:217], v[12:15]
	v_mfma_f32_16x16x32_bf16 v[56:59], v[146:149], v[162:165], v[56:59]
	v_mfma_f32_16x16x32_bf16 v[60:63], v[154:157], v[162:165], v[60:63]
	v_mfma_f32_16x16x32_bf16 v[40:43], v[146:149], v[170:173], v[40:43]
	v_mfma_f32_16x16x32_bf16 v[44:47], v[154:157], v[170:173], v[44:47]
	v_mfma_f32_16x16x32_bf16 v[24:27], v[146:149], v[186:189], v[24:27]
	v_mfma_f32_16x16x32_bf16 v[28:31], v[154:157], v[186:189], v[28:31]
	v_mfma_f32_16x16x32_bf16 v[8:11], v[146:149], v[218:221], v[8:11]
	v_mfma_f32_16x16x32_bf16 v[12:15], v[154:157], v[218:221], v[12:15]
	s_barrier
; #define G_STAGE(bufoff, gbase) do { _Pragma("unroll") for (int _i = 0; _i < 2; ++_i) \
;     __builtin_amdgcn_global_load_lds((const unsigned*)((const char*)(gbase) + voff[_i]), (GLAS unsigned*)(lds + (bufoff) + ldsw + _i * 8192), 16, 0, 0); } while (0)
; #define G_LDA(dst, b, h) do { _Pragma("unroll") for (int m = 0; m < 4; ++m) _Pragma("unroll") for (int k = 0; k < 2; ++k) \
;     dst[m][k] = *(const GLAS bf16x8*)(lds + G_SA(b, h) + aoff + m * 2048 + k * 1024); } while (0)
; #define G_LDB(dst, b, h) do { _Pragma("unroll") for (int n = 0; n < 2; ++n) _Pragma("unroll") for (int k = 0; k < 2; ++k) \
;     dst[n][k] = *(const GLAS bf16x8*)(lds + G_SB(b, h) + boff + n * 2048 + k * 1024); } while (0)
; #define G_MMA(ai, bj, At_, Bt_) do { __builtin_amdgcn_s_setprio(1); \
;     _Pragma("unroll") for (int m = 0; m < 4; ++m) _Pragma("unroll") for (int n = 0; n < 2; ++n) _Pragma("unroll") for (int k = 0; k < 2; ++k) \
;       acc[ai][bj][m][n] = __builtin_amdgcn_mfma_f32_16x16x32_bf16(Bt_[n][k], At_[m][k], acc[ai][bj][m][n], 0, 0, 0); \
;     __builtin_amdgcn_s_setprio(0); } while (0)
; #define G_WAIT_V(n) asm volatile("s_waitcnt vmcnt(" #n ")" ::: "memory")
; #define G_WAIT_L(n) asm volatile("s_waitcnt lgkmcnt(" #n ")" ::: "memory")
; #define G_BAR __builtin_amdgcn_s_barrier()
; #define G_SCHED __builtin_amdgcn_sched_barrier(0)
; __device__ __forceinline__ void gemm_phase(const Params& p, int l, const bf16_t* __restrict__ A, const bf16_t* __restrict__ Bt, int M, int N, int K,
;                            int epi, bf16_t* __restrict__ outp, char* smem, int wvi) {
;     ...
;         G_STAGE(G_SB(0, 1), b2 + hstep);
;         G_WAIT_V(6); G_BAR; G_MMA(1, 1, At, B1); G_BAR;
;         G_LDB(B0, 1, 0); G_SCHED; G_LDA(At, 1, 0); G_STAGE(G_SA(0, 1), a2 + hstep);
;         G_WAIT_L(8); G_BAR; G_WAIT_L(0); G_MMA(0, 0, At, B0); G_BAR; G_SCHED;
;         G_LDB(B1, 1, 1); G_STAGE(G_SB(1, 0), b3);
;         G_BAR; G_WAIT_L(0); G_MMA(0, 1, At, B1); G_BAR;
;         G_LDA(At, 1, 1); G_STAGE(G_SA(1, 0), a3);
;         G_BAR; G_WAIT_L(0); G_MMA(1, 0, At, B0); G_BAR; G_SCHED;
	s_add_u32 s10, s92, 0x40000
	s_addc_u32 s11, s93, 0
	s_add_i32 s23, s24, s58
	v_lshl_add_u64 v[142:143], s[10:11], 0, v[176:177]
	s_mov_b32 m0, s23
	s_nop 0
	global_load_lds_dwordx4 v[142:143], off
	v_lshl_add_u64 v[142:143], s[10:11], 0, v[128:129]
	s_add_i32 m0, s23, 0x2000
	s_nop 0
	global_load_lds_dwordx4 v[142:143], off
	v_add_u32_e32 v141, 0x18000, v139
	ds_read_b128 v[142:145], v141
	ds_read_b128 v[146:149], v141 offset:1024
	ds_read_b128 v[150:153], v141 offset:2048
	ds_read_b128 v[154:157], v141 offset:3072
	s_waitcnt vmcnt(10)
	s_barrier
	v_mfma_f32_16x16x32_bf16 v[48:51], v[222:225], v[158:161], v[48:51]
	v_mfma_f32_16x16x32_bf16 v[52:55], v[230:233], v[158:161], v[52:55]
	v_mfma_f32_16x16x32_bf16 v[32:35], v[222:225], v[166:169], v[32:35]
	v_mfma_f32_16x16x32_bf16 v[36:39], v[230:233], v[166:169], v[36:39]
	v_mfma_f32_16x16x32_bf16 v[16:19], v[222:225], v[182:185], v[16:19]
	v_mfma_f32_16x16x32_bf16 v[20:23], v[230:233], v[182:185], v[20:23]
	v_mfma_f32_16x16x32_bf16 v[0:3], v[222:225], v[214:217], v[0:3]
	v_mfma_f32_16x16x32_bf16 v[4:7], v[230:233], v[214:217], v[4:7]
	v_mfma_f32_16x16x32_bf16 v[48:51], v[226:229], v[162:165], v[48:51]
	v_mfma_f32_16x16x32_bf16 v[52:55], v[234:237], v[162:165], v[52:55]
	v_mfma_f32_16x16x32_bf16 v[32:35], v[226:229], v[170:173], v[32:35]
	v_mfma_f32_16x16x32_bf16 v[36:39], v[234:237], v[170:173], v[36:39]
	v_mfma_f32_16x16x32_bf16 v[16:19], v[226:229], v[186:189], v[16:19]
	v_mfma_f32_16x16x32_bf16 v[20:23], v[234:237], v[186:189], v[20:23]
	v_mfma_f32_16x16x32_bf16 v[0:3], v[226:229], v[218:221], v[0:3]
	v_mfma_f32_16x16x32_bf16 v[4:7], v[234:237], v[218:221], v[4:7]
	s_add_i32 s23, 0, 0x18000
	s_barrier
	s_add_u32 s10, s28, 0x40000
	s_addc_u32 s11, s29, 0
	s_mov_b32 m0, s88
	v_lshl_add_u64 v[222:223], s[10:11], 0, v[176:177]
	ds_read_b128 v[158:161], v140 offset:32768
	ds_read_b128 v[162:165], v140 offset:33792
	ds_read_b128 v[166:169], v140 offset:34816
	ds_read_b128 v[170:173], v140 offset:35840
	ds_read_b128 v[182:185], v140 offset:36864
	ds_read_b128 v[186:189], v140 offset:37888
	ds_read_b128 v[214:217], v140 offset:38912
	ds_read_b128 v[218:221], v140 offset:39936
	global_load_lds_dwordx4 v[222:223], off
	v_lshl_add_u64 v[222:223], s[10:11], 0, v[128:129]
	s_mov_b32 m0, s55
	s_nop 0
	global_load_lds_dwordx4 v[222:223], off
	s_waitcnt lgkmcnt(8)
	s_waitcnt vmcnt(10)
	s_barrier
	s_waitcnt lgkmcnt(0)
	s_waitcnt lgkmcnt(0)
	v_mfma_f32_16x16x32_bf16 v[120:123], v[142:145], v[158:161], v[120:123]
	v_mfma_f32_16x16x32_bf16 v[124:127], v[150:153], v[158:161], v[124:127]
	v_mfma_f32_16x16x32_bf16 v[104:107], v[142:145], v[166:169], v[104:107]
	v_mfma_f32_16x16x32_bf16 v[108:111], v[150:153], v[166:169], v[108:111]
	v_mfma_f32_16x16x32_bf16 v[88:91], v[142:145], v[182:185], v[88:91]
	v_mfma_f32_16x16x32_bf16 v[92:95], v[150:153], v[182:185], v[92:95]
	v_mfma_f32_16x16x32_bf16 v[72:75], v[142:145], v[214:217], v[72:75]
	v_mfma_f32_16x16x32_bf16 v[76:79], v[150:153], v[214:217], v[76:79]
	v_mfma_f32_16x16x32_bf16 v[120:123], v[146:149], v[162:165], v[120:123]
	v_mfma_f32_16x16x32_bf16 v[124:127], v[154:157], v[162:165], v[124:127]
	v_mfma_f32_16x16x32_bf16 v[104:107], v[146:149], v[170:173], v[104:107]
	v_mfma_f32_16x16x32_bf16 v[108:111], v[154:157], v[170:173], v[108:111]
	v_mfma_f32_16x16x32_bf16 v[88:91], v[146:149], v[186:189], v[88:91]
	v_mfma_f32_16x16x32_bf16 v[92:95], v[154:157], v[186:189], v[92:95]
	v_mfma_f32_16x16x32_bf16 v[72:75], v[146:149], v[218:221], v[72:75]
	v_mfma_f32_16x16x32_bf16 v[76:79], v[154:157], v[218:221], v[76:79]
	s_barrier
	s_add_i32 s24, 0, 0x1c000
	s_add_i32 s10, s23, s58
	v_add_u32_e32 v141, s24, v139
	v_lshl_add_u64 v[136:137], v[136:137], 0, s[64:65]
	s_mov_b32 m0, s10
	ds_read_b128 v[222:225], v141
	ds_read_b128 v[226:229], v141 offset:1024
	ds_read_b128 v[230:233], v141 offset:2048
	ds_read_b128 v[234:237], v141 offset:3072
	global_load_lds_dwordx4 v[136:137], off
	v_lshl_add_u64 v[136:137], v[174:175], 0, s[64:65]
	s_add_i32 m0, s10, 0x2000
	s_nop 0
	global_load_lds_dwordx4 v[136:137], off
	s_waitcnt vmcnt(10)
	s_barrier
	s_waitcnt lgkmcnt(0)
	s_waitcnt lgkmcnt(0)
	v_mfma_f32_16x16x32_bf16 v[112:115], v[222:225], v[158:161], v[112:115]
	v_mfma_f32_16x16x32_bf16 v[116:119], v[230:233], v[158:161], v[116:119]
	v_mfma_f32_16x16x32_bf16 v[96:99], v[222:225], v[166:169], v[96:99]
	v_mfma_f32_16x16x32_bf16 v[100:103], v[230:233], v[166:169], v[100:103]
	v_mfma_f32_16x16x32_bf16 v[80:83], v[222:225], v[182:185], v[80:83]
	v_mfma_f32_16x16x32_bf16 v[84:87], v[230:233], v[182:185], v[84:87]
	v_mfma_f32_16x16x32_bf16 v[64:67], v[222:225], v[214:217], v[64:67]
	v_mfma_f32_16x16x32_bf16 v[68:71], v[230:233], v[214:217], v[68:71]
	v_mfma_f32_16x16x32_bf16 v[112:115], v[226:229], v[162:165], v[112:115]
	v_mfma_f32_16x16x32_bf16 v[116:119], v[234:237], v[162:165], v[116:119]
	v_mfma_f32_16x16x32_bf16 v[96:99], v[226:229], v[170:173], v[96:99]
	v_mfma_f32_16x16x32_bf16 v[100:103], v[234:237], v[170:173], v[100:103]
	v_mfma_f32_16x16x32_bf16 v[80:83], v[226:229], v[186:189], v[80:83]
	v_mfma_f32_16x16x32_bf16 v[84:87], v[234:237], v[186:189], v[84:87]
	v_mfma_f32_16x16x32_bf16 v[64:67], v[226:229], v[218:221], v[64:67]
	v_mfma_f32_16x16x32_bf16 v[68:71], v[234:237], v[218:221], v[68:71]
	s_mov_b32 m0, s30
	v_lshl_add_u64 v[136:137], v[190:191], 0, s[64:65]
	s_barrier
	ds_read_b128 v[158:161], v140 offset:49152
	ds_read_b128 v[162:165], v140 offset:50176
	ds_read_b128 v[166:169], v140 offset:51200
	ds_read_b128 v[170:173], v140 offset:52224
	ds_read_b128 v[182:185], v140 offset:53248
	ds_read_b128 v[186:189], v140 offset:54272
	ds_read_b128 v[214:217], v140 offset:55296
	ds_read_b128 v[218:221], v140 offset:56320
	global_load_lds_dwordx4 v[136:137], off
	v_lshl_add_u64 v[136:137], v[238:239], 0, s[64:65]
	s_mov_b32 m0, s31
	s_nop 0
	global_load_lds_dwordx4 v[136:137], off
	s_waitcnt vmcnt(10)
	s_barrier
; __device__ __forceinline__ u32x4 mk4(unsigned a, unsigned b, unsigned c, unsigned d) { return (u32x4){a, b, c, d}; }
; __device__ __forceinline__ float silu_f(float x) { return x * __builtin_amdgcn_rcpf(1.f + __expf(-x)); }
; #define G_STAGE(bufoff, gbase) do { _Pragma("unroll") for (int _i = 0; _i < 2; ++_i) \
;     __builtin_amdgcn_global_load_lds((const unsigned*)((const char*)(gbase) + voff[_i]), (GLAS unsigned*)(lds + (bufoff) + ldsw + _i * 8192), 16, 0, 0); } while (0)
; #define G_MMA(ai, bj, At_, Bt_) do { __builtin_amdgcn_s_setprio(1); \
;     _Pragma("unroll") for (int m = 0; m < 4; ++m) _Pragma("unroll") for (int n = 0; n < 2; ++n) _Pragma("unroll") for (int k = 0; k < 2; ++k) \
;       acc[ai][bj][m][n] = __builtin_amdgcn_mfma_f32_16x16x32_bf16(Bt_[n][k], At_[m][k], acc[ai][bj][m][n], 0, 0, 0); \
;     __builtin_amdgcn_s_setprio(0); } while (0)
; #define G_WAIT_V(n) asm volatile("s_waitcnt vmcnt(" #n ")" ::: "memory")
; #define G_WAIT_L(n) asm volatile("s_waitcnt lgkmcnt(" #n ")" ::: "memory")
; #define G_BAR __builtin_amdgcn_s_barrier()
; #define G_SCHED __builtin_amdgcn_sched_barrier(0)
; __device__ __forceinline__ void gemm_phase(const Params& p, int l, const bf16_t* __restrict__ A, const bf16_t* __restrict__ Bt, int M, int N, int K,
;                            int epi, bf16_t* __restrict__ outp, char* smem, int wvi) {
;     ...
;         G_BAR; G_WAIT_L(0); G_MMA(1, 0, At, B0); G_BAR; G_SCHED;
;         G_STAGE(G_SB(1, 1), b3 + hstep);
;         G_WAIT_V(6); G_BAR; G_MMA(1, 1, At, B1); G_BAR;
;     ...
;     } else if (epi == EPI_SWIGLU) {
; #pragma unroll
;       for (int ai = 0; ai < 2; ++ai)
; #pragma unroll
;         for (int m = 0; m < 4; ++m) {
;           bf16_t* rp = outp + (size_t)(r0 + ai * GHALF + m * 16) * DFF + pn * 128 + wc * 32 + fq * 8;
;           unsigned pk[4];
; #pragma unroll
;           for (int bj = 0; bj < 2; ++bj) {
;             const f32x4 g = acc[ai][bj][m][0], u = acc[ai][bj][m][1];
;             const float o0 = silu_f(g[0]) * u[0], o1 = silu_f(g[1]) * u[1], o2 = silu_f(g[2]) * u[2], o3 = silu_f(g[3]) * u[3];
;             pk[2 * bj] = pk2(o0, o1); pk[2 * bj + 1] = pk2(o2, o3);
;           }
;           *reinterpret_cast<u32x4*>(rp) = mk4(pk[0], pk[1], pk[2], pk[3]);
;         }
	s_waitcnt lgkmcnt(0)
	s_waitcnt lgkmcnt(0)
	v_mfma_f32_16x16x32_bf16 v[56:59], v[142:145], v[158:161], v[56:59]
	v_mfma_f32_16x16x32_bf16 v[60:63], v[150:153], v[158:161], v[60:63]
	v_mfma_f32_16x16x32_bf16 v[40:43], v[142:145], v[166:169], v[40:43]
	v_mfma_f32_16x16x32_bf16 v[44:47], v[150:153], v[166:169], v[44:47]
	v_mfma_f32_16x16x32_bf16 v[24:27], v[142:145], v[182:185], v[24:27]
	v_mfma_f32_16x16x32_bf16 v[28:31], v[150:153], v[182:185], v[28:31]
	v_mfma_f32_16x16x32_bf16 v[8:11], v[142:145], v[214:217], v[8:11]
	v_mfma_f32_16x16x32_bf16 v[12:15], v[150:153], v[214:217], v[12:15]
	v_mfma_f32_16x16x32_bf16 v[56:59], v[146:149], v[162:165], v[56:59]
	v_mfma_f32_16x16x32_bf16 v[60:63], v[154:157], v[162:165], v[60:63]
	v_mfma_f32_16x16x32_bf16 v[40:43], v[146:149], v[170:173], v[40:43]
	v_mfma_f32_16x16x32_bf16 v[44:47], v[154:157], v[170:173], v[44:47]
	v_mfma_f32_16x16x32_bf16 v[24:27], v[146:149], v[186:189], v[24:27]
	v_mfma_f32_16x16x32_bf16 v[28:31], v[154:157], v[186:189], v[28:31]
	v_mfma_f32_16x16x32_bf16 v[8:11], v[146:149], v[218:221], v[8:11]
	v_mfma_f32_16x16x32_bf16 v[12:15], v[154:157], v[218:221], v[12:15]
	s_barrier
	s_add_u32 s10, s92, 0x40080
	s_addc_u32 s11, s93, 0
	s_add_i32 s23, s24, s58
	v_lshl_add_u64 v[136:137], s[10:11], 0, v[176:177]
	s_mov_b32 m0, s23
	s_nop 0
	global_load_lds_dwordx4 v[136:137], off
	v_lshl_add_u64 v[136:137], s[10:11], 0, v[128:129]
	s_add_i32 m0, s23, 0x2000
	s_nop 0
	global_load_lds_dwordx4 v[136:137], off
	v_add_u32_e32 v136, 0x10000, v139
	ds_read_b128 v[142:145], v136
	ds_read_b128 v[146:149], v136 offset:1024
	ds_read_b128 v[150:153], v136 offset:2048
	ds_read_b128 v[154:157], v136 offset:3072
	s_waitcnt vmcnt(6)
	s_barrier
	v_mfma_f32_16x16x32_bf16 v[48:51], v[222:225], v[158:161], v[48:51]
	v_mfma_f32_16x16x32_bf16 v[52:55], v[230:233], v[158:161], v[52:55]
	v_mfma_f32_16x16x32_bf16 v[32:35], v[222:225], v[166:169], v[32:35]
	v_mfma_f32_16x16x32_bf16 v[36:39], v[230:233], v[166:169], v[36:39]
	v_mfma_f32_16x16x32_bf16 v[16:19], v[222:225], v[182:185], v[16:19]
	v_mfma_f32_16x16x32_bf16 v[20:23], v[230:233], v[182:185], v[20:23]
	v_mfma_f32_16x16x32_bf16 v[0:3], v[222:225], v[214:217], v[0:3]
	v_mfma_f32_16x16x32_bf16 v[4:7], v[230:233], v[214:217], v[4:7]
	v_mfma_f32_16x16x32_bf16 v[48:51], v[226:229], v[162:165], v[48:51]
	v_mfma_f32_16x16x32_bf16 v[52:55], v[234:237], v[162:165], v[52:55]
	v_mfma_f32_16x16x32_bf16 v[32:35], v[226:229], v[170:173], v[32:35]
	v_mfma_f32_16x16x32_bf16 v[36:39], v[234:237], v[170:173], v[36:39]
	v_mfma_f32_16x16x32_bf16 v[16:19], v[226:229], v[186:189], v[16:19]
	v_mfma_f32_16x16x32_bf16 v[20:23], v[234:237], v[186:189], v[20:23]
	v_mfma_f32_16x16x32_bf16 v[0:3], v[226:229], v[218:221], v[0:3]
	v_mfma_f32_16x16x32_bf16 v[4:7], v[234:237], v[218:221], v[4:7]
	s_add_i32 s22, s22, 2
	s_add_u32 s7, s7, 0x100
	s_addc_u32 s21, s21, 0
	s_cmp_gt_u32 s22, 13
	s_mov_b64 s[10:11], s[2:3]
	s_barrier
	s_cbranch_scc0 .LBB0_320
	v_mul_f32_e32 v252, 0xbfb8aa3b, v120
	v_mul_f32_e32 v253, 0xbfb8aa3b, v121
	v_exp_f32_e32 v252, v252
	v_exp_f32_e32 v253, v253
	s_lshl_b32 s0, s0, 7
	s_ashr_i32 s1, s0, 31
	v_add_f32_e32 v252, 1.0, v252
	v_add_f32_e32 v253, 1.0, v253
	v_rcp_f32_e32 v252, v252
	v_rcp_f32_e32 v253, v253
	v_lshl_add_u32 v141, s16, 8, v138
	v_lshl_add_u64 v[136:137], s[0:1], 1, v[130:131]
	s_movk_i32 s2, 0x1600
	v_pk_mul_f32 v[120:121], v[120:121], v[252:253]
	s_and_b64 vcc, exec, s[14:15]
	v_pk_mul_f32 v[120:121], v[124:125], v[120:121]
	v_mul_f32_e32 v124, 0xbfb8aa3b, v122
	v_mul_f32_e32 v125, 0xbfb8aa3b, v123
	v_exp_f32_e32 v124, v124
	v_exp_f32_e32 v125, v125
	v_cvt_pk_bf16_f32 v120, v120, v121
	v_add_f32_e32 v124, 1.0, v124
	v_add_f32_e32 v125, 1.0, v125
	v_rcp_f32_e32 v124, v124
	v_rcp_f32_e32 v125, v125
	s_nop 0
	v_pk_mul_f32 v[122:123], v[122:123], v[124:125]
	s_nop 0
	v_pk_mul_f32 v[122:123], v[126:127], v[122:123]
	s_nop 0
	v_cvt_pk_bf16_f32 v121, v122, v123
	v_mul_f32_e32 v122, 0xbfb8aa3b, v112
	v_mul_f32_e32 v123, 0xbfb8aa3b, v113
	v_exp_f32_e32 v122, v122
	v_exp_f32_e32 v123, v123
	v_add_f32_e32 v122, 1.0, v122
	v_add_f32_e32 v123, 1.0, v123
	v_rcp_f32_e32 v122, v122
	v_rcp_f32_e32 v123, v123
	s_nop 0
	v_pk_mul_f32 v[112:113], v[112:113], v[122:123]
	s_nop 0
	v_pk_mul_f32 v[112:113], v[116:117], v[112:113]
	v_mul_f32_e32 v116, 0xbfb8aa3b, v114
	v_mul_f32_e32 v117, 0xbfb8aa3b, v115
	v_exp_f32_e32 v116, v116
	v_exp_f32_e32 v117, v117
	v_cvt_pk_bf16_f32 v122, v112, v113
	v_mad_i64_i32 v[112:113], s[0:1], v141, s2, v[136:137]
	v_add_f32_e32 v116, 1.0, v116
	v_add_f32_e32 v117, 1.0, v117
	v_rcp_f32_e32 v116, v116
	v_rcp_f32_e32 v117, v117
	s_nop 0
	v_pk_mul_f32 v[114:115], v[114:115], v[116:117]
	s_nop 0
	v_pk_mul_f32 v[114:115], v[118:119], v[114:115]
	s_nop 0
	v_cvt_pk_bf16_f32 v123, v114, v115
	global_store_dwordx4 v[112:113], v[120:123], off
	v_mul_f32_e32 v112, 0xbfb8aa3b, v104
	v_mul_f32_e32 v113, 0xbfb8aa3b, v105
	v_exp_f32_e32 v112, v112
	v_exp_f32_e32 v113, v113
	v_or_b32_e32 v114, 16, v141
	v_add_f32_e32 v112, 1.0, v112
	v_add_f32_e32 v113, 1.0, v113
	v_rcp_f32_e32 v112, v112
	v_rcp_f32_e32 v113, v113
	s_nop 0
	v_pk_mul_f32 v[104:105], v[104:105], v[112:113]
	s_nop 0
	v_pk_mul_f32 v[104:105], v[108:109], v[104:105]
	v_mul_f32_e32 v108, 0xbfb8aa3b, v106
	v_mul_f32_e32 v109, 0xbfb8aa3b, v107
	v_exp_f32_e32 v108, v108
	v_exp_f32_e32 v109, v109
	v_cvt_pk_bf16_f32 v104, v104, v105
	v_add_f32_e32 v108, 1.0, v108
	v_add_f32_e32 v109, 1.0, v109
	v_rcp_f32_e32 v108, v108
	v_rcp_f32_e32 v109, v109
	s_nop 0
	v_pk_mul_f32 v[106:107], v[106:107], v[108:109]
	s_nop 0
	v_pk_mul_f32 v[106:107], v[110:111], v[106:107]
	s_nop 0
	v_cvt_pk_bf16_f32 v105, v106, v107
; __device__ __forceinline__ u32x4 mk4(unsigned a, unsigned b, unsigned c, unsigned d) { return (u32x4){a, b, c, d}; }
; __device__ __forceinline__ float silu_f(float x) { return x * __builtin_amdgcn_rcpf(1.f + __expf(-x)); }
; __device__ __forceinline__ void gemm_phase(const Params& p, int l, const bf16_t* __restrict__ A, const bf16_t* __restrict__ Bt, int M, int N, int K,
;                            int epi, bf16_t* __restrict__ outp, char* smem, int wvi) {
;     ...
;       for (int ai = 0; ai < 2; ++ai)
; #pragma unroll
;         for (int m = 0; m < 4; ++m) {
;           bf16_t* rp = outp + (size_t)(r0 + ai * GHALF + m * 16) * DFF + pn * 128 + wc * 32 + fq * 8;
;           unsigned pk[4];
; #pragma unroll
;           for (int bj = 0; bj < 2; ++bj) {
;             const f32x4 g = acc[ai][bj][m][0], u = acc[ai][bj][m][1];
;             const float o0 = silu_f(g[0]) * u[0], o1 = silu_f(g[1]) * u[1], o2 = silu_f(g[2]) * u[2], o3 = silu_f(g[3]) * u[3];
;             pk[2 * bj] = pk2(o0, o1); pk[2 * bj + 1] = pk2(o2, o3);
;           }
;           *reinterpret_cast<u32x4*>(rp) = mk4(pk[0], pk[1], pk[2], pk[3]);
	v_mul_f32_e32 v106, 0xbfb8aa3b, v96
	v_mul_f32_e32 v107, 0xbfb8aa3b, v97
	v_exp_f32_e32 v106, v106
	v_exp_f32_e32 v107, v107
	v_add_f32_e32 v106, 1.0, v106
	v_add_f32_e32 v107, 1.0, v107
	v_rcp_f32_e32 v106, v106
	v_rcp_f32_e32 v107, v107
	s_nop 0
	v_pk_mul_f32 v[96:97], v[96:97], v[106:107]
	s_nop 0
	v_pk_mul_f32 v[96:97], v[100:101], v[96:97]
	v_mul_f32_e32 v100, 0xbfb8aa3b, v98
	v_mul_f32_e32 v101, 0xbfb8aa3b, v99
	v_exp_f32_e32 v100, v100
	v_exp_f32_e32 v101, v101
	v_cvt_pk_bf16_f32 v106, v96, v97
	v_mad_i64_i32 v[96:97], s[0:1], v114, s2, v[136:137]
	v_add_f32_e32 v100, 1.0, v100
	v_add_f32_e32 v101, 1.0, v101
	v_rcp_f32_e32 v100, v100
	v_rcp_f32_e32 v101, v101
	s_nop 0
	v_pk_mul_f32 v[98:99], v[98:99], v[100:101]
	s_nop 0
	v_pk_mul_f32 v[98:99], v[102:103], v[98:99]
	s_nop 0
	v_cvt_pk_bf16_f32 v107, v98, v99
	global_store_dwordx4 v[96:97], v[104:107], off
	v_mul_f32_e32 v96, 0xbfb8aa3b, v88
	v_mul_f32_e32 v97, 0xbfb8aa3b, v89
	v_exp_f32_e32 v96, v96
	v_exp_f32_e32 v97, v97
	v_or_b32_e32 v98, 32, v141
	v_add_f32_e32 v96, 1.0, v96
	v_add_f32_e32 v97, 1.0, v97
	v_rcp_f32_e32 v96, v96
	v_rcp_f32_e32 v97, v97
	s_nop 0
	v_pk_mul_f32 v[88:89], v[88:89], v[96:97]
	s_nop 0
	v_pk_mul_f32 v[88:89], v[92:93], v[88:89]
	v_mul_f32_e32 v92, 0xbfb8aa3b, v90
	v_mul_f32_e32 v93, 0xbfb8aa3b, v91
	v_exp_f32_e32 v92, v92
	v_exp_f32_e32 v93, v93
	v_cvt_pk_bf16_f32 v88, v88, v89
	v_add_f32_e32 v92, 1.0, v92
	v_add_f32_e32 v93, 1.0, v93
	v_rcp_f32_e32 v92, v92
	v_rcp_f32_e32 v93, v93
	s_nop 0
	v_pk_mul_f32 v[90:91], v[90:91], v[92:93]
	s_nop 0
	v_pk_mul_f32 v[90:91], v[94:95], v[90:91]
	s_nop 0
	v_cvt_pk_bf16_f32 v89, v90, v91
	v_mul_f32_e32 v90, 0xbfb8aa3b, v80
	v_mul_f32_e32 v91, 0xbfb8aa3b, v81
	v_exp_f32_e32 v90, v90
	v_exp_f32_e32 v91, v91
	v_add_f32_e32 v90, 1.0, v90
	v_add_f32_e32 v91, 1.0, v91
	v_rcp_f32_e32 v90, v90
	v_rcp_f32_e32 v91, v91
	s_nop 0
	v_pk_mul_f32 v[80:81], v[80:81], v[90:91]
	s_nop 0
	v_pk_mul_f32 v[80:81], v[84:85], v[80:81]
	v_mul_f32_e32 v84, 0xbfb8aa3b, v82
	v_mul_f32_e32 v85, 0xbfb8aa3b, v83
	v_exp_f32_e32 v84, v84
	v_exp_f32_e32 v85, v85
	v_cvt_pk_bf16_f32 v90, v80, v81
	v_mad_i64_i32 v[80:81], s[0:1], v98, s2, v[136:137]
	v_add_f32_e32 v84, 1.0, v84
	v_add_f32_e32 v85, 1.0, v85
	v_rcp_f32_e32 v84, v84
	v_rcp_f32_e32 v85, v85
	s_nop 0
	v_pk_mul_f32 v[82:83], v[82:83], v[84:85]
	s_nop 0
	v_pk_mul_f32 v[82:83], v[86:87], v[82:83]
	s_nop 0
	v_cvt_pk_bf16_f32 v91, v82, v83
	global_store_dwordx4 v[80:81], v[88:91], off
	v_mul_f32_e32 v80, 0xbfb8aa3b, v72
	v_mul_f32_e32 v81, 0xbfb8aa3b, v73
	v_exp_f32_e32 v80, v80
	v_exp_f32_e32 v81, v81
	v_or_b32_e32 v82, 48, v141
	v_add_f32_e32 v80, 1.0, v80
	v_add_f32_e32 v81, 1.0, v81
	v_rcp_f32_e32 v80, v80
	v_rcp_f32_e32 v81, v81
	s_nop 0
	v_pk_mul_f32 v[72:73], v[72:73], v[80:81]
	s_nop 0
	v_pk_mul_f32 v[72:73], v[76:77], v[72:73]
	v_mul_f32_e32 v76, 0xbfb8aa3b, v74
	v_mul_f32_e32 v77, 0xbfb8aa3b, v75
	v_exp_f32_e32 v76, v76
	v_exp_f32_e32 v77, v77
	v_cvt_pk_bf16_f32 v72, v72, v73
	v_add_f32_e32 v76, 1.0, v76
	v_add_f32_e32 v77, 1.0, v77
	v_rcp_f32_e32 v76, v76
	v_rcp_f32_e32 v77, v77
	s_nop 0
	v_pk_mul_f32 v[74:75], v[74:75], v[76:77]
	s_nop 0
	v_pk_mul_f32 v[74:75], v[78:79], v[74:75]
	s_nop 0
	v_cvt_pk_bf16_f32 v73, v74, v75
	v_mul_f32_e32 v74, 0xbfb8aa3b, v64
	v_mul_f32_e32 v75, 0xbfb8aa3b, v65
	v_exp_f32_e32 v74, v74
	v_exp_f32_e32 v75, v75
	v_add_f32_e32 v74, 1.0, v74
	v_add_f32_e32 v75, 1.0, v75
	v_rcp_f32_e32 v74, v74
	v_rcp_f32_e32 v75, v75
	s_nop 0
	v_pk_mul_f32 v[64:65], v[64:65], v[74:75]
	s_nop 0
	v_pk_mul_f32 v[64:65], v[68:69], v[64:65]
	v_mul_f32_e32 v68, 0xbfb8aa3b, v66
	v_mul_f32_e32 v69, 0xbfb8aa3b, v67
	v_exp_f32_e32 v68, v68
	v_exp_f32_e32 v69, v69
	v_cvt_pk_bf16_f32 v74, v64, v65
	v_mad_i64_i32 v[64:65], s[0:1], v82, s2, v[136:137]
	v_add_f32_e32 v68, 1.0, v68
	v_add_f32_e32 v69, 1.0, v69
	v_rcp_f32_e32 v68, v68
	v_rcp_f32_e32 v69, v69
	s_nop 0
	v_pk_mul_f32 v[66:67], v[66:67], v[68:69]
	s_nop 0
	v_pk_mul_f32 v[66:67], v[70:71], v[66:67]
	s_nop 0
	v_cvt_pk_bf16_f32 v75, v66, v67
	global_store_dwordx4 v[64:65], v[72:75], off
	v_mul_f32_e32 v64, 0xbfb8aa3b, v56
	v_mul_f32_e32 v65, 0xbfb8aa3b, v57
	v_exp_f32_e32 v64, v64
	v_exp_f32_e32 v65, v65
	v_add_u32_e32 v66, 0x80, v141
	v_add_f32_e32 v64, 1.0, v64
	v_add_f32_e32 v65, 1.0, v65
	v_rcp_f32_e32 v64, v64
	v_rcp_f32_e32 v65, v65
	s_nop 0
	v_pk_mul_f32 v[56:57], v[56:57], v[64:65]
	s_nop 0
	v_pk_mul_f32 v[56:57], v[60:61], v[56:57]
	v_mul_f32_e32 v60, 0xbfb8aa3b, v58
	v_mul_f32_e32 v61, 0xbfb8aa3b, v59
	v_exp_f32_e32 v60, v60
	v_exp_f32_e32 v61, v61
	v_cvt_pk_bf16_f32 v56, v56, v57
	v_add_f32_e32 v60, 1.0, v60
	v_add_f32_e32 v61, 1.0, v61
	v_rcp_f32_e32 v60, v60
	v_rcp_f32_e32 v61, v61
	s_nop 0
	v_pk_mul_f32 v[58:59], v[58:59], v[60:61]
	s_nop 0
	v_pk_mul_f32 v[58:59], v[62:63], v[58:59]
	s_nop 0
	v_cvt_pk_bf16_f32 v57, v58, v59
	v_mul_f32_e32 v58, 0xbfb8aa3b, v48
	v_mul_f32_e32 v59, 0xbfb8aa3b, v49
	v_exp_f32_e32 v58, v58
	v_exp_f32_e32 v59, v59
	v_add_f32_e32 v58, 1.0, v58
	v_add_f32_e32 v59, 1.0, v59
	v_rcp_f32_e32 v58, v58
	v_rcp_f32_e32 v59, v59
	s_nop 0
	v_pk_mul_f32 v[48:49], v[48:49], v[58:59]
	s_nop 0
	v_pk_mul_f32 v[48:49], v[52:53], v[48:49]
	v_mul_f32_e32 v52, 0xbfb8aa3b, v50
	v_mul_f32_e32 v53, 0xbfb8aa3b, v51
	v_exp_f32_e32 v52, v52
	v_exp_f32_e32 v53, v53
	v_cvt_pk_bf16_f32 v58, v48, v49
	v_mad_i64_i32 v[48:49], s[0:1], v66, s2, v[136:137]
	v_add_f32_e32 v52, 1.0, v52
	v_add_f32_e32 v53, 1.0, v53
	v_rcp_f32_e32 v52, v52
	v_rcp_f32_e32 v53, v53
	s_nop 0
	v_pk_mul_f32 v[50:51], v[50:51], v[52:53]
	s_nop 0
	v_pk_mul_f32 v[50:51], v[54:55], v[50:51]
	s_nop 0
	v_cvt_pk_bf16_f32 v59, v50, v51
; __device__ __forceinline__ u32x4 mk4(unsigned a, unsigned b, unsigned c, unsigned d) { return (u32x4){a, b, c, d}; }
; __device__ __forceinline__ float silu_f(float x) { return x * __builtin_amdgcn_rcpf(1.f + __expf(-x)); }
; __device__ __forceinline__ void gemm_phase(const Params& p, int l, const bf16_t* __restrict__ A, const bf16_t* __restrict__ Bt, int M, int N, int K,
;                            int epi, bf16_t* __restrict__ outp, char* smem, int wvi) {
;     ...
;       for (int ai = 0; ai < 2; ++ai)
; #pragma unroll
;         for (int m = 0; m < 4; ++m) {
;           bf16_t* rp = outp + (size_t)(r0 + ai * GHALF + m * 16) * DFF + pn * 128 + wc * 32 + fq * 8;
;           unsigned pk[4];
; #pragma unroll
;           for (int bj = 0; bj < 2; ++bj) {
;             const f32x4 g = acc[ai][bj][m][0], u = acc[ai][bj][m][1];
;             const float o0 = silu_f(g[0]) * u[0], o1 = silu_f(g[1]) * u[1], o2 = silu_f(g[2]) * u[2], o3 = silu_f(g[3]) * u[3];
;             pk[2 * bj] = pk2(o0, o1); pk[2 * bj + 1] = pk2(o2, o3);
;           }
;           *reinterpret_cast<u32x4*>(rp) = mk4(pk[0], pk[1], pk[2], pk[3]);
;         }
	global_store_dwordx4 v[48:49], v[56:59], off
	v_mul_f32_e32 v48, 0xbfb8aa3b, v40
	v_mul_f32_e32 v49, 0xbfb8aa3b, v41
	v_exp_f32_e32 v48, v48
	v_exp_f32_e32 v49, v49
	v_add_u32_e32 v50, 0x90, v141
	v_add_f32_e32 v48, 1.0, v48
	v_add_f32_e32 v49, 1.0, v49
	v_rcp_f32_e32 v48, v48
	v_rcp_f32_e32 v49, v49
	s_nop 0
	v_pk_mul_f32 v[40:41], v[40:41], v[48:49]
	s_nop 0
	v_pk_mul_f32 v[40:41], v[44:45], v[40:41]
	v_mul_f32_e32 v44, 0xbfb8aa3b, v42
	v_mul_f32_e32 v45, 0xbfb8aa3b, v43
	v_exp_f32_e32 v44, v44
	v_exp_f32_e32 v45, v45
	v_cvt_pk_bf16_f32 v40, v40, v41
	v_add_f32_e32 v44, 1.0, v44
	v_add_f32_e32 v45, 1.0, v45
	v_rcp_f32_e32 v44, v44
	v_rcp_f32_e32 v45, v45
	s_nop 0
	v_pk_mul_f32 v[42:43], v[42:43], v[44:45]
	s_nop 0
	v_pk_mul_f32 v[42:43], v[46:47], v[42:43]
	s_nop 0
	v_cvt_pk_bf16_f32 v41, v42, v43
	v_mul_f32_e32 v42, 0xbfb8aa3b, v32
	v_mul_f32_e32 v43, 0xbfb8aa3b, v33
	v_exp_f32_e32 v42, v42
	v_exp_f32_e32 v43, v43
	v_add_f32_e32 v42, 1.0, v42
	v_add_f32_e32 v43, 1.0, v43
	v_rcp_f32_e32 v42, v42
	v_rcp_f32_e32 v43, v43
	s_nop 0
	v_pk_mul_f32 v[32:33], v[32:33], v[42:43]
	s_nop 0
	v_pk_mul_f32 v[32:33], v[36:37], v[32:33]
	v_mul_f32_e32 v36, 0xbfb8aa3b, v34
	v_mul_f32_e32 v37, 0xbfb8aa3b, v35
	v_exp_f32_e32 v36, v36
	v_exp_f32_e32 v37, v37
	v_cvt_pk_bf16_f32 v42, v32, v33
	v_mad_i64_i32 v[32:33], s[0:1], v50, s2, v[136:137]
	v_add_f32_e32 v36, 1.0, v36
	v_add_f32_e32 v37, 1.0, v37
	v_rcp_f32_e32 v36, v36
	v_rcp_f32_e32 v37, v37
	s_nop 0
	v_pk_mul_f32 v[34:35], v[34:35], v[36:37]
	s_nop 0
	v_pk_mul_f32 v[34:35], v[38:39], v[34:35]
	s_nop 0
	v_cvt_pk_bf16_f32 v43, v34, v35
	global_store_dwordx4 v[32:33], v[40:43], off
	v_mul_f32_e32 v32, 0xbfb8aa3b, v24
	v_mul_f32_e32 v33, 0xbfb8aa3b, v25
	v_exp_f32_e32 v32, v32
	v_exp_f32_e32 v33, v33
	v_add_u32_e32 v34, 0xa0, v141
	v_add_f32_e32 v32, 1.0, v32
	v_add_f32_e32 v33, 1.0, v33
	v_rcp_f32_e32 v32, v32
	v_rcp_f32_e32 v33, v33
	s_nop 0
	v_pk_mul_f32 v[24:25], v[24:25], v[32:33]
	s_nop 0
	v_pk_mul_f32 v[24:25], v[28:29], v[24:25]
	v_mul_f32_e32 v28, 0xbfb8aa3b, v26
	v_mul_f32_e32 v29, 0xbfb8aa3b, v27
	v_exp_f32_e32 v28, v28
	v_exp_f32_e32 v29, v29
	v_cvt_pk_bf16_f32 v24, v24, v25
	v_add_f32_e32 v28, 1.0, v28
	v_add_f32_e32 v29, 1.0, v29
	v_rcp_f32_e32 v28, v28
	v_rcp_f32_e32 v29, v29
	s_nop 0
	v_pk_mul_f32 v[26:27], v[26:27], v[28:29]
	s_nop 0
	v_pk_mul_f32 v[26:27], v[30:31], v[26:27]
	s_nop 0
	v_cvt_pk_bf16_f32 v25, v26, v27
	v_mul_f32_e32 v26, 0xbfb8aa3b, v16
	v_mul_f32_e32 v27, 0xbfb8aa3b, v17
	v_exp_f32_e32 v26, v26
	v_exp_f32_e32 v27, v27
	v_add_f32_e32 v26, 1.0, v26
	v_add_f32_e32 v27, 1.0, v27
	v_rcp_f32_e32 v26, v26
	v_rcp_f32_e32 v27, v27
	s_nop 0
	v_pk_mul_f32 v[16:17], v[16:17], v[26:27]
	s_nop 0
	v_pk_mul_f32 v[16:17], v[20:21], v[16:17]
	v_mul_f32_e32 v20, 0xbfb8aa3b, v18
	v_mul_f32_e32 v21, 0xbfb8aa3b, v19
	v_exp_f32_e32 v20, v20
	v_exp_f32_e32 v21, v21
	v_cvt_pk_bf16_f32 v26, v16, v17
	v_mad_i64_i32 v[16:17], s[0:1], v34, s2, v[136:137]
	v_add_f32_e32 v20, 1.0, v20
	v_add_f32_e32 v21, 1.0, v21
	v_rcp_f32_e32 v20, v20
	v_rcp_f32_e32 v21, v21
	s_nop 0
	v_pk_mul_f32 v[18:19], v[18:19], v[20:21]
	s_nop 0
	v_pk_mul_f32 v[18:19], v[22:23], v[18:19]
	s_nop 0
	v_cvt_pk_bf16_f32 v27, v18, v19
	global_store_dwordx4 v[16:17], v[24:27], off
	v_mul_f32_e32 v16, 0xbfb8aa3b, v8
	v_mul_f32_e32 v17, 0xbfb8aa3b, v9
	v_exp_f32_e32 v16, v16
	v_exp_f32_e32 v17, v17
	v_add_u32_e32 v18, 0xb0, v141
	v_add_f32_e32 v16, 1.0, v16
	v_add_f32_e32 v17, 1.0, v17
	v_rcp_f32_e32 v16, v16
	v_rcp_f32_e32 v17, v17
	s_nop 0
	v_pk_mul_f32 v[8:9], v[8:9], v[16:17]
	s_nop 0
	v_pk_mul_f32 v[8:9], v[12:13], v[8:9]
	v_mul_f32_e32 v12, 0xbfb8aa3b, v10
	v_mul_f32_e32 v13, 0xbfb8aa3b, v11
	v_exp_f32_e32 v12, v12
	v_exp_f32_e32 v13, v13
	v_cvt_pk_bf16_f32 v8, v8, v9
	v_add_f32_e32 v12, 1.0, v12
	v_add_f32_e32 v13, 1.0, v13
	v_rcp_f32_e32 v12, v12
	v_rcp_f32_e32 v13, v13
	s_nop 0
	v_pk_mul_f32 v[10:11], v[10:11], v[12:13]
	s_nop 0
	v_pk_mul_f32 v[10:11], v[14:15], v[10:11]
	s_nop 0
	v_cvt_pk_bf16_f32 v9, v10, v11
	v_mul_f32_e32 v10, 0xbfb8aa3b, v0
	v_mul_f32_e32 v11, 0xbfb8aa3b, v1
	v_exp_f32_e32 v10, v10
	v_exp_f32_e32 v11, v11
	v_add_f32_e32 v10, 1.0, v10
	v_add_f32_e32 v11, 1.0, v11
	v_rcp_f32_e32 v10, v10
	v_rcp_f32_e32 v11, v11
	s_nop 0
	v_pk_mul_f32 v[0:1], v[0:1], v[10:11]
	s_nop 0
	v_pk_mul_f32 v[0:1], v[4:5], v[0:1]
	v_mul_f32_e32 v4, 0xbfb8aa3b, v2
	v_mul_f32_e32 v5, 0xbfb8aa3b, v3
	v_exp_f32_e32 v4, v4
	v_exp_f32_e32 v5, v5
	v_cvt_pk_bf16_f32 v10, v0, v1
	v_mad_i64_i32 v[0:1], s[0:1], v18, s2, v[136:137]
	v_add_f32_e32 v4, 1.0, v4
	v_add_f32_e32 v5, 1.0, v5
	v_rcp_f32_e32 v4, v4
	v_rcp_f32_e32 v5, v5
	s_mov_b64 s[2:3], -1
	v_pk_mul_f32 v[2:3], v[2:3], v[4:5]
	s_nop 0
	v_pk_mul_f32 v[2:3], v[6:7], v[2:3]
	s_nop 0
	v_cvt_pk_bf16_f32 v11, v2, v3
	global_store_dwordx4 v[0:1], v[8:11], off
	s_cbranch_vccz .LBB0_316
; __device__ __forceinline__ f32x4 zero4() { float z = 0.f; asm volatile("" : "+v"(z)); return (f32x4){z, z, z, z}; }
; __device__ __forceinline__ void gemm_phase(const Params& p, int l, const bf16_t* __restrict__ A, const bf16_t* __restrict__ Bt, int M, int N, int K,
;                            int epi, bf16_t* __restrict__ outp, char* smem, int wvi) {
;     ...
;       if (!has_next) break;
; #pragma unroll
;       for (int a = 0; a < 2; ++a)
; #pragma unroll
;         for (int b = 0; b < 2; ++b)
; #pragma unroll
;           for (int m = 0; m < 4; ++m)
; #pragma unroll
;             for (int n = 0; n < 2; ++n) acc[a][b][m][n] = zero4();
;       Lw = Ln; pm = npm; pn = npn; cA = nA; cB = nB;
	v_mov_b32_e32 v120, v177
	v_mov_b32_e32 v124, v177
	v_mov_b32_e32 v104, v177
	v_mov_b32_e32 v108, v177
	v_mov_b32_e32 v88, v177
	v_mov_b32_e32 v92, v177
	v_mov_b32_e32 v72, v177
	v_mov_b32_e32 v76, v177
	v_mov_b32_e32 v112, v177
	v_mov_b32_e32 v116, v177
	v_mov_b32_e32 v96, v177
	v_mov_b32_e32 v100, v177
	v_mov_b32_e32 v80, v177
	v_mov_b32_e32 v84, v177
	v_mov_b32_e32 v64, v177
	v_mov_b32_e32 v68, v177
	v_mov_b32_e32 v56, v177
	v_mov_b32_e32 v60, v177
	v_mov_b32_e32 v40, v177
	v_mov_b32_e32 v44, v177
	v_mov_b32_e32 v24, v177
	v_mov_b32_e32 v28, v177
	v_mov_b32_e32 v8, v177
	v_mov_b32_e32 v12, v177
	v_mov_b32_e32 v48, v177
	v_mov_b32_e32 v52, v177
	v_mov_b32_e32 v32, v177
	v_mov_b32_e32 v36, v177
	v_mov_b32_e32 v16, v177
	v_mov_b32_e32 v20, v177
	v_mov_b32_e32 v0, v177
	v_mov_b32_e32 v4, v177
	s_nop 0
	v_mov_b32_e32 v121, v120
	v_mov_b32_e32 v122, v120
	v_mov_b32_e32 v123, v120
	v_mov_b32_e32 v125, v124
	v_mov_b32_e32 v126, v124
	v_mov_b32_e32 v127, v124
	v_mov_b32_e32 v105, v104
	v_mov_b32_e32 v106, v104
	v_mov_b32_e32 v107, v104
	v_mov_b32_e32 v109, v108
	v_mov_b32_e32 v110, v108
	v_mov_b32_e32 v111, v108
	v_mov_b32_e32 v89, v88
	v_mov_b32_e32 v90, v88
	v_mov_b32_e32 v91, v88
	v_mov_b32_e32 v93, v92
	v_mov_b32_e32 v94, v92
	v_mov_b32_e32 v95, v92
	s_nop 0
	v_mov_b32_e32 v73, v72
	v_mov_b32_e32 v74, v72
	v_mov_b32_e32 v75, v72
	v_mov_b32_e32 v77, v76
	v_mov_b32_e32 v78, v76
	v_mov_b32_e32 v79, v76
	v_mov_b32_e32 v113, v112
	v_mov_b32_e32 v114, v112
	v_mov_b32_e32 v115, v112
	v_mov_b32_e32 v117, v116
	v_mov_b32_e32 v118, v116
	v_mov_b32_e32 v119, v116
	v_mov_b32_e32 v97, v96
	v_mov_b32_e32 v98, v96
	v_mov_b32_e32 v99, v96
	v_mov_b32_e32 v101, v100
	v_mov_b32_e32 v102, v100
	v_mov_b32_e32 v103, v100
	s_nop 0
	v_mov_b32_e32 v81, v80
	v_mov_b32_e32 v82, v80
	v_mov_b32_e32 v83, v80
	v_mov_b32_e32 v85, v84
	v_mov_b32_e32 v86, v84
	v_mov_b32_e32 v87, v84
	v_mov_b32_e32 v65, v64
	v_mov_b32_e32 v66, v64
	v_mov_b32_e32 v67, v64
	v_mov_b32_e32 v69, v68
	v_mov_b32_e32 v70, v68
	v_mov_b32_e32 v71, v68
	v_mov_b32_e32 v57, v56
	v_mov_b32_e32 v58, v56
	v_mov_b32_e32 v59, v56
	v_mov_b32_e32 v61, v60
	v_mov_b32_e32 v62, v60
	v_mov_b32_e32 v63, v60
	s_nop 0
	v_mov_b32_e32 v41, v40
	v_mov_b32_e32 v42, v40
	v_mov_b32_e32 v43, v40
	v_mov_b32_e32 v45, v44
	v_mov_b32_e32 v46, v44
	v_mov_b32_e32 v47, v44
	v_mov_b32_e32 v25, v24
	v_mov_b32_e32 v26, v24
	v_mov_b32_e32 v27, v24
	v_mov_b32_e32 v29, v28
	v_mov_b32_e32 v30, v28
	v_mov_b32_e32 v31, v28
	v_mov_b32_e32 v9, v8
	v_mov_b32_e32 v10, v8
	v_mov_b32_e32 v11, v8
	v_mov_b32_e32 v13, v12
	v_mov_b32_e32 v14, v12
	v_mov_b32_e32 v15, v12
	s_nop 0
	v_mov_b32_e32 v49, v48
	v_mov_b32_e32 v50, v48
	v_mov_b32_e32 v51, v48
	v_mov_b32_e32 v53, v52
	v_mov_b32_e32 v54, v52
	v_mov_b32_e32 v55, v52
	v_mov_b32_e32 v33, v32
	v_mov_b32_e32 v34, v32
	v_mov_b32_e32 v35, v32
	v_mov_b32_e32 v37, v36
	v_mov_b32_e32 v38, v36
	v_mov_b32_e32 v39, v36
	v_mov_b32_e32 v17, v16
	v_mov_b32_e32 v18, v16
	v_mov_b32_e32 v19, v16
	v_mov_b32_e32 v21, v20
	v_mov_b32_e32 v22, v20
	v_mov_b32_e32 v23, v20
	s_mov_b64 s[2:3], 0
	v_mov_b32_e32 v1, v0
	v_mov_b32_e32 v2, v0
	v_mov_b32_e32 v3, v0
	v_mov_b32_e32 v5, v4
	v_mov_b32_e32 v6, v4
	v_mov_b32_e32 v7, v4
	s_branch .LBB0_316

; #define G_STAGE(bufoff, gbase) do { _Pragma("unroll") for (int _i = 0; _i < 2; ++_i) \
;     __builtin_amdgcn_global_load_lds((const unsigned*)((const char*)(gbase) + voff[_i]), (GLAS unsigned*)(lds + (bufoff) + ldsw + _i * 8192), 16, 0, 0); } while (0)
; #define G_LDA(dst, b, h) do { _Pragma("unroll") for (int m = 0; m < 4; ++m) _Pragma("unroll") for (int k = 0; k < 2; ++k) \
;     dst[m][k] = *(const GLAS bf16x8*)(lds + G_SA(b, h) + aoff + m * 2048 + k * 1024); } while (0)
; #define G_LDB(dst, b, h) do { _Pragma("unroll") for (int n = 0; n < 2; ++n) _Pragma("unroll") for (int k = 0; k < 2; ++k) \
;     dst[n][k] = *(const GLAS bf16x8*)(lds + G_SB(b, h) + boff + n * 2048 + k * 1024); } while (0)
; #define G_MMA(ai, bj, At_, Bt_) do { __builtin_amdgcn_s_setprio(1); \
;     _Pragma("unroll") for (int m = 0; m < 4; ++m) _Pragma("unroll") for (int n = 0; n < 2; ++n) _Pragma("unroll") for (int k = 0; k < 2; ++k) \
;       acc[ai][bj][m][n] = __builtin_amdgcn_mfma_f32_16x16x32_bf16(Bt_[n][k], At_[m][k], acc[ai][bj][m][n], 0, 0, 0); \
;     __builtin_amdgcn_s_setprio(0); } while (0)
; #define G_WAIT_L(n) asm volatile("s_waitcnt lgkmcnt(" #n ")" ::: "memory")
; #define G_BAR __builtin_amdgcn_s_barrier()
; #define G_SCHED __builtin_amdgcn_sched_barrier(0)
; __device__ __forceinline__ void gemm_phase(const Params& p, int l, const bf16_t* __restrict__ A, const bf16_t* __restrict__ Bt, int M, int N, int K,
;                            int epi, bf16_t* __restrict__ outp, char* smem, int wvi) {
;     ...
;       for (int t = 0; t < nt; t += 2) {
;         const bool lastt = (t == nt - 2);
;         const char* a1 = cA + (size_t)(t + 1) * kstep;
;         const char* a2 = lastt ? nA : cA + (size_t)(t + 2) * kstep; const char* b2 = lastt ? nB : cB + (size_t)(t + 2) * kstep;
;         const char* a3 = a2 + kstep; const char* b3 = b2 + kstep;
;         G_LDB(B0, 0, 0); G_SCHED; G_LDA(At, 0, 0); G_STAGE(G_SA(1, 1), a1 + hstep);
;         G_WAIT_L(8); G_BAR; G_WAIT_L(0); G_MMA(0, 0, At, B0); G_BAR; G_SCHED;
;         G_LDB(B1, 0, 1); G_STAGE(G_SB(0, 0), b2);
;         G_BAR; G_WAIT_L(0); G_MMA(0, 1, At, B1); G_BAR;
;         G_LDA(At, 0, 1); G_STAGE(G_SA(0, 0), a2);
;         G_BAR; G_WAIT_L(0); G_MMA(1, 0, At, B0); G_BAR; G_SCHED;
.LBB0_373:
	s_add_u32 s2, s16, 0x100
	s_addc_u32 s3, s17, 0
	s_add_i32 s34, 0, 0x10000
	s_cmp_eq_u32 s55, 12
	s_cselect_b32 s29, s11, s3
	s_cselect_b32 s28, s10, s2
	s_cselect_b32 s13, s7, s53
	s_cselect_b32 s12, s5, s31
	v_lshl_add_u64 v[190:191], s[16:17], 0, v[132:133]
	s_add_i32 m0, s9, 0xc000
	ds_read_b128 v[156:159], v138
	ds_read_b128 v[160:163], v138 offset:1024
	ds_read_b128 v[164:167], v138 offset:2048
	ds_read_b128 v[168:171], v138 offset:3072
	ds_read_b128 v[172:175], v138 offset:4096
	ds_read_b128 v[182:185], v138 offset:5120
	ds_read_b128 v[186:189], v138 offset:6144
	ds_read_b128 v[214:217], v138 offset:7168
	global_load_lds_dwordx4 v[190:191], off
	v_lshl_add_u64 v[190:191], s[16:17], 0, v[134:135]
	s_add_i32 m0, s9, 0xe000
	s_nop 0
	global_load_lds_dwordx4 v[190:191], off
	s_waitcnt lgkmcnt(8)
	s_barrier
	s_waitcnt lgkmcnt(0)
	s_waitcnt lgkmcnt(0)
	v_mfma_f32_16x16x32_bf16 v[20:23], v[140:143], v[156:159], v[20:23]
	v_mfma_f32_16x16x32_bf16 v[28:31], v[148:151], v[156:159], v[28:31]
	v_mfma_f32_16x16x32_bf16 v[12:15], v[140:143], v[164:167], v[12:15]
	v_mfma_f32_16x16x32_bf16 v[24:27], v[148:151], v[164:167], v[24:27]
	v_mfma_f32_16x16x32_bf16 v[4:7], v[140:143], v[172:175], v[4:7]
	v_mfma_f32_16x16x32_bf16 v[16:19], v[148:151], v[172:175], v[16:19]
	v_mfma_f32_16x16x32_bf16 v[0:3], v[140:143], v[186:189], v[0:3]
	v_mfma_f32_16x16x32_bf16 v[8:11], v[148:151], v[186:189], v[8:11]
	v_mfma_f32_16x16x32_bf16 v[20:23], v[144:147], v[160:163], v[20:23]
	v_mfma_f32_16x16x32_bf16 v[28:31], v[152:155], v[160:163], v[28:31]
	v_mfma_f32_16x16x32_bf16 v[12:15], v[144:147], v[168:171], v[12:15]
	v_mfma_f32_16x16x32_bf16 v[24:27], v[152:155], v[168:171], v[24:27]
	v_mfma_f32_16x16x32_bf16 v[4:7], v[144:147], v[182:185], v[4:7]
	v_mfma_f32_16x16x32_bf16 v[16:19], v[152:155], v[182:185], v[16:19]
	v_mfma_f32_16x16x32_bf16 v[0:3], v[144:147], v[214:217], v[0:3]
	v_mfma_f32_16x16x32_bf16 v[8:11], v[152:155], v[214:217], v[8:11]
	s_barrier
	s_add_i32 s35, 0, 0x14000
	s_add_i32 s16, s34, s58
	v_add_u32_e32 v139, s35, v137
	v_lshl_add_u64 v[190:191], s[12:13], 0, v[176:177]
	s_mov_b32 m0, s16
	ds_read_b128 v[218:221], v139
	ds_read_b128 v[222:225], v139 offset:1024
	ds_read_b128 v[226:229], v139 offset:2048
	ds_read_b128 v[230:233], v139 offset:3072
	global_load_lds_dwordx4 v[190:191], off
	v_lshl_add_u64 v[234:235], s[12:13], 0, v[128:129]
	s_add_i32 m0, s16, 0x2000
	s_nop 0
	global_load_lds_dwordx4 v[234:235], off
	s_barrier
	s_waitcnt lgkmcnt(0)
	s_waitcnt lgkmcnt(0)
	v_mfma_f32_16x16x32_bf16 v[80:83], v[218:221], v[156:159], v[80:83]
	v_mfma_f32_16x16x32_bf16 v[92:95], v[226:229], v[156:159], v[92:95]
	v_mfma_f32_16x16x32_bf16 v[64:67], v[218:221], v[164:167], v[64:67]
	v_mfma_f32_16x16x32_bf16 v[84:87], v[226:229], v[164:167], v[84:87]
	v_mfma_f32_16x16x32_bf16 v[52:55], v[218:221], v[172:175], v[52:55]
	v_mfma_f32_16x16x32_bf16 v[76:79], v[226:229], v[172:175], v[76:79]
	v_mfma_f32_16x16x32_bf16 v[40:43], v[218:221], v[186:189], v[40:43]
	v_mfma_f32_16x16x32_bf16 v[60:63], v[226:229], v[186:189], v[60:63]
	v_mfma_f32_16x16x32_bf16 v[80:83], v[222:225], v[160:163], v[80:83]
	v_mfma_f32_16x16x32_bf16 v[92:95], v[230:233], v[160:163], v[92:95]
	v_mfma_f32_16x16x32_bf16 v[64:67], v[222:225], v[168:171], v[64:67]
	v_mfma_f32_16x16x32_bf16 v[84:87], v[230:233], v[168:171], v[84:87]
	v_mfma_f32_16x16x32_bf16 v[52:55], v[222:225], v[182:185], v[52:55]
	v_mfma_f32_16x16x32_bf16 v[76:79], v[230:233], v[182:185], v[76:79]
	v_mfma_f32_16x16x32_bf16 v[40:43], v[222:225], v[214:217], v[40:43]
	v_mfma_f32_16x16x32_bf16 v[60:63], v[230:233], v[214:217], v[60:63]
	s_mov_b32 m0, s9
	v_lshl_add_u64 v[236:237], s[28:29], 0, v[176:177]
	s_barrier
	ds_read_b128 v[156:159], v138 offset:16384
	ds_read_b128 v[160:163], v138 offset:17408
	ds_read_b128 v[164:167], v138 offset:18432
	ds_read_b128 v[168:171], v138 offset:19456
	ds_read_b128 v[172:175], v138 offset:20480
	ds_read_b128 v[182:185], v138 offset:21504
	ds_read_b128 v[186:189], v138 offset:22528
	ds_read_b128 v[214:217], v138 offset:23552
	global_load_lds_dwordx4 v[236:237], off
	v_lshl_add_u64 v[238:239], s[28:29], 0, v[128:129]
	s_mov_b32 m0, s24
	s_nop 0
	global_load_lds_dwordx4 v[238:239], off
	s_waitcnt vmcnt(10)
	s_barrier
	s_waitcnt lgkmcnt(0)
	s_waitcnt lgkmcnt(0)
	v_mfma_f32_16x16x32_bf16 v[68:71], v[140:143], v[156:159], v[68:71]
	v_mfma_f32_16x16x32_bf16 v[88:91], v[148:151], v[156:159], v[88:91]
	v_mfma_f32_16x16x32_bf16 v[48:51], v[140:143], v[164:167], v[48:51]
	v_mfma_f32_16x16x32_bf16 v[72:75], v[148:151], v[164:167], v[72:75]
	v_mfma_f32_16x16x32_bf16 v[36:39], v[140:143], v[172:175], v[36:39]
	v_mfma_f32_16x16x32_bf16 v[56:59], v[148:151], v[172:175], v[56:59]
	v_mfma_f32_16x16x32_bf16 v[32:35], v[140:143], v[186:189], v[32:35]
	v_mfma_f32_16x16x32_bf16 v[44:47], v[148:151], v[186:189], v[44:47]
	v_mfma_f32_16x16x32_bf16 v[68:71], v[144:147], v[160:163], v[68:71]
	v_mfma_f32_16x16x32_bf16 v[88:91], v[152:155], v[160:163], v[88:91]
	v_mfma_f32_16x16x32_bf16 v[48:51], v[144:147], v[168:171], v[48:51]
	v_mfma_f32_16x16x32_bf16 v[72:75], v[152:155], v[168:171], v[72:75]
	v_mfma_f32_16x16x32_bf16 v[36:39], v[144:147], v[182:185], v[36:39]
	v_mfma_f32_16x16x32_bf16 v[56:59], v[152:155], v[182:185], v[56:59]
	v_mfma_f32_16x16x32_bf16 v[32:35], v[144:147], v[214:217], v[32:35]
	v_mfma_f32_16x16x32_bf16 v[44:47], v[152:155], v[214:217], v[44:47]
	s_barrier
; #define G_STAGE(bufoff, gbase) do { _Pragma("unroll") for (int _i = 0; _i < 2; ++_i) \
;     __builtin_amdgcn_global_load_lds((const unsigned*)((const char*)(gbase) + voff[_i]), (GLAS unsigned*)(lds + (bufoff) + ldsw + _i * 8192), 16, 0, 0); } while (0)
; #define G_LDA(dst, b, h) do { _Pragma("unroll") for (int m = 0; m < 4; ++m) _Pragma("unroll") for (int k = 0; k < 2; ++k) \
;     dst[m][k] = *(const GLAS bf16x8*)(lds + G_SA(b, h) + aoff + m * 2048 + k * 1024); } while (0)
; #define G_LDB(dst, b, h) do { _Pragma("unroll") for (int n = 0; n < 2; ++n) _Pragma("unroll") for (int k = 0; k < 2; ++k) \
;     dst[n][k] = *(const GLAS bf16x8*)(lds + G_SB(b, h) + boff + n * 2048 + k * 1024); } while (0)
; #define G_MMA(ai, bj, At_, Bt_) do { __builtin_amdgcn_s_setprio(1); \
;     _Pragma("unroll") for (int m = 0; m < 4; ++m) _Pragma("unroll") for (int n = 0; n < 2; ++n) _Pragma("unroll") for (int k = 0; k < 2; ++k) \
;       acc[ai][bj][m][n] = __builtin_amdgcn_mfma_f32_16x16x32_bf16(Bt_[n][k], At_[m][k], acc[ai][bj][m][n], 0, 0, 0); \
;     __builtin_amdgcn_s_setprio(0); } while (0)
; #define G_WAIT_V(n) asm volatile("s_waitcnt vmcnt(" #n ")" ::: "memory")
; #define G_WAIT_L(n) asm volatile("s_waitcnt lgkmcnt(" #n ")" ::: "memory")
; #define G_BAR __builtin_amdgcn_s_barrier()
; #define G_SCHED __builtin_amdgcn_sched_barrier(0)
; __device__ __forceinline__ void gemm_phase(const Params& p, int l, const bf16_t* __restrict__ A, const bf16_t* __restrict__ Bt, int M, int N, int K,
;                            int epi, bf16_t* __restrict__ outp, char* smem, int wvi) {
;     ...
;         G_STAGE(G_SB(0, 1), b2 + hstep);
;         G_WAIT_V(6); G_BAR; G_MMA(1, 1, At, B1); G_BAR;
;         G_LDB(B0, 1, 0); G_SCHED; G_LDA(At, 1, 0); G_STAGE(G_SA(0, 1), a2 + hstep);
;         G_WAIT_L(8); G_BAR; G_WAIT_L(0); G_MMA(0, 0, At, B0); G_BAR; G_SCHED;
;         G_LDB(B1, 1, 1); G_STAGE(G_SB(1, 0), b3);
;         G_BAR; G_WAIT_L(0); G_MMA(0, 1, At, B1); G_BAR;
;         G_LDA(At, 1, 1); G_STAGE(G_SA(1, 0), a3);
;         G_BAR; G_WAIT_L(0); G_MMA(1, 0, At, B0); G_BAR; G_SCHED;
	s_add_u32 s16, s12, 0x40000
	s_addc_u32 s17, s13, 0
	s_add_i32 s34, s35, s58
	v_lshl_add_u64 v[140:141], s[16:17], 0, v[176:177]
	s_mov_b32 m0, s34
	s_nop 0
	global_load_lds_dwordx4 v[140:141], off
	v_lshl_add_u64 v[140:141], s[16:17], 0, v[128:129]
	s_add_i32 m0, s34, 0x2000
	s_nop 0
	global_load_lds_dwordx4 v[140:141], off
	v_add_u32_e32 v139, 0x18000, v137
	ds_read_b128 v[140:143], v139
	ds_read_b128 v[144:147], v139 offset:1024
	ds_read_b128 v[148:151], v139 offset:2048
	ds_read_b128 v[152:155], v139 offset:3072
	s_waitcnt vmcnt(10)
	s_barrier
	v_mfma_f32_16x16x32_bf16 v[120:123], v[218:221], v[156:159], v[120:123]
	v_mfma_f32_16x16x32_bf16 v[124:127], v[226:229], v[156:159], v[124:127]
	v_mfma_f32_16x16x32_bf16 v[112:115], v[218:221], v[164:167], v[112:115]
	v_mfma_f32_16x16x32_bf16 v[116:119], v[226:229], v[164:167], v[116:119]
	v_mfma_f32_16x16x32_bf16 v[104:107], v[218:221], v[172:175], v[104:107]
	v_mfma_f32_16x16x32_bf16 v[108:111], v[226:229], v[172:175], v[108:111]
	v_mfma_f32_16x16x32_bf16 v[96:99], v[218:221], v[186:189], v[96:99]
	v_mfma_f32_16x16x32_bf16 v[100:103], v[226:229], v[186:189], v[100:103]
	v_mfma_f32_16x16x32_bf16 v[120:123], v[222:225], v[160:163], v[120:123]
	v_mfma_f32_16x16x32_bf16 v[124:127], v[230:233], v[160:163], v[124:127]
	v_mfma_f32_16x16x32_bf16 v[112:115], v[222:225], v[168:171], v[112:115]
	v_mfma_f32_16x16x32_bf16 v[116:119], v[230:233], v[168:171], v[116:119]
	v_mfma_f32_16x16x32_bf16 v[104:107], v[222:225], v[182:185], v[104:107]
	v_mfma_f32_16x16x32_bf16 v[108:111], v[230:233], v[182:185], v[108:111]
	v_mfma_f32_16x16x32_bf16 v[96:99], v[222:225], v[214:217], v[96:99]
	v_mfma_f32_16x16x32_bf16 v[100:103], v[230:233], v[214:217], v[100:103]
	s_add_i32 s34, 0, 0x18000
	s_barrier
	s_add_u32 s16, s28, 0x40000
	s_addc_u32 s17, s29, 0
	s_mov_b32 m0, s25
	v_lshl_add_u64 v[218:219], s[16:17], 0, v[176:177]
	ds_read_b128 v[156:159], v138 offset:32768
	ds_read_b128 v[160:163], v138 offset:33792
	ds_read_b128 v[164:167], v138 offset:34816
	ds_read_b128 v[168:171], v138 offset:35840
	ds_read_b128 v[172:175], v138 offset:36864
	ds_read_b128 v[182:185], v138 offset:37888
	ds_read_b128 v[186:189], v138 offset:38912
	ds_read_b128 v[214:217], v138 offset:39936
	global_load_lds_dwordx4 v[218:219], off
	v_lshl_add_u64 v[218:219], s[16:17], 0, v[128:129]
	s_mov_b32 m0, s26
	s_nop 0
	global_load_lds_dwordx4 v[218:219], off
	s_waitcnt lgkmcnt(8)
	s_waitcnt vmcnt(10)
	s_barrier
	s_waitcnt lgkmcnt(0)
	s_waitcnt lgkmcnt(0)
	v_mfma_f32_16x16x32_bf16 v[20:23], v[140:143], v[156:159], v[20:23]
	v_mfma_f32_16x16x32_bf16 v[28:31], v[148:151], v[156:159], v[28:31]
	v_mfma_f32_16x16x32_bf16 v[12:15], v[140:143], v[164:167], v[12:15]
	v_mfma_f32_16x16x32_bf16 v[24:27], v[148:151], v[164:167], v[24:27]
	v_mfma_f32_16x16x32_bf16 v[4:7], v[140:143], v[172:175], v[4:7]
	v_mfma_f32_16x16x32_bf16 v[16:19], v[148:151], v[172:175], v[16:19]
	v_mfma_f32_16x16x32_bf16 v[0:3], v[140:143], v[186:189], v[0:3]
	v_mfma_f32_16x16x32_bf16 v[8:11], v[148:151], v[186:189], v[8:11]
	v_mfma_f32_16x16x32_bf16 v[20:23], v[144:147], v[160:163], v[20:23]
	v_mfma_f32_16x16x32_bf16 v[28:31], v[152:155], v[160:163], v[28:31]
	v_mfma_f32_16x16x32_bf16 v[12:15], v[144:147], v[168:171], v[12:15]
	v_mfma_f32_16x16x32_bf16 v[24:27], v[152:155], v[168:171], v[24:27]
	v_mfma_f32_16x16x32_bf16 v[4:7], v[144:147], v[182:185], v[4:7]
	v_mfma_f32_16x16x32_bf16 v[16:19], v[152:155], v[182:185], v[16:19]
	v_mfma_f32_16x16x32_bf16 v[0:3], v[144:147], v[214:217], v[0:3]
	v_mfma_f32_16x16x32_bf16 v[8:11], v[152:155], v[214:217], v[8:11]
	s_barrier
	s_add_i32 s16, 0, 0x1c000
	s_add_i32 s17, s34, s58
	v_add_u32_e32 v139, s16, v137
	v_lshl_add_u64 v[190:191], v[190:191], 0, s[64:65]
	s_mov_b32 m0, s17
	ds_read_b128 v[218:221], v139
	ds_read_b128 v[222:225], v139 offset:1024
	ds_read_b128 v[226:229], v139 offset:2048
	ds_read_b128 v[230:233], v139 offset:3072
	global_load_lds_dwordx4 v[190:191], off
	v_lshl_add_u64 v[190:191], v[234:235], 0, s[64:65]
	s_add_i32 m0, s17, 0x2000
	s_nop 0
	global_load_lds_dwordx4 v[190:191], off
	s_waitcnt vmcnt(10)
	s_barrier
	s_waitcnt lgkmcnt(0)
	s_waitcnt lgkmcnt(0)
	v_mfma_f32_16x16x32_bf16 v[80:83], v[218:221], v[156:159], v[80:83]
	v_mfma_f32_16x16x32_bf16 v[92:95], v[226:229], v[156:159], v[92:95]
	v_mfma_f32_16x16x32_bf16 v[64:67], v[218:221], v[164:167], v[64:67]
	v_mfma_f32_16x16x32_bf16 v[84:87], v[226:229], v[164:167], v[84:87]
	v_mfma_f32_16x16x32_bf16 v[52:55], v[218:221], v[172:175], v[52:55]
	v_mfma_f32_16x16x32_bf16 v[76:79], v[226:229], v[172:175], v[76:79]
	v_mfma_f32_16x16x32_bf16 v[40:43], v[218:221], v[186:189], v[40:43]
	v_mfma_f32_16x16x32_bf16 v[60:63], v[226:229], v[186:189], v[60:63]
	v_mfma_f32_16x16x32_bf16 v[80:83], v[222:225], v[160:163], v[80:83]
	v_mfma_f32_16x16x32_bf16 v[92:95], v[230:233], v[160:163], v[92:95]
	v_mfma_f32_16x16x32_bf16 v[64:67], v[222:225], v[168:171], v[64:67]
	v_mfma_f32_16x16x32_bf16 v[84:87], v[230:233], v[168:171], v[84:87]
	v_mfma_f32_16x16x32_bf16 v[52:55], v[222:225], v[182:185], v[52:55]
	v_mfma_f32_16x16x32_bf16 v[76:79], v[230:233], v[182:185], v[76:79]
	v_mfma_f32_16x16x32_bf16 v[40:43], v[222:225], v[214:217], v[40:43]
	v_mfma_f32_16x16x32_bf16 v[60:63], v[230:233], v[214:217], v[60:63]
	s_mov_b32 m0, s0
	v_lshl_add_u64 v[190:191], v[236:237], 0, s[64:65]
	s_barrier
	ds_read_b128 v[156:159], v138 offset:49152
	ds_read_b128 v[160:163], v138 offset:50176
	ds_read_b128 v[164:167], v138 offset:51200
	ds_read_b128 v[168:171], v138 offset:52224
	ds_read_b128 v[172:175], v138 offset:53248
	ds_read_b128 v[182:185], v138 offset:54272
	ds_read_b128 v[186:189], v138 offset:55296
	ds_read_b128 v[214:217], v138 offset:56320
	global_load_lds_dwordx4 v[190:191], off
	v_lshl_add_u64 v[190:191], v[238:239], 0, s[64:65]
	s_mov_b32 m0, s1
	s_nop 0
	global_load_lds_dwordx4 v[190:191], off
	s_waitcnt vmcnt(10)
	s_barrier
; __device__ __forceinline__ u32x4 mk4(unsigned a, unsigned b, unsigned c, unsigned d) { return (u32x4){a, b, c, d}; }
; #define G_STAGE(bufoff, gbase) do { _Pragma("unroll") for (int _i = 0; _i < 2; ++_i) \
;     __builtin_amdgcn_global_load_lds((const unsigned*)((const char*)(gbase) + voff[_i]), (GLAS unsigned*)(lds + (bufoff) + ldsw + _i * 8192), 16, 0, 0); } while (0)
; #define G_MMA(ai, bj, At_, Bt_) do { __builtin_amdgcn_s_setprio(1); \
;     _Pragma("unroll") for (int m = 0; m < 4; ++m) _Pragma("unroll") for (int n = 0; n < 2; ++n) _Pragma("unroll") for (int k = 0; k < 2; ++k) \
;       acc[ai][bj][m][n] = __builtin_amdgcn_mfma_f32_16x16x32_bf16(Bt_[n][k], At_[m][k], acc[ai][bj][m][n], 0, 0, 0); \
;     __builtin_amdgcn_s_setprio(0); } while (0)
; #define G_WAIT_V(n) asm volatile("s_waitcnt vmcnt(" #n ")" ::: "memory")
; #define G_WAIT_L(n) asm volatile("s_waitcnt lgkmcnt(" #n ")" ::: "memory")
; #define G_BAR __builtin_amdgcn_s_barrier()
; #define G_SCHED __builtin_amdgcn_sched_barrier(0)
; __device__ __forceinline__ void gemm_phase(const Params& p, int l, const bf16_t* __restrict__ A, const bf16_t* __restrict__ Bt, int M, int N, int K,
;                            int epi, bf16_t* __restrict__ outp, char* smem, int wvi) {
;     ...
;         G_BAR; G_WAIT_L(0); G_MMA(1, 0, At, B0); G_BAR; G_SCHED;
;         G_STAGE(G_SB(1, 1), b3 + hstep);
;         G_WAIT_V(6); G_BAR; G_MMA(1, 1, At, B1); G_BAR;
;     ...
;     if (epi == EPI_PLAIN) {
; #pragma unroll
;       for (int ai = 0; ai < 2; ++ai)
; #pragma unroll
;         for (int m = 0; m < 4; ++m) {
;           bf16_t* rp = outp + (size_t)(r0 + ai * GHALF + m * 16) * N + bcol + wc * 32 + fq * 8;
; #pragma unroll
;           for (int bj = 0; bj < 2; ++bj) {
;             const f32x4 v0 = acc[ai][bj][m][0], v1 = acc[ai][bj][m][1];
;             *reinterpret_cast<u32x4*>(rp + bj * GHALF) = mk4(pk2(v0[0], v0[1]), pk2(v0[2], v0[3]), pk2(v1[0], v1[1]), pk2(v1[2], v1[3]));
;           }
;         }
	s_waitcnt lgkmcnt(0)
	s_waitcnt lgkmcnt(0)
	v_mfma_f32_16x16x32_bf16 v[68:71], v[140:143], v[156:159], v[68:71]
	v_mfma_f32_16x16x32_bf16 v[88:91], v[148:151], v[156:159], v[88:91]
	v_mfma_f32_16x16x32_bf16 v[48:51], v[140:143], v[164:167], v[48:51]
	v_mfma_f32_16x16x32_bf16 v[72:75], v[148:151], v[164:167], v[72:75]
	v_mfma_f32_16x16x32_bf16 v[36:39], v[140:143], v[172:175], v[36:39]
	v_mfma_f32_16x16x32_bf16 v[56:59], v[148:151], v[172:175], v[56:59]
	v_mfma_f32_16x16x32_bf16 v[32:35], v[140:143], v[186:189], v[32:35]
	v_mfma_f32_16x16x32_bf16 v[44:47], v[148:151], v[186:189], v[44:47]
	v_mfma_f32_16x16x32_bf16 v[68:71], v[144:147], v[160:163], v[68:71]
	v_mfma_f32_16x16x32_bf16 v[88:91], v[152:155], v[160:163], v[88:91]
	v_mfma_f32_16x16x32_bf16 v[48:51], v[144:147], v[168:171], v[48:51]
	v_mfma_f32_16x16x32_bf16 v[72:75], v[152:155], v[168:171], v[72:75]
	v_mfma_f32_16x16x32_bf16 v[36:39], v[144:147], v[182:185], v[36:39]
	v_mfma_f32_16x16x32_bf16 v[56:59], v[152:155], v[182:185], v[56:59]
	v_mfma_f32_16x16x32_bf16 v[32:35], v[144:147], v[214:217], v[32:35]
	v_mfma_f32_16x16x32_bf16 v[44:47], v[152:155], v[214:217], v[44:47]
	s_barrier
	s_add_u32 s12, s12, 0x40080
	s_addc_u32 s13, s13, 0
	s_add_i32 s16, s16, s58
	v_lshl_add_u64 v[140:141], s[12:13], 0, v[176:177]
	s_mov_b32 m0, s16
	s_nop 0
	global_load_lds_dwordx4 v[140:141], off
	v_lshl_add_u64 v[140:141], s[12:13], 0, v[128:129]
	s_add_i32 m0, s16, 0x2000
	s_nop 0
	global_load_lds_dwordx4 v[140:141], off
	v_add_u32_e32 v139, 0x10000, v137
	ds_read_b128 v[140:143], v139
	ds_read_b128 v[144:147], v139 offset:1024
	ds_read_b128 v[148:151], v139 offset:2048
	ds_read_b128 v[152:155], v139 offset:3072
	s_waitcnt vmcnt(6)
	s_barrier
	v_mfma_f32_16x16x32_bf16 v[120:123], v[218:221], v[156:159], v[120:123]
	v_mfma_f32_16x16x32_bf16 v[124:127], v[226:229], v[156:159], v[124:127]
	v_mfma_f32_16x16x32_bf16 v[112:115], v[218:221], v[164:167], v[112:115]
	v_mfma_f32_16x16x32_bf16 v[116:119], v[226:229], v[164:167], v[116:119]
	v_mfma_f32_16x16x32_bf16 v[104:107], v[218:221], v[172:175], v[104:107]
	v_mfma_f32_16x16x32_bf16 v[108:111], v[226:229], v[172:175], v[108:111]
	v_mfma_f32_16x16x32_bf16 v[96:99], v[218:221], v[186:189], v[96:99]
	v_mfma_f32_16x16x32_bf16 v[100:103], v[226:229], v[186:189], v[100:103]
	v_mfma_f32_16x16x32_bf16 v[120:123], v[222:225], v[160:163], v[120:123]
	v_mfma_f32_16x16x32_bf16 v[124:127], v[230:233], v[160:163], v[124:127]
	v_mfma_f32_16x16x32_bf16 v[112:115], v[222:225], v[168:171], v[112:115]
	v_mfma_f32_16x16x32_bf16 v[116:119], v[230:233], v[168:171], v[116:119]
	v_mfma_f32_16x16x32_bf16 v[104:107], v[222:225], v[182:185], v[104:107]
	v_mfma_f32_16x16x32_bf16 v[108:111], v[230:233], v[182:185], v[108:111]
	v_mfma_f32_16x16x32_bf16 v[96:99], v[222:225], v[214:217], v[96:99]
	v_mfma_f32_16x16x32_bf16 v[100:103], v[230:233], v[214:217], v[100:103]
	s_add_i32 s55, s55, 2
	s_add_u32 s31, s31, 0x100
	s_addc_u32 s53, s53, 0
	s_cmp_gt_u32 s55, 13
	s_mov_b64 s[16:17], s[2:3]
	s_barrier
	s_cbranch_scc0 .LBB0_373
	s_lshl_b32 s2, s30, 8
	v_lshl_add_u32 v250, s8, 8, v136
	s_ashr_i32 s3, s2, 31
	v_ashrrev_i32_e32 v251, 31, v250
	v_lshl_add_u64 v[252:253], s[2:3], 1, v[130:131]
	v_lshlrev_b64 v[254:255], 11, v[250:251]
	v_lshl_add_u64 v[254:255], v[252:253], 0, v[254:255]
	v_cvt_pk_bf16_f32 v20, v20, v21
	v_cvt_pk_bf16_f32 v21, v22, v23
	v_cvt_pk_bf16_f32 v22, v28, v29
	v_cvt_pk_bf16_f32 v23, v30, v31
	global_store_dwordx4 v[254:255], v[20:23], off
	v_cvt_pk_bf16_f32 v12, v12, v13
	v_cvt_pk_bf16_f32 v13, v14, v15
	v_cvt_pk_bf16_f32 v20, v80, v81
	v_cvt_pk_bf16_f32 v21, v82, v83
	v_cvt_pk_bf16_f32 v22, v92, v93
	v_cvt_pk_bf16_f32 v23, v94, v95
	global_store_dwordx4 v[254:255], v[20:23], off offset:256
	v_cvt_pk_bf16_f32 v14, v24, v25
	v_cvt_pk_bf16_f32 v15, v26, v27
	v_or_b32_e32 v20, 16, v250
	v_ashrrev_i32_e32 v21, 31, v20
	v_lshlrev_b64 v[20:21], 11, v[20:21]
	v_lshl_add_u64 v[20:21], v[252:253], 0, v[20:21]
	global_store_dwordx4 v[20:21], v[12:15], off
	v_cvt_pk_bf16_f32 v4, v4, v5
	v_cvt_pk_bf16_f32 v5, v6, v7
	v_cvt_pk_bf16_f32 v12, v64, v65
	v_cvt_pk_bf16_f32 v13, v66, v67
	v_cvt_pk_bf16_f32 v14, v84, v85
	v_cvt_pk_bf16_f32 v15, v86, v87
	global_store_dwordx4 v[20:21], v[12:15], off offset:256
	v_cvt_pk_bf16_f32 v6, v16, v17
	v_cvt_pk_bf16_f32 v7, v18, v19
	v_or_b32_e32 v12, 32, v250
	v_ashrrev_i32_e32 v13, 31, v12
	v_lshlrev_b64 v[12:13], 11, v[12:13]
	v_lshl_add_u64 v[12:13], v[252:253], 0, v[12:13]
	global_store_dwordx4 v[12:13], v[4:7], off
	v_cvt_pk_bf16_f32 v0, v0, v1
	v_cvt_pk_bf16_f32 v1, v2, v3
	v_cvt_pk_bf16_f32 v4, v52, v53
	v_cvt_pk_bf16_f32 v5, v54, v55
	v_cvt_pk_bf16_f32 v6, v76, v77
	v_cvt_pk_bf16_f32 v7, v78, v79
	global_store_dwordx4 v[12:13], v[4:7], off offset:256
	v_cvt_pk_bf16_f32 v2, v8, v9
	v_cvt_pk_bf16_f32 v3, v10, v11
	v_or_b32_e32 v4, 48, v250
	v_ashrrev_i32_e32 v5, 31, v4
	v_lshlrev_b64 v[4:5], 11, v[4:5]
	v_lshl_add_u64 v[4:5], v[252:253], 0, v[4:5]
	global_store_dwordx4 v[4:5], v[0:3], off
	s_mov_b64 s[2:3], 0x40000
	s_movk_i32 s53, 0x440
	v_cvt_pk_bf16_f32 v0, v40, v41
	v_cvt_pk_bf16_f32 v1, v42, v43
	v_cvt_pk_bf16_f32 v2, v60, v61
	v_cvt_pk_bf16_f32 v3, v62, v63
	global_store_dwordx4 v[4:5], v[0:3], off offset:256
	v_lshl_add_u64 v[4:5], v[254:255], 0, s[2:3]
	s_mov_b32 s2, 0x40000
	v_add_co_u32_e32 v6, vcc, s2, v254
; __device__ __forceinline__ u32x4 mk4(unsigned a, unsigned b, unsigned c, unsigned d) { return (u32x4){a, b, c, d}; }
; __device__ __forceinline__ f32x4 zero4() { float z = 0.f; asm volatile("" : "+v"(z)); return (f32x4){z, z, z, z}; }
; __device__ __forceinline__ void gemm_phase(const Params& p, int l, const bf16_t* __restrict__ A, const bf16_t* __restrict__ Bt, int M, int N, int K,
;                            int epi, bf16_t* __restrict__ outp, char* smem, int wvi) {
;     ...
;     if (epi == EPI_PLAIN) {
; #pragma unroll
;       for (int ai = 0; ai < 2; ++ai)
; #pragma unroll
;         for (int m = 0; m < 4; ++m) {
;           bf16_t* rp = outp + (size_t)(r0 + ai * GHALF + m * 16) * N + bcol + wc * 32 + fq * 8;
; #pragma unroll
;           for (int bj = 0; bj < 2; ++bj) {
;             const f32x4 v0 = acc[ai][bj][m][0], v1 = acc[ai][bj][m][1];
;             *reinterpret_cast<u32x4*>(rp + bj * GHALF) = mk4(pk2(v0[0], v0[1]), pk2(v0[2], v0[3]), pk2(v1[0], v1[1]), pk2(v1[2], v1[3]));
;           }
;         }
;     ...
;       if (!has_next) break;
; #pragma unroll
;       for (int a = 0; a < 2; ++a)
; #pragma unroll
;         for (int b = 0; b < 2; ++b)
; #pragma unroll
;           for (int m = 0; m < 4; ++m)
; #pragma unroll
;             for (int n = 0; n < 2; ++n) acc[a][b][m][n] = zero4();
;       Lw = Ln; pm = npm; pn = npn; cA = nA; cB = nB;
	v_cvt_pk_bf16_f32 v0, v68, v69
	v_cvt_pk_bf16_f32 v1, v70, v71
	v_cvt_pk_bf16_f32 v2, v88, v89
	v_cvt_pk_bf16_f32 v3, v90, v91
	v_addc_co_u32_e32 v7, vcc, 0, v255, vcc
	global_store_dwordx4 v[6:7], v[0:3], off
	s_mov_b64 s[2:3], 0x48000
	v_readlane_b32 s55, v244, 31
	v_cvt_pk_bf16_f32 v0, v120, v121
	v_cvt_pk_bf16_f32 v1, v122, v123
	v_cvt_pk_bf16_f32 v2, v124, v125
	v_cvt_pk_bf16_f32 v3, v126, v127
	global_store_dwordx4 v[4:5], v[0:3], off offset:256
	v_lshl_add_u64 v[4:5], v[254:255], 0, s[2:3]
	s_mov_b32 s2, 0x48000
	v_add_co_u32_e32 v6, vcc, s2, v254
	v_cvt_pk_bf16_f32 v0, v48, v49
	v_cvt_pk_bf16_f32 v1, v50, v51
	v_cvt_pk_bf16_f32 v2, v72, v73
	v_cvt_pk_bf16_f32 v3, v74, v75
	v_addc_co_u32_e32 v7, vcc, 0, v255, vcc
	global_store_dwordx4 v[6:7], v[0:3], off
	s_mov_b64 s[2:3], 0x50000
	s_nop 0
	v_cvt_pk_bf16_f32 v0, v112, v113
	v_cvt_pk_bf16_f32 v1, v114, v115
	v_cvt_pk_bf16_f32 v2, v116, v117
	v_cvt_pk_bf16_f32 v3, v118, v119
	global_store_dwordx4 v[4:5], v[0:3], off offset:256
	v_lshl_add_u64 v[4:5], v[254:255], 0, s[2:3]
	s_mov_b32 s2, 0x50000
	v_add_co_u32_e32 v6, vcc, s2, v254
	v_cvt_pk_bf16_f32 v0, v36, v37
	v_cvt_pk_bf16_f32 v1, v38, v39
	v_cvt_pk_bf16_f32 v2, v56, v57
	v_cvt_pk_bf16_f32 v3, v58, v59
	v_addc_co_u32_e32 v7, vcc, 0, v255, vcc
	global_store_dwordx4 v[6:7], v[0:3], off
	s_mov_b64 s[2:3], 0x58000
	s_nop 0
	v_cvt_pk_bf16_f32 v0, v104, v105
	v_cvt_pk_bf16_f32 v1, v106, v107
	v_cvt_pk_bf16_f32 v2, v108, v109
	v_cvt_pk_bf16_f32 v3, v110, v111
	global_store_dwordx4 v[4:5], v[0:3], off offset:256
	v_lshl_add_u64 v[4:5], v[254:255], 0, s[2:3]
	s_mov_b32 s2, 0x58000
	v_add_co_u32_e32 v6, vcc, s2, v254
	v_cvt_pk_bf16_f32 v0, v32, v33
	v_cvt_pk_bf16_f32 v1, v34, v35
	v_cvt_pk_bf16_f32 v2, v44, v45
	v_cvt_pk_bf16_f32 v3, v46, v47
	v_addc_co_u32_e32 v7, vcc, 0, v255, vcc
	global_store_dwordx4 v[6:7], v[0:3], off
	s_mov_b64 s[2:3], -1
	s_and_b64 vcc, exec, s[14:15]
	v_cvt_pk_bf16_f32 v0, v96, v97
	v_cvt_pk_bf16_f32 v1, v98, v99
	v_cvt_pk_bf16_f32 v2, v100, v101
	v_cvt_pk_bf16_f32 v3, v102, v103
	global_store_dwordx4 v[4:5], v[0:3], off offset:256
	s_cbranch_vccz .LBB0_369
	v_mov_b32_e32 v20, v177
	v_mov_b32_e32 v28, v177
	v_mov_b32_e32 v12, v177
	v_mov_b32_e32 v24, v177
	v_mov_b32_e32 v4, v177
	v_mov_b32_e32 v16, v177
	v_mov_b32_e32 v0, v177
	v_mov_b32_e32 v8, v177
	v_mov_b32_e32 v80, v177
	v_mov_b32_e32 v92, v177
	v_mov_b32_e32 v64, v177
	v_mov_b32_e32 v84, v177
	v_mov_b32_e32 v52, v177
	v_mov_b32_e32 v76, v177
	v_mov_b32_e32 v40, v177
	v_mov_b32_e32 v60, v177
	v_mov_b32_e32 v68, v177
	v_mov_b32_e32 v88, v177
	v_mov_b32_e32 v48, v177
	v_mov_b32_e32 v72, v177
	v_mov_b32_e32 v36, v177
	v_mov_b32_e32 v56, v177
	v_mov_b32_e32 v32, v177
	v_mov_b32_e32 v44, v177
	v_mov_b32_e32 v120, v177
	v_mov_b32_e32 v124, v177
	v_mov_b32_e32 v112, v177
	v_mov_b32_e32 v116, v177
	v_mov_b32_e32 v104, v177
	v_mov_b32_e32 v108, v177
	v_mov_b32_e32 v96, v177
	v_mov_b32_e32 v100, v177
	s_nop 0
	v_mov_b32_e32 v21, v20
	v_mov_b32_e32 v22, v20
	v_mov_b32_e32 v23, v20
	v_mov_b32_e32 v29, v28
	v_mov_b32_e32 v30, v28
	v_mov_b32_e32 v31, v28
	v_mov_b32_e32 v13, v12
	v_mov_b32_e32 v14, v12
	v_mov_b32_e32 v15, v12
	v_mov_b32_e32 v25, v24
	v_mov_b32_e32 v26, v24
	v_mov_b32_e32 v27, v24
	v_mov_b32_e32 v5, v4
	v_mov_b32_e32 v6, v4
	v_mov_b32_e32 v7, v4
	v_mov_b32_e32 v17, v16
	v_mov_b32_e32 v18, v16
	v_mov_b32_e32 v19, v16
	s_nop 0
	v_mov_b32_e32 v1, v0
	v_mov_b32_e32 v2, v0
	v_mov_b32_e32 v3, v0
	v_mov_b32_e32 v9, v8
	v_mov_b32_e32 v10, v8
	v_mov_b32_e32 v11, v8
	v_mov_b32_e32 v81, v80
	v_mov_b32_e32 v82, v80
	v_mov_b32_e32 v83, v80
	v_mov_b32_e32 v93, v92
	v_mov_b32_e32 v94, v92
	v_mov_b32_e32 v95, v92
	v_mov_b32_e32 v65, v64
	v_mov_b32_e32 v66, v64
	v_mov_b32_e32 v67, v64
	v_mov_b32_e32 v85, v84
	v_mov_b32_e32 v86, v84
	v_mov_b32_e32 v87, v84
	s_nop 0
	v_mov_b32_e32 v53, v52
	v_mov_b32_e32 v54, v52
	v_mov_b32_e32 v55, v52
	v_mov_b32_e32 v77, v76
	v_mov_b32_e32 v78, v76
	v_mov_b32_e32 v79, v76
	v_mov_b32_e32 v41, v40
	v_mov_b32_e32 v42, v40
	v_mov_b32_e32 v43, v40
	v_mov_b32_e32 v61, v60
	v_mov_b32_e32 v62, v60
	v_mov_b32_e32 v63, v60
	v_mov_b32_e32 v69, v68
	v_mov_b32_e32 v70, v68
	v_mov_b32_e32 v71, v68
	v_mov_b32_e32 v89, v88
	v_mov_b32_e32 v90, v88
	v_mov_b32_e32 v91, v88
	s_nop 0
	v_mov_b32_e32 v49, v48
	v_mov_b32_e32 v50, v48
	v_mov_b32_e32 v51, v48
	v_mov_b32_e32 v73, v72
	v_mov_b32_e32 v74, v72
	v_mov_b32_e32 v75, v72
	v_mov_b32_e32 v37, v36
	v_mov_b32_e32 v38, v36
	v_mov_b32_e32 v39, v36
	v_mov_b32_e32 v57, v56
	v_mov_b32_e32 v58, v56
	v_mov_b32_e32 v59, v56
	v_mov_b32_e32 v33, v32
	v_mov_b32_e32 v34, v32
	v_mov_b32_e32 v35, v32
	v_mov_b32_e32 v45, v44
	v_mov_b32_e32 v46, v44
	v_mov_b32_e32 v47, v44
	s_nop 0
	v_mov_b32_e32 v121, v120
	v_mov_b32_e32 v122, v120
	v_mov_b32_e32 v123, v120
	v_mov_b32_e32 v125, v124
	v_mov_b32_e32 v126, v124
	v_mov_b32_e32 v127, v124
	v_mov_b32_e32 v113, v112
	v_mov_b32_e32 v114, v112
	v_mov_b32_e32 v115, v112
	v_mov_b32_e32 v117, v116
	v_mov_b32_e32 v118, v116
	v_mov_b32_e32 v119, v116
	v_mov_b32_e32 v105, v104
	v_mov_b32_e32 v106, v104
	v_mov_b32_e32 v107, v104
	v_mov_b32_e32 v109, v108
	v_mov_b32_e32 v110, v108
	v_mov_b32_e32 v111, v108
	s_mov_b64 s[2:3], 0
	v_mov_b32_e32 v97, v96
	v_mov_b32_e32 v98, v96
	v_mov_b32_e32 v99, v96
	v_mov_b32_e32 v101, v100
	v_mov_b32_e32 v102, v100
	v_mov_b32_e32 v103, v100
	s_branch .LBB0_369

; #define G_STAGE(bufoff, gbase) do { _Pragma("unroll") for (int _i = 0; _i < 2; ++_i) \
;     __builtin_amdgcn_global_load_lds((const unsigned*)((const char*)(gbase) + voff[_i]), (GLAS unsigned*)(lds + (bufoff) + ldsw + _i * 8192), 16, 0, 0); } while (0)
; #define G_LDA(dst, b, h) do { _Pragma("unroll") for (int m = 0; m < 4; ++m) _Pragma("unroll") for (int k = 0; k < 2; ++k) \
;     dst[m][k] = *(const GLAS bf16x8*)(lds + G_SA(b, h) + aoff + m * 2048 + k * 1024); } while (0)
; #define G_LDB(dst, b, h) do { _Pragma("unroll") for (int n = 0; n < 2; ++n) _Pragma("unroll") for (int k = 0; k < 2; ++k) \
;     dst[n][k] = *(const GLAS bf16x8*)(lds + G_SB(b, h) + boff + n * 2048 + k * 1024); } while (0)
; #define G_MMA(ai, bj, At_, Bt_) do { __builtin_amdgcn_s_setprio(1); \
;     _Pragma("unroll") for (int m = 0; m < 4; ++m) _Pragma("unroll") for (int n = 0; n < 2; ++n) _Pragma("unroll") for (int k = 0; k < 2; ++k) \
;       acc[ai][bj][m][n] = __builtin_amdgcn_mfma_f32_16x16x32_bf16(Bt_[n][k], At_[m][k], acc[ai][bj][m][n], 0, 0, 0); \
;     __builtin_amdgcn_s_setprio(0); } while (0)
; #define G_WAIT_L(n) asm volatile("s_waitcnt lgkmcnt(" #n ")" ::: "memory")
; #define G_BAR __builtin_amdgcn_s_barrier()
; #define G_SCHED __builtin_amdgcn_sched_barrier(0)
; __device__ __forceinline__ void gemm_phase(const Params& p, int l, const bf16_t* __restrict__ A, const bf16_t* __restrict__ Bt, int M, int N, int K,
;                            int epi, bf16_t* __restrict__ outp, char* smem, int wvi) {
;     ...
;       for (int t = 0; t < nt; t += 2) {
;         const bool lastt = (t == nt - 2);
;         const char* a1 = cA + (size_t)(t + 1) * kstep;
;         const char* a2 = lastt ? nA : cA + (size_t)(t + 2) * kstep; const char* b2 = lastt ? nB : cB + (size_t)(t + 2) * kstep;
;         const char* a3 = a2 + kstep; const char* b3 = b2 + kstep;
;         G_LDB(B0, 0, 0); G_SCHED; G_LDA(At, 0, 0); G_STAGE(G_SA(1, 1), a1 + hstep);
;         G_WAIT_L(8); G_BAR; G_WAIT_L(0); G_MMA(0, 0, At, B0); G_BAR; G_SCHED;
;         G_LDB(B1, 0, 1); G_STAGE(G_SB(0, 0), b2);
;         G_BAR; G_WAIT_L(0); G_MMA(0, 1, At, B1); G_BAR;
;         G_LDA(At, 0, 1); G_STAGE(G_SA(0, 0), a2);
;         G_BAR; G_WAIT_L(0); G_MMA(1, 0, At, B0); G_BAR; G_SCHED;
.LBB0_568:
	s_add_u32 s2, s6, 0x100
	s_addc_u32 s3, s7, 0
	s_add_i32 s21, 0, 0x10000
	v_add_u32_e32 v140, s21, v159
	ds_read_b128 v[128:131], v140
	ds_read_b128 v[132:135], v140 offset:1024
	ds_read_b128 v[136:139], v140 offset:2048
	ds_read_b128 v[140:143], v140 offset:3072
	s_cmp_eq_u32 s20, 12
	s_cselect_b32 s29, s13, s3
	s_cselect_b32 s28, s12, s2
	s_cselect_b32 s5, s9, s17
	s_cselect_b32 s4, s1, s11
	v_lshl_add_u64 v[156:157], s[6:7], 0, v[152:153]
	s_add_i32 m0, s30, 0xc000
	ds_read_b128 v[162:165], v160
	ds_read_b128 v[166:169], v160 offset:1024
	ds_read_b128 v[170:173], v160 offset:2048
	ds_read_b128 v[182:185], v160 offset:3072
	ds_read_b128 v[186:189], v160 offset:4096
	ds_read_b128 v[214:217], v160 offset:5120
	ds_read_b128 v[218:221], v160 offset:6144
	ds_read_b128 v[222:225], v160 offset:7168
	global_load_lds_dwordx4 v[156:157], off
	v_lshl_add_u64 v[156:157], s[6:7], 0, v[154:155]
	s_add_i32 m0, s30, 0xe000
	s_nop 0
	global_load_lds_dwordx4 v[156:157], off
	s_waitcnt lgkmcnt(8)
	s_barrier
	s_waitcnt lgkmcnt(0)
	s_waitcnt lgkmcnt(0)
	v_mfma_f32_16x16x32_bf16 v[20:23], v[128:131], v[162:165], v[20:23]
	v_mfma_f32_16x16x32_bf16 v[28:31], v[136:139], v[162:165], v[28:31]
	v_mfma_f32_16x16x32_bf16 v[12:15], v[128:131], v[170:173], v[12:15]
	v_mfma_f32_16x16x32_bf16 v[24:27], v[136:139], v[170:173], v[24:27]
	v_mfma_f32_16x16x32_bf16 v[4:7], v[128:131], v[186:189], v[4:7]
	v_mfma_f32_16x16x32_bf16 v[16:19], v[136:139], v[186:189], v[16:19]
	v_mfma_f32_16x16x32_bf16 v[0:3], v[128:131], v[218:221], v[0:3]
	v_mfma_f32_16x16x32_bf16 v[8:11], v[136:139], v[218:221], v[8:11]
	v_mfma_f32_16x16x32_bf16 v[20:23], v[132:135], v[166:169], v[20:23]
	v_mfma_f32_16x16x32_bf16 v[28:31], v[140:143], v[166:169], v[28:31]
	v_mfma_f32_16x16x32_bf16 v[12:15], v[132:135], v[182:185], v[12:15]
	v_mfma_f32_16x16x32_bf16 v[24:27], v[140:143], v[182:185], v[24:27]
	v_mfma_f32_16x16x32_bf16 v[4:7], v[132:135], v[214:217], v[4:7]
	v_mfma_f32_16x16x32_bf16 v[16:19], v[140:143], v[214:217], v[16:19]
	v_mfma_f32_16x16x32_bf16 v[0:3], v[132:135], v[222:225], v[0:3]
	v_mfma_f32_16x16x32_bf16 v[8:11], v[140:143], v[222:225], v[8:11]
	s_barrier
	s_add_i32 s22, 0, 0x14000
	v_add_u32_e32 v156, s22, v159
	s_add_i32 s6, s21, s58
	ds_read_b128 v[226:229], v156
	ds_read_b128 v[230:233], v156 offset:1024
	ds_read_b128 v[234:237], v156 offset:2048
	ds_read_b128 v[238:241], v156 offset:3072
	v_lshl_add_u64 v[156:157], s[4:5], 0, v[146:147]
	s_mov_b32 m0, s6
	v_lshl_add_u64 v[174:175], s[4:5], 0, v[144:145]
	global_load_lds_dwordx4 v[156:157], off
	s_add_i32 m0, s6, 0x2000
	s_nop 0
	global_load_lds_dwordx4 v[174:175], off
	s_barrier
	s_waitcnt lgkmcnt(0)
	s_waitcnt lgkmcnt(0)
	v_mfma_f32_16x16x32_bf16 v[84:87], v[226:229], v[162:165], v[84:87]
	v_mfma_f32_16x16x32_bf16 v[100:103], v[234:237], v[162:165], v[100:103]
	v_mfma_f32_16x16x32_bf16 v[76:79], v[226:229], v[170:173], v[76:79]
	v_mfma_f32_16x16x32_bf16 v[92:95], v[234:237], v[170:173], v[92:95]
	v_mfma_f32_16x16x32_bf16 v[64:67], v[226:229], v[186:189], v[64:67]
	v_mfma_f32_16x16x32_bf16 v[80:83], v[234:237], v[186:189], v[80:83]
	v_mfma_f32_16x16x32_bf16 v[52:55], v[226:229], v[218:221], v[52:55]
	v_mfma_f32_16x16x32_bf16 v[68:71], v[234:237], v[218:221], v[68:71]
	v_mfma_f32_16x16x32_bf16 v[84:87], v[230:233], v[166:169], v[84:87]
	v_mfma_f32_16x16x32_bf16 v[100:103], v[238:241], v[166:169], v[100:103]
	v_mfma_f32_16x16x32_bf16 v[76:79], v[230:233], v[182:185], v[76:79]
	v_mfma_f32_16x16x32_bf16 v[92:95], v[238:241], v[182:185], v[92:95]
	v_mfma_f32_16x16x32_bf16 v[64:67], v[230:233], v[214:217], v[64:67]
	v_mfma_f32_16x16x32_bf16 v[80:83], v[238:241], v[214:217], v[80:83]
	v_mfma_f32_16x16x32_bf16 v[52:55], v[230:233], v[222:225], v[52:55]
	v_mfma_f32_16x16x32_bf16 v[68:71], v[238:241], v[222:225], v[68:71]
	s_mov_b32 m0, s30
	v_lshl_add_u64 v[190:191], s[28:29], 0, v[146:147]
	s_barrier
	ds_read_b128 v[162:165], v160 offset:16384
	ds_read_b128 v[166:169], v160 offset:17408
	ds_read_b128 v[170:173], v160 offset:18432
	ds_read_b128 v[182:185], v160 offset:19456
	ds_read_b128 v[186:189], v160 offset:20480
	ds_read_b128 v[214:217], v160 offset:21504
	ds_read_b128 v[218:221], v160 offset:22528
	ds_read_b128 v[222:225], v160 offset:23552
	global_load_lds_dwordx4 v[190:191], off
	v_lshl_add_u64 v[242:243], s[28:29], 0, v[144:145]
	s_mov_b32 m0, s31
	s_nop 0
	global_load_lds_dwordx4 v[242:243], off
	s_waitcnt vmcnt(10)
	s_barrier
	s_waitcnt lgkmcnt(0)
	s_waitcnt lgkmcnt(0)
	v_mfma_f32_16x16x32_bf16 v[56:59], v[128:131], v[162:165], v[56:59]
	v_mfma_f32_16x16x32_bf16 v[72:75], v[136:139], v[162:165], v[72:75]
	v_mfma_f32_16x16x32_bf16 v[44:47], v[128:131], v[170:173], v[44:47]
	v_mfma_f32_16x16x32_bf16 v[60:63], v[136:139], v[170:173], v[60:63]
	v_mfma_f32_16x16x32_bf16 v[36:39], v[128:131], v[186:189], v[36:39]
	v_mfma_f32_16x16x32_bf16 v[48:51], v[136:139], v[186:189], v[48:51]
	v_mfma_f32_16x16x32_bf16 v[32:35], v[128:131], v[218:221], v[32:35]
	v_mfma_f32_16x16x32_bf16 v[40:43], v[136:139], v[218:221], v[40:43]
	v_mfma_f32_16x16x32_bf16 v[56:59], v[132:135], v[166:169], v[56:59]
	v_mfma_f32_16x16x32_bf16 v[72:75], v[140:143], v[166:169], v[72:75]
	v_mfma_f32_16x16x32_bf16 v[44:47], v[132:135], v[182:185], v[44:47]
	v_mfma_f32_16x16x32_bf16 v[60:63], v[140:143], v[182:185], v[60:63]
	v_mfma_f32_16x16x32_bf16 v[36:39], v[132:135], v[214:217], v[36:39]
	v_mfma_f32_16x16x32_bf16 v[48:51], v[140:143], v[214:217], v[48:51]
	v_mfma_f32_16x16x32_bf16 v[32:35], v[132:135], v[222:225], v[32:35]
	v_mfma_f32_16x16x32_bf16 v[40:43], v[140:143], v[222:225], v[40:43]
	s_barrier
; #define G_STAGE(bufoff, gbase) do { _Pragma("unroll") for (int _i = 0; _i < 2; ++_i) \
;     __builtin_amdgcn_global_load_lds((const unsigned*)((const char*)(gbase) + voff[_i]), (GLAS unsigned*)(lds + (bufoff) + ldsw + _i * 8192), 16, 0, 0); } while (0)
; #define G_LDA(dst, b, h) do { _Pragma("unroll") for (int m = 0; m < 4; ++m) _Pragma("unroll") for (int k = 0; k < 2; ++k) \
;     dst[m][k] = *(const GLAS bf16x8*)(lds + G_SA(b, h) + aoff + m * 2048 + k * 1024); } while (0)
; #define G_LDB(dst, b, h) do { _Pragma("unroll") for (int n = 0; n < 2; ++n) _Pragma("unroll") for (int k = 0; k < 2; ++k) \
;     dst[n][k] = *(const GLAS bf16x8*)(lds + G_SB(b, h) + boff + n * 2048 + k * 1024); } while (0)
; #define G_MMA(ai, bj, At_, Bt_) do { __builtin_amdgcn_s_setprio(1); \
;     _Pragma("unroll") for (int m = 0; m < 4; ++m) _Pragma("unroll") for (int n = 0; n < 2; ++n) _Pragma("unroll") for (int k = 0; k < 2; ++k) \
;       acc[ai][bj][m][n] = __builtin_amdgcn_mfma_f32_16x16x32_bf16(Bt_[n][k], At_[m][k], acc[ai][bj][m][n], 0, 0, 0); \
;     __builtin_amdgcn_s_setprio(0); } while (0)
; #define G_WAIT_V(n) asm volatile("s_waitcnt vmcnt(" #n ")" ::: "memory")
; #define G_WAIT_L(n) asm volatile("s_waitcnt lgkmcnt(" #n ")" ::: "memory")
; #define G_BAR __builtin_amdgcn_s_barrier()
; #define G_SCHED __builtin_amdgcn_sched_barrier(0)
; __device__ __forceinline__ void gemm_phase(const Params& p, int l, const bf16_t* __restrict__ A, const bf16_t* __restrict__ Bt, int M, int N, int K,
;                            int epi, bf16_t* __restrict__ outp, char* smem, int wvi) {
;     ...
;         G_STAGE(G_SB(0, 1), b2 + hstep);
;         G_WAIT_V(6); G_BAR; G_MMA(1, 1, At, B1); G_BAR;
;         G_LDB(B0, 1, 0); G_SCHED; G_LDA(At, 1, 0); G_STAGE(G_SA(0, 1), a2 + hstep);
;         G_WAIT_L(8); G_BAR; G_WAIT_L(0); G_MMA(0, 0, At, B0); G_BAR; G_SCHED;
;         G_LDB(B1, 1, 1); G_STAGE(G_SB(1, 0), b3);
;         G_BAR; G_WAIT_L(0); G_MMA(0, 1, At, B1); G_BAR;
	s_add_u32 s6, s4, 0x40000
	s_addc_u32 s7, s5, 0
	s_add_i32 s21, s22, s58
	v_lshl_add_u64 v[128:129], s[6:7], 0, v[146:147]
	s_mov_b32 m0, s21
	s_nop 0
	global_load_lds_dwordx4 v[128:129], off
	v_lshl_add_u64 v[128:129], s[6:7], 0, v[144:145]
	s_add_i32 m0, s21, 0x2000
	s_nop 0
	global_load_lds_dwordx4 v[128:129], off
	v_add_u32_e32 v140, 0x18000, v159
	ds_read_b128 v[128:131], v140
	ds_read_b128 v[132:135], v140 offset:1024
	ds_read_b128 v[136:139], v140 offset:2048
	ds_read_b128 v[140:143], v140 offset:3072
	s_waitcnt vmcnt(10)
	s_barrier
	v_mfma_f32_16x16x32_bf16 v[120:123], v[226:229], v[162:165], v[120:123]
	v_mfma_f32_16x16x32_bf16 v[124:127], v[234:237], v[162:165], v[124:127]
	v_mfma_f32_16x16x32_bf16 v[112:115], v[226:229], v[170:173], v[112:115]
	v_mfma_f32_16x16x32_bf16 v[116:119], v[234:237], v[170:173], v[116:119]
	v_mfma_f32_16x16x32_bf16 v[104:107], v[226:229], v[186:189], v[104:107]
	v_mfma_f32_16x16x32_bf16 v[108:111], v[234:237], v[186:189], v[108:111]
	v_mfma_f32_16x16x32_bf16 v[88:91], v[226:229], v[218:221], v[88:91]
	v_mfma_f32_16x16x32_bf16 v[96:99], v[234:237], v[218:221], v[96:99]
	v_mfma_f32_16x16x32_bf16 v[120:123], v[230:233], v[166:169], v[120:123]
	v_mfma_f32_16x16x32_bf16 v[124:127], v[238:241], v[166:169], v[124:127]
	v_mfma_f32_16x16x32_bf16 v[112:115], v[230:233], v[182:185], v[112:115]
	v_mfma_f32_16x16x32_bf16 v[116:119], v[238:241], v[182:185], v[116:119]
	v_mfma_f32_16x16x32_bf16 v[104:107], v[230:233], v[214:217], v[104:107]
	v_mfma_f32_16x16x32_bf16 v[108:111], v[238:241], v[214:217], v[108:111]
	v_mfma_f32_16x16x32_bf16 v[88:91], v[230:233], v[222:225], v[88:91]
	v_mfma_f32_16x16x32_bf16 v[96:99], v[238:241], v[222:225], v[96:99]
	s_add_i32 s21, 0, 0x18000
	s_barrier
	s_add_u32 s6, s28, 0x40000
	s_addc_u32 s7, s29, 0
	s_mov_b32 m0, s88
	v_lshl_add_u64 v[226:227], s[6:7], 0, v[146:147]
	ds_read_b128 v[162:165], v160 offset:32768
	ds_read_b128 v[166:169], v160 offset:33792
	ds_read_b128 v[170:173], v160 offset:34816
	ds_read_b128 v[182:185], v160 offset:35840
	ds_read_b128 v[186:189], v160 offset:36864
	ds_read_b128 v[214:217], v160 offset:37888
	ds_read_b128 v[218:221], v160 offset:38912
	ds_read_b128 v[222:225], v160 offset:39936
	global_load_lds_dwordx4 v[226:227], off
	v_lshl_add_u64 v[226:227], s[6:7], 0, v[144:145]
	s_mov_b32 m0, s89
	s_nop 0
	global_load_lds_dwordx4 v[226:227], off
	s_waitcnt lgkmcnt(8)
	s_waitcnt vmcnt(10)
	s_barrier
	s_waitcnt lgkmcnt(0)
	s_waitcnt lgkmcnt(0)
	v_mfma_f32_16x16x32_bf16 v[20:23], v[128:131], v[162:165], v[20:23]
	v_mfma_f32_16x16x32_bf16 v[28:31], v[136:139], v[162:165], v[28:31]
	v_mfma_f32_16x16x32_bf16 v[12:15], v[128:131], v[170:173], v[12:15]
	v_mfma_f32_16x16x32_bf16 v[24:27], v[136:139], v[170:173], v[24:27]
	v_mfma_f32_16x16x32_bf16 v[4:7], v[128:131], v[186:189], v[4:7]
	v_mfma_f32_16x16x32_bf16 v[16:19], v[136:139], v[186:189], v[16:19]
	v_mfma_f32_16x16x32_bf16 v[0:3], v[128:131], v[218:221], v[0:3]
	v_mfma_f32_16x16x32_bf16 v[8:11], v[136:139], v[218:221], v[8:11]
	v_mfma_f32_16x16x32_bf16 v[20:23], v[132:135], v[166:169], v[20:23]
	v_mfma_f32_16x16x32_bf16 v[28:31], v[140:143], v[166:169], v[28:31]
	v_mfma_f32_16x16x32_bf16 v[12:15], v[132:135], v[182:185], v[12:15]
	v_mfma_f32_16x16x32_bf16 v[24:27], v[140:143], v[182:185], v[24:27]
	v_mfma_f32_16x16x32_bf16 v[4:7], v[132:135], v[214:217], v[4:7]
	v_mfma_f32_16x16x32_bf16 v[16:19], v[140:143], v[214:217], v[16:19]
	v_mfma_f32_16x16x32_bf16 v[0:3], v[132:135], v[222:225], v[0:3]
	v_mfma_f32_16x16x32_bf16 v[8:11], v[140:143], v[222:225], v[8:11]
	s_barrier
	s_add_i32 s6, 0, 0x1c000
	s_add_i32 s7, s21, s58
	v_add_u32_e32 v161, s6, v159
	v_lshl_add_u64 v[156:157], v[156:157], 0, s[64:65]
	s_mov_b32 m0, s7
	ds_read_b128 v[226:229], v161
	ds_read_b128 v[230:233], v161 offset:1024
	ds_read_b128 v[234:237], v161 offset:2048
	ds_read_b128 v[238:241], v161 offset:3072
	global_load_lds_dwordx4 v[156:157], off
	v_lshl_add_u64 v[156:157], v[174:175], 0, s[64:65]
	s_add_i32 m0, s7, 0x2000
	s_nop 0
	global_load_lds_dwordx4 v[156:157], off
	s_waitcnt vmcnt(10)
	s_barrier
	s_waitcnt lgkmcnt(0)
	s_waitcnt lgkmcnt(0)
	v_mfma_f32_16x16x32_bf16 v[84:87], v[226:229], v[162:165], v[84:87]
	v_mfma_f32_16x16x32_bf16 v[100:103], v[234:237], v[162:165], v[100:103]
	v_mfma_f32_16x16x32_bf16 v[76:79], v[226:229], v[170:173], v[76:79]
	v_mfma_f32_16x16x32_bf16 v[92:95], v[234:237], v[170:173], v[92:95]
	v_mfma_f32_16x16x32_bf16 v[64:67], v[226:229], v[186:189], v[64:67]
	v_mfma_f32_16x16x32_bf16 v[80:83], v[234:237], v[186:189], v[80:83]
	v_mfma_f32_16x16x32_bf16 v[52:55], v[226:229], v[218:221], v[52:55]
	v_mfma_f32_16x16x32_bf16 v[68:71], v[234:237], v[218:221], v[68:71]
	v_mfma_f32_16x16x32_bf16 v[84:87], v[230:233], v[166:169], v[84:87]
	v_mfma_f32_16x16x32_bf16 v[100:103], v[238:241], v[166:169], v[100:103]
	v_mfma_f32_16x16x32_bf16 v[76:79], v[230:233], v[182:185], v[76:79]
	v_mfma_f32_16x16x32_bf16 v[92:95], v[238:241], v[182:185], v[92:95]
	v_mfma_f32_16x16x32_bf16 v[64:67], v[230:233], v[214:217], v[64:67]
	v_mfma_f32_16x16x32_bf16 v[80:83], v[238:241], v[214:217], v[80:83]
	v_mfma_f32_16x16x32_bf16 v[52:55], v[230:233], v[222:225], v[52:55]
	v_mfma_f32_16x16x32_bf16 v[68:71], v[238:241], v[222:225], v[68:71]
	s_mov_b32 m0, s92
	v_lshl_add_u64 v[156:157], v[190:191], 0, s[64:65]
	s_barrier
; #define G_STAGE(bufoff, gbase) do { _Pragma("unroll") for (int _i = 0; _i < 2; ++_i) \
;     __builtin_amdgcn_global_load_lds((const unsigned*)((const char*)(gbase) + voff[_i]), (GLAS unsigned*)(lds + (bufoff) + ldsw + _i * 8192), 16, 0, 0); } while (0)
; #define G_LDA(dst, b, h) do { _Pragma("unroll") for (int m = 0; m < 4; ++m) _Pragma("unroll") for (int k = 0; k < 2; ++k) \
;     dst[m][k] = *(const GLAS bf16x8*)(lds + G_SA(b, h) + aoff + m * 2048 + k * 1024); } while (0)
; #define G_MMA(ai, bj, At_, Bt_) do { __builtin_amdgcn_s_setprio(1); \
;     _Pragma("unroll") for (int m = 0; m < 4; ++m) _Pragma("unroll") for (int n = 0; n < 2; ++n) _Pragma("unroll") for (int k = 0; k < 2; ++k) \
;       acc[ai][bj][m][n] = __builtin_amdgcn_mfma_f32_16x16x32_bf16(Bt_[n][k], At_[m][k], acc[ai][bj][m][n], 0, 0, 0); \
;     __builtin_amdgcn_s_setprio(0); } while (0)
; #define G_WAIT_V(n) asm volatile("s_waitcnt vmcnt(" #n ")" ::: "memory")
; #define G_WAIT_L(n) asm volatile("s_waitcnt lgkmcnt(" #n ")" ::: "memory")
; #define G_BAR __builtin_amdgcn_s_barrier()
; #define G_SCHED __builtin_amdgcn_sched_barrier(0)
; __device__ __forceinline__ void gemm_phase(const Params& p, int l, const bf16_t* __restrict__ A, const bf16_t* __restrict__ Bt, int M, int N, int K,
;                            int epi, bf16_t* __restrict__ outp, char* smem, int wvi) {
;     ...
;         G_LDA(At, 1, 1); G_STAGE(G_SA(1, 0), a3);
;         G_BAR; G_WAIT_L(0); G_MMA(1, 0, At, B0); G_BAR; G_SCHED;
;         G_STAGE(G_SB(1, 1), b3 + hstep);
;         G_WAIT_V(6); G_BAR; G_MMA(1, 1, At, B1); G_BAR;
;     ...
;       } else if (wc == 0 && fq < 2) {
;         const float* db = p.dt_bias + l * 16 + fq * 8;
;         float dbv[8];
; #pragma unroll
;         for (int i = 0; i < 8; ++i) dbv[i] = db[i];
; #pragma unroll
;         for (int ai = 0; ai < 2; ++ai)
; #pragma unroll
;           for (int m = 0; m < 4; ++m) {
;             const f32x4 v0 = acc[ai][0][m][0], v1 = acc[ai][0][m][1];
;             float4 o0, o1;
;             o0.x = softplus_f(v0[0] + dbv[0]); o0.y = softplus_f(v0[1] + dbv[1]); o0.z = softplus_f(v0[2] + dbv[2]); o0.w = softplus_f(v0[3] + dbv[3]);
	ds_read_b128 v[162:165], v160 offset:49152
	ds_read_b128 v[166:169], v160 offset:50176
	ds_read_b128 v[170:173], v160 offset:51200
	ds_read_b128 v[182:185], v160 offset:52224
	ds_read_b128 v[186:189], v160 offset:53248
	ds_read_b128 v[214:217], v160 offset:54272
	ds_read_b128 v[218:221], v160 offset:55296
	ds_read_b128 v[222:225], v160 offset:56320
	global_load_lds_dwordx4 v[156:157], off
	v_lshl_add_u64 v[156:157], v[242:243], 0, s[64:65]
	s_mov_b32 m0, s93
	s_nop 0
	global_load_lds_dwordx4 v[156:157], off
	s_waitcnt vmcnt(10)
	s_barrier
	s_waitcnt lgkmcnt(0)
	s_waitcnt lgkmcnt(0)
	v_mfma_f32_16x16x32_bf16 v[56:59], v[128:131], v[162:165], v[56:59]
	v_mfma_f32_16x16x32_bf16 v[72:75], v[136:139], v[162:165], v[72:75]
	v_mfma_f32_16x16x32_bf16 v[44:47], v[128:131], v[170:173], v[44:47]
	v_mfma_f32_16x16x32_bf16 v[60:63], v[136:139], v[170:173], v[60:63]
	v_mfma_f32_16x16x32_bf16 v[36:39], v[128:131], v[186:189], v[36:39]
	v_mfma_f32_16x16x32_bf16 v[48:51], v[136:139], v[186:189], v[48:51]
	v_mfma_f32_16x16x32_bf16 v[32:35], v[128:131], v[218:221], v[32:35]
	v_mfma_f32_16x16x32_bf16 v[40:43], v[136:139], v[218:221], v[40:43]
	v_mfma_f32_16x16x32_bf16 v[56:59], v[132:135], v[166:169], v[56:59]
	v_mfma_f32_16x16x32_bf16 v[72:75], v[140:143], v[166:169], v[72:75]
	v_mfma_f32_16x16x32_bf16 v[44:47], v[132:135], v[182:185], v[44:47]
	v_mfma_f32_16x16x32_bf16 v[60:63], v[140:143], v[182:185], v[60:63]
	v_mfma_f32_16x16x32_bf16 v[36:39], v[132:135], v[214:217], v[36:39]
	v_mfma_f32_16x16x32_bf16 v[48:51], v[140:143], v[214:217], v[48:51]
	v_mfma_f32_16x16x32_bf16 v[32:35], v[132:135], v[222:225], v[32:35]
	v_mfma_f32_16x16x32_bf16 v[40:43], v[140:143], v[222:225], v[40:43]
	s_barrier
	s_add_u32 s4, s4, 0x40080
	s_addc_u32 s5, s5, 0
	s_add_i32 s6, s6, s58
	v_lshl_add_u64 v[128:129], s[4:5], 0, v[146:147]
	s_mov_b32 m0, s6
	s_nop 0
	global_load_lds_dwordx4 v[128:129], off
	v_lshl_add_u64 v[128:129], s[4:5], 0, v[144:145]
	s_add_i32 m0, s6, 0x2000
	s_nop 0
	global_load_lds_dwordx4 v[128:129], off
	s_waitcnt vmcnt(6)
	s_barrier
	v_mfma_f32_16x16x32_bf16 v[120:123], v[226:229], v[162:165], v[120:123]
	v_mfma_f32_16x16x32_bf16 v[124:127], v[234:237], v[162:165], v[124:127]
	v_mfma_f32_16x16x32_bf16 v[112:115], v[226:229], v[170:173], v[112:115]
	v_mfma_f32_16x16x32_bf16 v[116:119], v[234:237], v[170:173], v[116:119]
	v_mfma_f32_16x16x32_bf16 v[104:107], v[226:229], v[186:189], v[104:107]
	v_mfma_f32_16x16x32_bf16 v[108:111], v[234:237], v[186:189], v[108:111]
	v_mfma_f32_16x16x32_bf16 v[88:91], v[226:229], v[218:221], v[88:91]
	v_mfma_f32_16x16x32_bf16 v[96:99], v[234:237], v[218:221], v[96:99]
	v_mfma_f32_16x16x32_bf16 v[120:123], v[230:233], v[166:169], v[120:123]
	v_mfma_f32_16x16x32_bf16 v[124:127], v[238:241], v[166:169], v[124:127]
	v_mfma_f32_16x16x32_bf16 v[112:115], v[230:233], v[182:185], v[112:115]
	v_mfma_f32_16x16x32_bf16 v[116:119], v[238:241], v[182:185], v[116:119]
	v_mfma_f32_16x16x32_bf16 v[104:107], v[230:233], v[214:217], v[104:107]
	v_mfma_f32_16x16x32_bf16 v[108:111], v[238:241], v[214:217], v[108:111]
	v_mfma_f32_16x16x32_bf16 v[88:91], v[230:233], v[222:225], v[88:91]
	v_mfma_f32_16x16x32_bf16 v[96:99], v[238:241], v[222:225], v[96:99]
	s_add_i32 s20, s20, 2
	s_add_u32 s11, s11, 0x100
	s_addc_u32 s17, s17, 0
	s_cmp_gt_u32 s20, 13
	s_mov_b64 s[6:7], s[2:3]
	s_barrier
	s_cbranch_scc0 .LBB0_568
	v_lshl_add_u32 v156, s0, 8, v158
	s_cmp_gt_i32 s16, 11
	s_mov_b64 s[2:3], -1
	s_mov_b32 s9, 0x41a00000
	s_cbranch_scc0 .LBB0_957
	s_and_saveexec_b64 s[6:7], s[24:25]
	s_cbranch_execz .LBB0_956
	global_load_dwordx4 v[132:135], v[148:149], off
	global_load_dwordx4 v[128:131], v[148:149], off offset:16
	s_waitcnt vmcnt(0)
	v_add_f32_e32 v136, v20, v132
	v_cmp_nlt_f32_e32 vcc, s9, v136
	s_and_saveexec_b64 s[2:3], vcc
	s_cbranch_execz .LBB0_577
	v_mul_f32_e32 v136, 0x3fb8aa3b, v136
	v_exp_f32_e32 v137, v136
	s_nop 0
	v_cmp_ngt_f32_e32 vcc, s18, v137
	s_and_saveexec_b64 s[0:1], vcc
	s_xor_b64 s[28:29], exec, s[0:1]
	s_cbranch_execz .LBB0_574
	v_add_f32_e32 v136, 1.0, v137
	s_mov_b32 s0, 0x800000
	v_cmp_gt_f32_e32 vcc, s0, v136
	s_mov_b32 s0, 0x3f317217
	s_nop 0
	v_cndmask_b32_e64 v137, 0, 32, vcc
	v_ldexp_f32 v136, v136, v137
	v_log_f32_e32 v136, v136
	s_nop 0
	v_mul_f32_e32 v137, 0x3f317217, v136
	v_fma_f32 v137, v136, s0, -v137
	v_fmac_f32_e32 v137, 0x3377d1cf, v136
	s_mov_b32 s0, 0x7f800000
	v_fmac_f32_e32 v137, 0x3f317217, v136
	v_cmp_lt_f32_e64 s[4:5], |v136|, s0
	s_nop 1
	v_cndmask_b32_e64 v136, v136, v137, s[4:5]
	v_cndmask_b32_e32 v137, 0, v212, vcc
	v_sub_f32_e32 v136, v136, v137

; #define G_STAGE(bufoff, gbase) do { _Pragma("unroll") for (int _i = 0; _i < 2; ++_i) \
;     __builtin_amdgcn_global_load_lds((const unsigned*)((const char*)(gbase) + voff[_i]), (GLAS unsigned*)(lds + (bufoff) + ldsw + _i * 8192), 16, 0, 0); } while (0)
; #define G_LDA(dst, b, h) do { _Pragma("unroll") for (int m = 0; m < 4; ++m) _Pragma("unroll") for (int k = 0; k < 2; ++k) \
;     dst[m][k] = *(const GLAS bf16x8*)(lds + G_SA(b, h) + aoff + m * 2048 + k * 1024); } while (0)
; #define G_LDB(dst, b, h) do { _Pragma("unroll") for (int n = 0; n < 2; ++n) _Pragma("unroll") for (int k = 0; k < 2; ++k) \
;     dst[n][k] = *(const GLAS bf16x8*)(lds + G_SB(b, h) + boff + n * 2048 + k * 1024); } while (0)
; #define G_MMA(ai, bj, At_, Bt_) do { __builtin_amdgcn_s_setprio(1); \
;     _Pragma("unroll") for (int m = 0; m < 4; ++m) _Pragma("unroll") for (int n = 0; n < 2; ++n) _Pragma("unroll") for (int k = 0; k < 2; ++k) \
;       acc[ai][bj][m][n] = __builtin_amdgcn_mfma_f32_16x16x32_bf16(Bt_[n][k], At_[m][k], acc[ai][bj][m][n], 0, 0, 0); \
;     __builtin_amdgcn_s_setprio(0); } while (0)
; #define G_WAIT_L(n) asm volatile("s_waitcnt lgkmcnt(" #n ")" ::: "memory")
; #define G_BAR __builtin_amdgcn_s_barrier()
; #define G_SCHED __builtin_amdgcn_sched_barrier(0)
; __device__ __forceinline__ void gemm_phase(const Params& p, int l, const bf16_t* __restrict__ A, const bf16_t* __restrict__ Bt, int M, int N, int K,
;                            int epi, bf16_t* __restrict__ outp, char* smem, int wvi) {
;     ...
;       for (int t = 0; t < nt; t += 2) {
;         const bool lastt = (t == nt - 2);
;         const char* a1 = cA + (size_t)(t + 1) * kstep;
;         const char* a2 = lastt ? nA : cA + (size_t)(t + 2) * kstep; const char* b2 = lastt ? nB : cB + (size_t)(t + 2) * kstep;
;         const char* a3 = a2 + kstep; const char* b3 = b2 + kstep;
;         G_LDB(B0, 0, 0); G_SCHED; G_LDA(At, 0, 0); G_STAGE(G_SA(1, 1), a1 + hstep);
;         G_WAIT_L(8); G_BAR; G_WAIT_L(0); G_MMA(0, 0, At, B0); G_BAR; G_SCHED;
;         G_LDB(B1, 0, 1); G_STAGE(G_SB(0, 0), b2);
;         G_BAR; G_WAIT_L(0); G_MMA(0, 1, At, B1); G_BAR;
;         G_LDA(At, 0, 1); G_STAGE(G_SA(0, 0), a2);
;         G_BAR; G_WAIT_L(0); G_MMA(1, 0, At, B0); G_BAR; G_SCHED;
.LBB0_1039:
	s_add_u32 s2, s12, 0x100
	s_addc_u32 s3, s13, 0
	s_add_i32 s53, 0, 0x10000
	s_cmp_eq_u32 s31, 40
	s_cselect_b32 s15, s5, s3
	s_cselect_b32 s14, s4, s2
	s_cselect_b32 s11, s28, s30
	s_cselect_b32 s10, s27, s29
	v_lshl_add_u64 v[190:191], s[12:13], 0, v[132:133]
	s_add_i32 m0, s1, 0xc000
	ds_read_b128 v[156:159], v138
	ds_read_b128 v[160:163], v138 offset:1024
	ds_read_b128 v[164:167], v138 offset:2048
	ds_read_b128 v[168:171], v138 offset:3072
	ds_read_b128 v[172:175], v138 offset:4096
	ds_read_b128 v[182:185], v138 offset:5120
	ds_read_b128 v[186:189], v138 offset:6144
	ds_read_b128 v[214:217], v138 offset:7168
	global_load_lds_dwordx4 v[190:191], off
	v_lshl_add_u64 v[190:191], s[12:13], 0, v[134:135]
	s_add_i32 m0, s1, 0xe000
	s_nop 0
	global_load_lds_dwordx4 v[190:191], off
	s_waitcnt lgkmcnt(8)
	s_barrier
	s_waitcnt lgkmcnt(0)
	s_waitcnt lgkmcnt(0)
	v_mfma_f32_16x16x32_bf16 v[20:23], v[140:143], v[156:159], v[20:23]
	v_mfma_f32_16x16x32_bf16 v[28:31], v[148:151], v[156:159], v[28:31]
	v_mfma_f32_16x16x32_bf16 v[12:15], v[140:143], v[164:167], v[12:15]
	v_mfma_f32_16x16x32_bf16 v[24:27], v[148:151], v[164:167], v[24:27]
	v_mfma_f32_16x16x32_bf16 v[4:7], v[140:143], v[172:175], v[4:7]
	v_mfma_f32_16x16x32_bf16 v[16:19], v[148:151], v[172:175], v[16:19]
	v_mfma_f32_16x16x32_bf16 v[0:3], v[140:143], v[186:189], v[0:3]
	v_mfma_f32_16x16x32_bf16 v[8:11], v[148:151], v[186:189], v[8:11]
	v_mfma_f32_16x16x32_bf16 v[20:23], v[144:147], v[160:163], v[20:23]
	v_mfma_f32_16x16x32_bf16 v[28:31], v[152:155], v[160:163], v[28:31]
	v_mfma_f32_16x16x32_bf16 v[12:15], v[144:147], v[168:171], v[12:15]
	v_mfma_f32_16x16x32_bf16 v[24:27], v[152:155], v[168:171], v[24:27]
	v_mfma_f32_16x16x32_bf16 v[4:7], v[144:147], v[182:185], v[4:7]
	v_mfma_f32_16x16x32_bf16 v[16:19], v[152:155], v[182:185], v[16:19]
	v_mfma_f32_16x16x32_bf16 v[0:3], v[144:147], v[214:217], v[0:3]
	v_mfma_f32_16x16x32_bf16 v[8:11], v[152:155], v[214:217], v[8:11]
	s_barrier
	s_add_i32 s55, 0, 0x14000
	s_add_i32 s12, s53, s58
	v_add_u32_e32 v139, s55, v137
	v_lshl_add_u64 v[190:191], s[10:11], 0, v[176:177]
	s_mov_b32 m0, s12
	ds_read_b128 v[218:221], v139
	ds_read_b128 v[222:225], v139 offset:1024
	ds_read_b128 v[226:229], v139 offset:2048
	ds_read_b128 v[230:233], v139 offset:3072
	global_load_lds_dwordx4 v[190:191], off
	v_lshl_add_u64 v[234:235], s[10:11], 0, v[128:129]
	s_add_i32 m0, s12, 0x2000
	s_nop 0
	global_load_lds_dwordx4 v[234:235], off
	s_barrier
	s_waitcnt lgkmcnt(0)
	s_waitcnt lgkmcnt(0)
	v_mfma_f32_16x16x32_bf16 v[80:83], v[218:221], v[156:159], v[80:83]
	v_mfma_f32_16x16x32_bf16 v[92:95], v[226:229], v[156:159], v[92:95]
	v_mfma_f32_16x16x32_bf16 v[64:67], v[218:221], v[164:167], v[64:67]
	v_mfma_f32_16x16x32_bf16 v[84:87], v[226:229], v[164:167], v[84:87]
	v_mfma_f32_16x16x32_bf16 v[52:55], v[218:221], v[172:175], v[52:55]
	v_mfma_f32_16x16x32_bf16 v[76:79], v[226:229], v[172:175], v[76:79]
	v_mfma_f32_16x16x32_bf16 v[40:43], v[218:221], v[186:189], v[40:43]
	v_mfma_f32_16x16x32_bf16 v[60:63], v[226:229], v[186:189], v[60:63]
	v_mfma_f32_16x16x32_bf16 v[80:83], v[222:225], v[160:163], v[80:83]
	v_mfma_f32_16x16x32_bf16 v[92:95], v[230:233], v[160:163], v[92:95]
	v_mfma_f32_16x16x32_bf16 v[64:67], v[222:225], v[168:171], v[64:67]
	v_mfma_f32_16x16x32_bf16 v[84:87], v[230:233], v[168:171], v[84:87]
	v_mfma_f32_16x16x32_bf16 v[52:55], v[222:225], v[182:185], v[52:55]
	v_mfma_f32_16x16x32_bf16 v[76:79], v[230:233], v[182:185], v[76:79]
	v_mfma_f32_16x16x32_bf16 v[40:43], v[222:225], v[214:217], v[40:43]
	v_mfma_f32_16x16x32_bf16 v[60:63], v[230:233], v[214:217], v[60:63]
	s_mov_b32 m0, s1
	v_lshl_add_u64 v[236:237], s[14:15], 0, v[176:177]
	s_barrier
	ds_read_b128 v[156:159], v138 offset:16384
	ds_read_b128 v[160:163], v138 offset:17408
	ds_read_b128 v[164:167], v138 offset:18432
	ds_read_b128 v[168:171], v138 offset:19456
	ds_read_b128 v[172:175], v138 offset:20480
	ds_read_b128 v[182:185], v138 offset:21504
	ds_read_b128 v[186:189], v138 offset:22528
	ds_read_b128 v[214:217], v138 offset:23552
	global_load_lds_dwordx4 v[236:237], off
	v_lshl_add_u64 v[238:239], s[14:15], 0, v[128:129]
	s_mov_b32 m0, s16
	s_nop 0
	global_load_lds_dwordx4 v[238:239], off
	s_waitcnt vmcnt(10)
	s_barrier
	s_waitcnt lgkmcnt(0)
	s_waitcnt lgkmcnt(0)
	v_mfma_f32_16x16x32_bf16 v[68:71], v[140:143], v[156:159], v[68:71]
	v_mfma_f32_16x16x32_bf16 v[88:91], v[148:151], v[156:159], v[88:91]
	v_mfma_f32_16x16x32_bf16 v[48:51], v[140:143], v[164:167], v[48:51]
	v_mfma_f32_16x16x32_bf16 v[72:75], v[148:151], v[164:167], v[72:75]
	v_mfma_f32_16x16x32_bf16 v[36:39], v[140:143], v[172:175], v[36:39]
	v_mfma_f32_16x16x32_bf16 v[56:59], v[148:151], v[172:175], v[56:59]
	v_mfma_f32_16x16x32_bf16 v[32:35], v[140:143], v[186:189], v[32:35]
	v_mfma_f32_16x16x32_bf16 v[44:47], v[148:151], v[186:189], v[44:47]
	v_mfma_f32_16x16x32_bf16 v[68:71], v[144:147], v[160:163], v[68:71]
	v_mfma_f32_16x16x32_bf16 v[88:91], v[152:155], v[160:163], v[88:91]
	v_mfma_f32_16x16x32_bf16 v[48:51], v[144:147], v[168:171], v[48:51]
	v_mfma_f32_16x16x32_bf16 v[72:75], v[152:155], v[168:171], v[72:75]
	v_mfma_f32_16x16x32_bf16 v[36:39], v[144:147], v[182:185], v[36:39]
	v_mfma_f32_16x16x32_bf16 v[56:59], v[152:155], v[182:185], v[56:59]
	v_mfma_f32_16x16x32_bf16 v[32:35], v[144:147], v[214:217], v[32:35]
	v_mfma_f32_16x16x32_bf16 v[44:47], v[152:155], v[214:217], v[44:47]
	s_barrier
; #define G_STAGE(bufoff, gbase) do { _Pragma("unroll") for (int _i = 0; _i < 2; ++_i) \
;     __builtin_amdgcn_global_load_lds((const unsigned*)((const char*)(gbase) + voff[_i]), (GLAS unsigned*)(lds + (bufoff) + ldsw + _i * 8192), 16, 0, 0); } while (0)
; #define G_LDA(dst, b, h) do { _Pragma("unroll") for (int m = 0; m < 4; ++m) _Pragma("unroll") for (int k = 0; k < 2; ++k) \
;     dst[m][k] = *(const GLAS bf16x8*)(lds + G_SA(b, h) + aoff + m * 2048 + k * 1024); } while (0)
; #define G_LDB(dst, b, h) do { _Pragma("unroll") for (int n = 0; n < 2; ++n) _Pragma("unroll") for (int k = 0; k < 2; ++k) \
;     dst[n][k] = *(const GLAS bf16x8*)(lds + G_SB(b, h) + boff + n * 2048 + k * 1024); } while (0)
; #define G_MMA(ai, bj, At_, Bt_) do { __builtin_amdgcn_s_setprio(1); \
;     _Pragma("unroll") for (int m = 0; m < 4; ++m) _Pragma("unroll") for (int n = 0; n < 2; ++n) _Pragma("unroll") for (int k = 0; k < 2; ++k) \
;       acc[ai][bj][m][n] = __builtin_amdgcn_mfma_f32_16x16x32_bf16(Bt_[n][k], At_[m][k], acc[ai][bj][m][n], 0, 0, 0); \
;     __builtin_amdgcn_s_setprio(0); } while (0)
; #define G_WAIT_V(n) asm volatile("s_waitcnt vmcnt(" #n ")" ::: "memory")
; #define G_WAIT_L(n) asm volatile("s_waitcnt lgkmcnt(" #n ")" ::: "memory")
; #define G_BAR __builtin_amdgcn_s_barrier()
; #define G_SCHED __builtin_amdgcn_sched_barrier(0)
; __device__ __forceinline__ void gemm_phase(const Params& p, int l, const bf16_t* __restrict__ A, const bf16_t* __restrict__ Bt, int M, int N, int K,
;                            int epi, bf16_t* __restrict__ outp, char* smem, int wvi) {
;     ...
;         G_STAGE(G_SB(0, 1), b2 + hstep);
;         G_WAIT_V(6); G_BAR; G_MMA(1, 1, At, B1); G_BAR;
;         G_LDB(B0, 1, 0); G_SCHED; G_LDA(At, 1, 0); G_STAGE(G_SA(0, 1), a2 + hstep);
;         G_WAIT_L(8); G_BAR; G_WAIT_L(0); G_MMA(0, 0, At, B0); G_BAR; G_SCHED;
;         G_LDB(B1, 1, 1); G_STAGE(G_SB(1, 0), b3);
;         G_BAR; G_WAIT_L(0); G_MMA(0, 1, At, B1); G_BAR;
;         G_LDA(At, 1, 1); G_STAGE(G_SA(1, 0), a3);
;         G_BAR; G_WAIT_L(0); G_MMA(1, 0, At, B0); G_BAR; G_SCHED;
	s_add_u32 s12, s10, 0xb0000
	s_addc_u32 s13, s11, 0
	s_add_i32 s53, s55, s58
	v_lshl_add_u64 v[140:141], s[12:13], 0, v[176:177]
	s_mov_b32 m0, s53
	s_nop 0
	global_load_lds_dwordx4 v[140:141], off
	v_lshl_add_u64 v[140:141], s[12:13], 0, v[128:129]
	s_add_i32 m0, s53, 0x2000
	s_nop 0
	global_load_lds_dwordx4 v[140:141], off
	v_add_u32_e32 v139, 0x18000, v137
	ds_read_b128 v[140:143], v139
	ds_read_b128 v[144:147], v139 offset:1024
	ds_read_b128 v[148:151], v139 offset:2048
	ds_read_b128 v[152:155], v139 offset:3072
	s_waitcnt vmcnt(10)
	s_barrier
	v_mfma_f32_16x16x32_bf16 v[120:123], v[218:221], v[156:159], v[120:123]
	v_mfma_f32_16x16x32_bf16 v[124:127], v[226:229], v[156:159], v[124:127]
	v_mfma_f32_16x16x32_bf16 v[112:115], v[218:221], v[164:167], v[112:115]
	v_mfma_f32_16x16x32_bf16 v[116:119], v[226:229], v[164:167], v[116:119]
	v_mfma_f32_16x16x32_bf16 v[104:107], v[218:221], v[172:175], v[104:107]
	v_mfma_f32_16x16x32_bf16 v[108:111], v[226:229], v[172:175], v[108:111]
	v_mfma_f32_16x16x32_bf16 v[96:99], v[218:221], v[186:189], v[96:99]
	v_mfma_f32_16x16x32_bf16 v[100:103], v[226:229], v[186:189], v[100:103]
	v_mfma_f32_16x16x32_bf16 v[120:123], v[222:225], v[160:163], v[120:123]
	v_mfma_f32_16x16x32_bf16 v[124:127], v[230:233], v[160:163], v[124:127]
	v_mfma_f32_16x16x32_bf16 v[112:115], v[222:225], v[168:171], v[112:115]
	v_mfma_f32_16x16x32_bf16 v[116:119], v[230:233], v[168:171], v[116:119]
	v_mfma_f32_16x16x32_bf16 v[104:107], v[222:225], v[182:185], v[104:107]
	v_mfma_f32_16x16x32_bf16 v[108:111], v[230:233], v[182:185], v[108:111]
	v_mfma_f32_16x16x32_bf16 v[96:99], v[222:225], v[214:217], v[96:99]
	v_mfma_f32_16x16x32_bf16 v[100:103], v[230:233], v[214:217], v[100:103]
	s_add_i32 s53, 0, 0x18000
	s_barrier
	s_add_u32 s12, s14, 0xb0000
	s_addc_u32 s13, s15, 0
	s_mov_b32 m0, s17
	v_lshl_add_u64 v[218:219], s[12:13], 0, v[176:177]
	ds_read_b128 v[156:159], v138 offset:32768
	ds_read_b128 v[160:163], v138 offset:33792
	ds_read_b128 v[164:167], v138 offset:34816
	ds_read_b128 v[168:171], v138 offset:35840
	ds_read_b128 v[172:175], v138 offset:36864
	ds_read_b128 v[182:185], v138 offset:37888
	ds_read_b128 v[186:189], v138 offset:38912
	ds_read_b128 v[214:217], v138 offset:39936
	global_load_lds_dwordx4 v[218:219], off
	v_lshl_add_u64 v[218:219], s[12:13], 0, v[128:129]
	s_mov_b32 m0, s20
	s_nop 0
	global_load_lds_dwordx4 v[218:219], off
	s_waitcnt lgkmcnt(8)
	s_waitcnt vmcnt(10)
	s_barrier
	s_waitcnt lgkmcnt(0)
	s_waitcnt lgkmcnt(0)
	v_mfma_f32_16x16x32_bf16 v[20:23], v[140:143], v[156:159], v[20:23]
	v_mfma_f32_16x16x32_bf16 v[28:31], v[148:151], v[156:159], v[28:31]
	v_mfma_f32_16x16x32_bf16 v[12:15], v[140:143], v[164:167], v[12:15]
	v_mfma_f32_16x16x32_bf16 v[24:27], v[148:151], v[164:167], v[24:27]
	v_mfma_f32_16x16x32_bf16 v[4:7], v[140:143], v[172:175], v[4:7]
	v_mfma_f32_16x16x32_bf16 v[16:19], v[148:151], v[172:175], v[16:19]
	v_mfma_f32_16x16x32_bf16 v[0:3], v[140:143], v[186:189], v[0:3]
	v_mfma_f32_16x16x32_bf16 v[8:11], v[148:151], v[186:189], v[8:11]
	v_mfma_f32_16x16x32_bf16 v[20:23], v[144:147], v[160:163], v[20:23]
	v_mfma_f32_16x16x32_bf16 v[28:31], v[152:155], v[160:163], v[28:31]
	v_mfma_f32_16x16x32_bf16 v[12:15], v[144:147], v[168:171], v[12:15]
	v_mfma_f32_16x16x32_bf16 v[24:27], v[152:155], v[168:171], v[24:27]
	v_mfma_f32_16x16x32_bf16 v[4:7], v[144:147], v[182:185], v[4:7]
	v_mfma_f32_16x16x32_bf16 v[16:19], v[152:155], v[182:185], v[16:19]
	v_mfma_f32_16x16x32_bf16 v[0:3], v[144:147], v[214:217], v[0:3]
	v_mfma_f32_16x16x32_bf16 v[8:11], v[152:155], v[214:217], v[8:11]
	s_barrier
	s_add_i32 s12, 0, 0x1c000
	s_add_i32 s13, s53, s58
	v_add_u32_e32 v139, s12, v137
	v_lshl_add_u64 v[190:191], v[190:191], 0, s[64:65]
	s_mov_b32 m0, s13
	ds_read_b128 v[218:221], v139
	ds_read_b128 v[222:225], v139 offset:1024
	ds_read_b128 v[226:229], v139 offset:2048
	ds_read_b128 v[230:233], v139 offset:3072
	global_load_lds_dwordx4 v[190:191], off
	v_lshl_add_u64 v[190:191], v[234:235], 0, s[64:65]
	s_add_i32 m0, s13, 0x2000
	s_nop 0
	global_load_lds_dwordx4 v[190:191], off
	s_waitcnt vmcnt(10)
	s_barrier
	s_waitcnt lgkmcnt(0)
	s_waitcnt lgkmcnt(0)
	v_mfma_f32_16x16x32_bf16 v[80:83], v[218:221], v[156:159], v[80:83]
	v_mfma_f32_16x16x32_bf16 v[92:95], v[226:229], v[156:159], v[92:95]
	v_mfma_f32_16x16x32_bf16 v[64:67], v[218:221], v[164:167], v[64:67]
	v_mfma_f32_16x16x32_bf16 v[84:87], v[226:229], v[164:167], v[84:87]
	v_mfma_f32_16x16x32_bf16 v[52:55], v[218:221], v[172:175], v[52:55]
	v_mfma_f32_16x16x32_bf16 v[76:79], v[226:229], v[172:175], v[76:79]
	v_mfma_f32_16x16x32_bf16 v[40:43], v[218:221], v[186:189], v[40:43]
	v_mfma_f32_16x16x32_bf16 v[60:63], v[226:229], v[186:189], v[60:63]
	v_mfma_f32_16x16x32_bf16 v[80:83], v[222:225], v[160:163], v[80:83]
	v_mfma_f32_16x16x32_bf16 v[92:95], v[230:233], v[160:163], v[92:95]
	v_mfma_f32_16x16x32_bf16 v[64:67], v[222:225], v[168:171], v[64:67]
	v_mfma_f32_16x16x32_bf16 v[84:87], v[230:233], v[168:171], v[84:87]
	v_mfma_f32_16x16x32_bf16 v[52:55], v[222:225], v[182:185], v[52:55]
	v_mfma_f32_16x16x32_bf16 v[76:79], v[230:233], v[182:185], v[76:79]
	v_mfma_f32_16x16x32_bf16 v[40:43], v[222:225], v[214:217], v[40:43]
	v_mfma_f32_16x16x32_bf16 v[60:63], v[230:233], v[214:217], v[60:63]
	s_mov_b32 m0, s0
	v_lshl_add_u64 v[190:191], v[236:237], 0, s[64:65]
	s_barrier
	ds_read_b128 v[156:159], v138 offset:49152
	ds_read_b128 v[160:163], v138 offset:50176
	ds_read_b128 v[164:167], v138 offset:51200
	ds_read_b128 v[168:171], v138 offset:52224
	ds_read_b128 v[172:175], v138 offset:53248
	ds_read_b128 v[182:185], v138 offset:54272
	ds_read_b128 v[186:189], v138 offset:55296
	ds_read_b128 v[214:217], v138 offset:56320
	global_load_lds_dwordx4 v[190:191], off
	v_lshl_add_u64 v[190:191], v[238:239], 0, s[64:65]
	s_mov_b32 m0, s21
	s_nop 0
	global_load_lds_dwordx4 v[190:191], off
	s_waitcnt vmcnt(10)
	s_barrier
; __device__ __forceinline__ u32x4 mk4(unsigned a, unsigned b, unsigned c, unsigned d) { return (u32x4){a, b, c, d}; }
; #define G_STAGE(bufoff, gbase) do { _Pragma("unroll") for (int _i = 0; _i < 2; ++_i) \
;     __builtin_amdgcn_global_load_lds((const unsigned*)((const char*)(gbase) + voff[_i]), (GLAS unsigned*)(lds + (bufoff) + ldsw + _i * 8192), 16, 0, 0); } while (0)
; #define G_MMA(ai, bj, At_, Bt_) do { __builtin_amdgcn_s_setprio(1); \
;     _Pragma("unroll") for (int m = 0; m < 4; ++m) _Pragma("unroll") for (int n = 0; n < 2; ++n) _Pragma("unroll") for (int k = 0; k < 2; ++k) \
;       acc[ai][bj][m][n] = __builtin_amdgcn_mfma_f32_16x16x32_bf16(Bt_[n][k], At_[m][k], acc[ai][bj][m][n], 0, 0, 0); \
;     __builtin_amdgcn_s_setprio(0); } while (0)
; #define G_WAIT_V(n) asm volatile("s_waitcnt vmcnt(" #n ")" ::: "memory")
; #define G_WAIT_L(n) asm volatile("s_waitcnt lgkmcnt(" #n ")" ::: "memory")
; #define G_BAR __builtin_amdgcn_s_barrier()
; #define G_SCHED __builtin_amdgcn_sched_barrier(0)
; __device__ __forceinline__ void gemm_phase(const Params& p, int l, const bf16_t* __restrict__ A, const bf16_t* __restrict__ Bt, int M, int N, int K,
;                            int epi, bf16_t* __restrict__ outp, char* smem, int wvi) {
;     ...
;         G_BAR; G_WAIT_L(0); G_MMA(1, 0, At, B0); G_BAR; G_SCHED;
;         G_STAGE(G_SB(1, 1), b3 + hstep);
;         G_WAIT_V(6); G_BAR; G_MMA(1, 1, At, B1); G_BAR;
;     ...
;     if (epi == EPI_PLAIN) {
; #pragma unroll
;       for (int ai = 0; ai < 2; ++ai)
; #pragma unroll
;         for (int m = 0; m < 4; ++m) {
;           bf16_t* rp = outp + (size_t)(r0 + ai * GHALF + m * 16) * N + bcol + wc * 32 + fq * 8;
; #pragma unroll
;           for (int bj = 0; bj < 2; ++bj) {
;             const f32x4 v0 = acc[ai][bj][m][0], v1 = acc[ai][bj][m][1];
;             *reinterpret_cast<u32x4*>(rp + bj * GHALF) = mk4(pk2(v0[0], v0[1]), pk2(v0[2], v0[3]), pk2(v1[0], v1[1]), pk2(v1[2], v1[3]));
;           }
;         }
	s_waitcnt lgkmcnt(0)
	s_waitcnt lgkmcnt(0)
	v_mfma_f32_16x16x32_bf16 v[68:71], v[140:143], v[156:159], v[68:71]
	v_mfma_f32_16x16x32_bf16 v[88:91], v[148:151], v[156:159], v[88:91]
	v_mfma_f32_16x16x32_bf16 v[48:51], v[140:143], v[164:167], v[48:51]
	v_mfma_f32_16x16x32_bf16 v[72:75], v[148:151], v[164:167], v[72:75]
	v_mfma_f32_16x16x32_bf16 v[36:39], v[140:143], v[172:175], v[36:39]
	v_mfma_f32_16x16x32_bf16 v[56:59], v[148:151], v[172:175], v[56:59]
	v_mfma_f32_16x16x32_bf16 v[32:35], v[140:143], v[186:189], v[32:35]
	v_mfma_f32_16x16x32_bf16 v[44:47], v[148:151], v[186:189], v[44:47]
	v_mfma_f32_16x16x32_bf16 v[68:71], v[144:147], v[160:163], v[68:71]
	v_mfma_f32_16x16x32_bf16 v[88:91], v[152:155], v[160:163], v[88:91]
	v_mfma_f32_16x16x32_bf16 v[48:51], v[144:147], v[168:171], v[48:51]
	v_mfma_f32_16x16x32_bf16 v[72:75], v[152:155], v[168:171], v[72:75]
	v_mfma_f32_16x16x32_bf16 v[36:39], v[144:147], v[182:185], v[36:39]
	v_mfma_f32_16x16x32_bf16 v[56:59], v[152:155], v[182:185], v[56:59]
	v_mfma_f32_16x16x32_bf16 v[32:35], v[144:147], v[214:217], v[32:35]
	v_mfma_f32_16x16x32_bf16 v[44:47], v[152:155], v[214:217], v[44:47]
	s_barrier
	s_add_u32 s10, s10, 0xb0080
	s_addc_u32 s11, s11, 0
	s_add_i32 s12, s12, s58
	v_lshl_add_u64 v[140:141], s[10:11], 0, v[176:177]
	s_mov_b32 m0, s12
	s_nop 0
	global_load_lds_dwordx4 v[140:141], off
	v_lshl_add_u64 v[140:141], s[10:11], 0, v[128:129]
	s_add_i32 m0, s12, 0x2000
	s_nop 0
	global_load_lds_dwordx4 v[140:141], off
	v_add_u32_e32 v139, 0x10000, v137
	ds_read_b128 v[140:143], v139
	ds_read_b128 v[144:147], v139 offset:1024
	ds_read_b128 v[148:151], v139 offset:2048
	ds_read_b128 v[152:155], v139 offset:3072
	s_waitcnt vmcnt(6)
	s_barrier
	v_mfma_f32_16x16x32_bf16 v[120:123], v[218:221], v[156:159], v[120:123]
	v_mfma_f32_16x16x32_bf16 v[124:127], v[226:229], v[156:159], v[124:127]
	v_mfma_f32_16x16x32_bf16 v[112:115], v[218:221], v[164:167], v[112:115]
	v_mfma_f32_16x16x32_bf16 v[116:119], v[226:229], v[164:167], v[116:119]
	v_mfma_f32_16x16x32_bf16 v[104:107], v[218:221], v[172:175], v[104:107]
	v_mfma_f32_16x16x32_bf16 v[108:111], v[226:229], v[172:175], v[108:111]
	v_mfma_f32_16x16x32_bf16 v[96:99], v[218:221], v[186:189], v[96:99]
	v_mfma_f32_16x16x32_bf16 v[100:103], v[226:229], v[186:189], v[100:103]
	v_mfma_f32_16x16x32_bf16 v[120:123], v[222:225], v[160:163], v[120:123]
	v_mfma_f32_16x16x32_bf16 v[124:127], v[230:233], v[160:163], v[124:127]
	v_mfma_f32_16x16x32_bf16 v[112:115], v[222:225], v[168:171], v[112:115]
	v_mfma_f32_16x16x32_bf16 v[116:119], v[230:233], v[168:171], v[116:119]
	v_mfma_f32_16x16x32_bf16 v[104:107], v[222:225], v[182:185], v[104:107]
	v_mfma_f32_16x16x32_bf16 v[108:111], v[230:233], v[182:185], v[108:111]
	v_mfma_f32_16x16x32_bf16 v[96:99], v[222:225], v[214:217], v[96:99]
	v_mfma_f32_16x16x32_bf16 v[100:103], v[230:233], v[214:217], v[100:103]
	s_add_i32 s31, s31, 2
	s_add_u32 s29, s29, 0x100
	s_addc_u32 s30, s30, 0
	s_cmp_gt_u32 s31, 41
	s_mov_b64 s[12:13], s[2:3]
	s_barrier
	s_cbranch_scc0 .LBB0_1039
	s_lshl_b32 s2, s26, 8
	v_lshl_add_u32 v250, s25, 8, v136
	s_ashr_i32 s3, s2, 31
	v_ashrrev_i32_e32 v251, 31, v250
	v_lshl_add_u64 v[252:253], s[2:3], 1, v[130:131]
	v_lshlrev_b64 v[254:255], 11, v[250:251]
	v_lshl_add_u64 v[254:255], v[252:253], 0, v[254:255]
	v_cvt_pk_bf16_f32 v20, v20, v21
	v_cvt_pk_bf16_f32 v21, v22, v23
	v_cvt_pk_bf16_f32 v22, v28, v29
	v_cvt_pk_bf16_f32 v23, v30, v31
	global_store_dwordx4 v[254:255], v[20:23], off
	v_cvt_pk_bf16_f32 v12, v12, v13
	v_cvt_pk_bf16_f32 v13, v14, v15
	v_cvt_pk_bf16_f32 v20, v80, v81
	v_cvt_pk_bf16_f32 v21, v82, v83
	v_cvt_pk_bf16_f32 v22, v92, v93
	v_cvt_pk_bf16_f32 v23, v94, v95
	global_store_dwordx4 v[254:255], v[20:23], off offset:256
	v_cvt_pk_bf16_f32 v14, v24, v25
	v_cvt_pk_bf16_f32 v15, v26, v27
	v_or_b32_e32 v20, 16, v250
	v_ashrrev_i32_e32 v21, 31, v20
	v_lshlrev_b64 v[20:21], 11, v[20:21]
	v_lshl_add_u64 v[20:21], v[252:253], 0, v[20:21]
	global_store_dwordx4 v[20:21], v[12:15], off
	v_cvt_pk_bf16_f32 v4, v4, v5
	v_cvt_pk_bf16_f32 v5, v6, v7
	v_cvt_pk_bf16_f32 v12, v64, v65
	v_cvt_pk_bf16_f32 v13, v66, v67
	v_cvt_pk_bf16_f32 v14, v84, v85
	v_cvt_pk_bf16_f32 v15, v86, v87
	global_store_dwordx4 v[20:21], v[12:15], off offset:256
	v_cvt_pk_bf16_f32 v6, v16, v17
	v_cvt_pk_bf16_f32 v7, v18, v19
	v_or_b32_e32 v12, 32, v250
	v_ashrrev_i32_e32 v13, 31, v12
	v_lshlrev_b64 v[12:13], 11, v[12:13]
	v_lshl_add_u64 v[12:13], v[252:253], 0, v[12:13]
	global_store_dwordx4 v[12:13], v[4:7], off
	v_cvt_pk_bf16_f32 v0, v0, v1
	v_cvt_pk_bf16_f32 v1, v2, v3
	v_cvt_pk_bf16_f32 v4, v52, v53
	v_cvt_pk_bf16_f32 v5, v54, v55
	v_cvt_pk_bf16_f32 v6, v76, v77
	v_cvt_pk_bf16_f32 v7, v78, v79
	global_store_dwordx4 v[12:13], v[4:7], off offset:256
	v_cvt_pk_bf16_f32 v2, v8, v9
	v_cvt_pk_bf16_f32 v3, v10, v11
	v_or_b32_e32 v4, 48, v250
	v_ashrrev_i32_e32 v5, 31, v4
	v_lshlrev_b64 v[4:5], 11, v[4:5]
	v_lshl_add_u64 v[4:5], v[252:253], 0, v[4:5]
	global_store_dwordx4 v[4:5], v[0:3], off
	s_mov_b64 s[2:3], 0x40000
	s_nop 0
	v_cvt_pk_bf16_f32 v0, v40, v41
	v_cvt_pk_bf16_f32 v1, v42, v43
	v_cvt_pk_bf16_f32 v2, v60, v61
	v_cvt_pk_bf16_f32 v3, v62, v63
	global_store_dwordx4 v[4:5], v[0:3], off offset:256
	v_lshl_add_u64 v[4:5], v[254:255], 0, s[2:3]
	s_mov_b32 s2, 0x40000
	v_add_co_u32_e32 v6, vcc, s2, v254
; __device__ __forceinline__ u32x4 mk4(unsigned a, unsigned b, unsigned c, unsigned d) { return (u32x4){a, b, c, d}; }
; __device__ __forceinline__ f32x4 zero4() { float z = 0.f; asm volatile("" : "+v"(z)); return (f32x4){z, z, z, z}; }
; __device__ __forceinline__ void gemm_phase(const Params& p, int l, const bf16_t* __restrict__ A, const bf16_t* __restrict__ Bt, int M, int N, int K,
;                            int epi, bf16_t* __restrict__ outp, char* smem, int wvi) {
;     ...
;     if (epi == EPI_PLAIN) {
; #pragma unroll
;       for (int ai = 0; ai < 2; ++ai)
; #pragma unroll
;         for (int m = 0; m < 4; ++m) {
;           bf16_t* rp = outp + (size_t)(r0 + ai * GHALF + m * 16) * N + bcol + wc * 32 + fq * 8;
; #pragma unroll
;           for (int bj = 0; bj < 2; ++bj) {
;             const f32x4 v0 = acc[ai][bj][m][0], v1 = acc[ai][bj][m][1];
;             *reinterpret_cast<u32x4*>(rp + bj * GHALF) = mk4(pk2(v0[0], v0[1]), pk2(v0[2], v0[3]), pk2(v1[0], v1[1]), pk2(v1[2], v1[3]));
;           }
;         }
;     ...
;       if (!has_next) break;
; #pragma unroll
;       for (int a = 0; a < 2; ++a)
; #pragma unroll
;         for (int b = 0; b < 2; ++b)
; #pragma unroll
;           for (int m = 0; m < 4; ++m)
; #pragma unroll
;             for (int n = 0; n < 2; ++n) acc[a][b][m][n] = zero4();
;       Lw = Ln; pm = npm; pn = npn; cA = nA; cB = nB;
	v_cvt_pk_bf16_f32 v0, v68, v69
	v_cvt_pk_bf16_f32 v1, v70, v71
	v_cvt_pk_bf16_f32 v2, v88, v89
	v_cvt_pk_bf16_f32 v3, v90, v91
	v_addc_co_u32_e32 v7, vcc, 0, v255, vcc
	global_store_dwordx4 v[6:7], v[0:3], off
	s_mov_b64 s[2:3], 0x48000
	s_nop 0
	v_cvt_pk_bf16_f32 v0, v120, v121
	v_cvt_pk_bf16_f32 v1, v122, v123
	v_cvt_pk_bf16_f32 v2, v124, v125
	v_cvt_pk_bf16_f32 v3, v126, v127
	global_store_dwordx4 v[4:5], v[0:3], off offset:256
	v_lshl_add_u64 v[4:5], v[254:255], 0, s[2:3]
	s_mov_b32 s2, 0x48000
	v_add_co_u32_e32 v6, vcc, s2, v254
	v_cvt_pk_bf16_f32 v0, v48, v49
	v_cvt_pk_bf16_f32 v1, v50, v51
	v_cvt_pk_bf16_f32 v2, v72, v73
	v_cvt_pk_bf16_f32 v3, v74, v75
	v_addc_co_u32_e32 v7, vcc, 0, v255, vcc
	global_store_dwordx4 v[6:7], v[0:3], off
	s_mov_b64 s[2:3], 0x50000
	s_nop 0
	v_cvt_pk_bf16_f32 v0, v112, v113
	v_cvt_pk_bf16_f32 v1, v114, v115
	v_cvt_pk_bf16_f32 v2, v116, v117
	v_cvt_pk_bf16_f32 v3, v118, v119
	global_store_dwordx4 v[4:5], v[0:3], off offset:256
	v_lshl_add_u64 v[4:5], v[254:255], 0, s[2:3]
	s_mov_b32 s2, 0x50000
	v_add_co_u32_e32 v6, vcc, s2, v254
	v_cvt_pk_bf16_f32 v0, v36, v37
	v_cvt_pk_bf16_f32 v1, v38, v39
	v_cvt_pk_bf16_f32 v2, v56, v57
	v_cvt_pk_bf16_f32 v3, v58, v59
	v_addc_co_u32_e32 v7, vcc, 0, v255, vcc
	global_store_dwordx4 v[6:7], v[0:3], off
	s_mov_b64 s[2:3], 0x58000
	s_nop 0
	v_cvt_pk_bf16_f32 v0, v104, v105
	v_cvt_pk_bf16_f32 v1, v106, v107
	v_cvt_pk_bf16_f32 v2, v108, v109
	v_cvt_pk_bf16_f32 v3, v110, v111
	global_store_dwordx4 v[4:5], v[0:3], off offset:256
	v_lshl_add_u64 v[4:5], v[254:255], 0, s[2:3]
	s_mov_b32 s2, 0x58000
	v_add_co_u32_e32 v6, vcc, s2, v254
	v_cvt_pk_bf16_f32 v0, v32, v33
	v_cvt_pk_bf16_f32 v1, v34, v35
	v_cvt_pk_bf16_f32 v2, v44, v45
	v_cvt_pk_bf16_f32 v3, v46, v47
	v_addc_co_u32_e32 v7, vcc, 0, v255, vcc
	global_store_dwordx4 v[6:7], v[0:3], off
	s_mov_b64 s[2:3], -1
	s_and_b64 vcc, exec, s[8:9]
	v_cvt_pk_bf16_f32 v0, v96, v97
	v_cvt_pk_bf16_f32 v1, v98, v99
	v_cvt_pk_bf16_f32 v2, v100, v101
	v_cvt_pk_bf16_f32 v3, v102, v103
	global_store_dwordx4 v[4:5], v[0:3], off offset:256
	s_cbranch_vccz .LBB0_1035
	v_mov_b32_e32 v20, v177
	v_mov_b32_e32 v28, v177
	v_mov_b32_e32 v12, v177
	v_mov_b32_e32 v24, v177
	v_mov_b32_e32 v4, v177
	v_mov_b32_e32 v16, v177
	v_mov_b32_e32 v0, v177
	v_mov_b32_e32 v8, v177
	v_mov_b32_e32 v80, v177
	v_mov_b32_e32 v92, v177
	v_mov_b32_e32 v64, v177
	v_mov_b32_e32 v84, v177
	v_mov_b32_e32 v52, v177
	v_mov_b32_e32 v76, v177
	v_mov_b32_e32 v40, v177
	v_mov_b32_e32 v60, v177
	v_mov_b32_e32 v68, v177
	v_mov_b32_e32 v88, v177
	v_mov_b32_e32 v48, v177
	v_mov_b32_e32 v72, v177
	v_mov_b32_e32 v36, v177
	v_mov_b32_e32 v56, v177
	v_mov_b32_e32 v32, v177
	v_mov_b32_e32 v44, v177
	v_mov_b32_e32 v120, v177
	v_mov_b32_e32 v124, v177
	v_mov_b32_e32 v112, v177
	v_mov_b32_e32 v116, v177
	v_mov_b32_e32 v104, v177
	v_mov_b32_e32 v108, v177
	v_mov_b32_e32 v96, v177
	v_mov_b32_e32 v100, v177
	s_nop 0
	v_mov_b32_e32 v21, v20
	v_mov_b32_e32 v22, v20
	v_mov_b32_e32 v23, v20
	v_mov_b32_e32 v29, v28
	v_mov_b32_e32 v30, v28
	v_mov_b32_e32 v31, v28
	v_mov_b32_e32 v13, v12
	v_mov_b32_e32 v14, v12
	v_mov_b32_e32 v15, v12
	v_mov_b32_e32 v25, v24
	v_mov_b32_e32 v26, v24
	v_mov_b32_e32 v27, v24
	v_mov_b32_e32 v5, v4
	v_mov_b32_e32 v6, v4
	v_mov_b32_e32 v7, v4
	v_mov_b32_e32 v17, v16
	v_mov_b32_e32 v18, v16
	v_mov_b32_e32 v19, v16
	s_nop 0
	v_mov_b32_e32 v1, v0
	v_mov_b32_e32 v2, v0
	v_mov_b32_e32 v3, v0
	v_mov_b32_e32 v9, v8
	v_mov_b32_e32 v10, v8
	v_mov_b32_e32 v11, v8
	v_mov_b32_e32 v81, v80
	v_mov_b32_e32 v82, v80
	v_mov_b32_e32 v83, v80
	v_mov_b32_e32 v93, v92
	v_mov_b32_e32 v94, v92
	v_mov_b32_e32 v95, v92
	v_mov_b32_e32 v65, v64
	v_mov_b32_e32 v66, v64
	v_mov_b32_e32 v67, v64
	v_mov_b32_e32 v85, v84
	v_mov_b32_e32 v86, v84
	v_mov_b32_e32 v87, v84
	s_nop 0
	v_mov_b32_e32 v53, v52
	v_mov_b32_e32 v54, v52
	v_mov_b32_e32 v55, v52
	v_mov_b32_e32 v77, v76
	v_mov_b32_e32 v78, v76
	v_mov_b32_e32 v79, v76
	v_mov_b32_e32 v41, v40
	v_mov_b32_e32 v42, v40
	v_mov_b32_e32 v43, v40
	v_mov_b32_e32 v61, v60
	v_mov_b32_e32 v62, v60
	v_mov_b32_e32 v63, v60
	v_mov_b32_e32 v69, v68
	v_mov_b32_e32 v70, v68
	v_mov_b32_e32 v71, v68
	v_mov_b32_e32 v89, v88
	v_mov_b32_e32 v90, v88
	v_mov_b32_e32 v91, v88
	s_nop 0
	v_mov_b32_e32 v49, v48
	v_mov_b32_e32 v50, v48
	v_mov_b32_e32 v51, v48
	v_mov_b32_e32 v73, v72
	v_mov_b32_e32 v74, v72
	v_mov_b32_e32 v75, v72
	v_mov_b32_e32 v37, v36
	v_mov_b32_e32 v38, v36
	v_mov_b32_e32 v39, v36
	v_mov_b32_e32 v57, v56
	v_mov_b32_e32 v58, v56
	v_mov_b32_e32 v59, v56
	v_mov_b32_e32 v33, v32
	v_mov_b32_e32 v34, v32
	v_mov_b32_e32 v35, v32
	v_mov_b32_e32 v45, v44
	v_mov_b32_e32 v46, v44
	v_mov_b32_e32 v47, v44
	s_nop 0
	v_mov_b32_e32 v121, v120
	v_mov_b32_e32 v122, v120
	v_mov_b32_e32 v123, v120
	v_mov_b32_e32 v125, v124
	v_mov_b32_e32 v126, v124
	v_mov_b32_e32 v127, v124
	v_mov_b32_e32 v113, v112
	v_mov_b32_e32 v114, v112
	v_mov_b32_e32 v115, v112
	v_mov_b32_e32 v117, v116
	v_mov_b32_e32 v118, v116
	v_mov_b32_e32 v119, v116
	v_mov_b32_e32 v105, v104
	v_mov_b32_e32 v106, v104
	v_mov_b32_e32 v107, v104
	v_mov_b32_e32 v109, v108
	v_mov_b32_e32 v110, v108
	v_mov_b32_e32 v111, v108
	s_mov_b64 s[2:3], 0
	v_mov_b32_e32 v97, v96
	v_mov_b32_e32 v98, v96
	v_mov_b32_e32 v99, v96
	v_mov_b32_e32 v101, v100
	v_mov_b32_e32 v102, v100
	v_mov_b32_e32 v103, v100
	s_branch .LBB0_1035

; #define G_STAGE(bufoff, gbase) do { _Pragma("unroll") for (int _i = 0; _i < 2; ++_i) \
;     __builtin_amdgcn_global_load_lds((const unsigned*)((const char*)(gbase) + voff[_i]), (GLAS unsigned*)(lds + (bufoff) + ldsw + _i * 8192), 16, 0, 0); } while (0)
; #define G_LDA(dst, b, h) do { _Pragma("unroll") for (int m = 0; m < 4; ++m) _Pragma("unroll") for (int k = 0; k < 2; ++k) \
;     dst[m][k] = *(const GLAS bf16x8*)(lds + G_SA(b, h) + aoff + m * 2048 + k * 1024); } while (0)
; #define G_LDB(dst, b, h) do { _Pragma("unroll") for (int n = 0; n < 2; ++n) _Pragma("unroll") for (int k = 0; k < 2; ++k) \
;     dst[n][k] = *(const GLAS bf16x8*)(lds + G_SB(b, h) + boff + n * 2048 + k * 1024); } while (0)
; #define G_MMA(ai, bj, At_, Bt_) do { __builtin_amdgcn_s_setprio(1); \
;     _Pragma("unroll") for (int m = 0; m < 4; ++m) _Pragma("unroll") for (int n = 0; n < 2; ++n) _Pragma("unroll") for (int k = 0; k < 2; ++k) \
;       acc[ai][bj][m][n] = __builtin_amdgcn_mfma_f32_16x16x32_bf16(Bt_[n][k], At_[m][k], acc[ai][bj][m][n], 0, 0, 0); \
;     __builtin_amdgcn_s_setprio(0); } while (0)
; #define G_WAIT_L(n) asm volatile("s_waitcnt lgkmcnt(" #n ")" ::: "memory")
; #define G_BAR __builtin_amdgcn_s_barrier()
; #define G_SCHED __builtin_amdgcn_sched_barrier(0)
; __device__ __forceinline__ void gemm_phase(const Params& p, int l, const bf16_t* __restrict__ A, const bf16_t* __restrict__ Bt, int M, int N, int K,
;                            int epi, bf16_t* __restrict__ outp, char* smem, int wvi) {
;     ...
;       for (int t = 0; t < nt; t += 2) {
;         const bool lastt = (t == nt - 2);
;         const char* a1 = cA + (size_t)(t + 1) * kstep;
;         const char* a2 = lastt ? nA : cA + (size_t)(t + 2) * kstep; const char* b2 = lastt ? nB : cB + (size_t)(t + 2) * kstep;
;         const char* a3 = a2 + kstep; const char* b3 = b2 + kstep;
;         G_LDB(B0, 0, 0); G_SCHED; G_LDA(At, 0, 0); G_STAGE(G_SA(1, 1), a1 + hstep);
;         G_WAIT_L(8); G_BAR; G_WAIT_L(0); G_MMA(0, 0, At, B0); G_BAR; G_SCHED;
;         G_LDB(B1, 0, 1); G_STAGE(G_SB(0, 0), b2);
;         G_BAR; G_WAIT_L(0); G_MMA(0, 1, At, B1); G_BAR;
;         G_LDA(At, 0, 1); G_STAGE(G_SA(0, 0), a2);
;         G_BAR; G_WAIT_L(0); G_MMA(1, 0, At, B0); G_BAR; G_SCHED;
.LBB0_1199:
	s_add_u32 s2, s16, 0x100
	s_addc_u32 s3, s17, 0
	s_add_i32 s24, 0, 0x10000
	s_cmp_eq_u32 s23, 12
	s_cselect_b32 s29, s9, s3
	s_cselect_b32 s28, s8, s2
	s_cselect_b32 s15, s7, s22
	s_cselect_b32 s14, s5, s21
	v_lshl_add_u64 v[136:137], s[16:17], 0, v[132:133]
	s_add_i32 m0, s30, 0xc000
	ds_read_b128 v[158:161], v140
	ds_read_b128 v[162:165], v140 offset:1024
	ds_read_b128 v[166:169], v140 offset:2048
	ds_read_b128 v[170:173], v140 offset:3072
	ds_read_b128 v[182:185], v140 offset:4096
	ds_read_b128 v[186:189], v140 offset:5120
	ds_read_b128 v[214:217], v140 offset:6144
	ds_read_b128 v[218:221], v140 offset:7168
	global_load_lds_dwordx4 v[136:137], off
	v_lshl_add_u64 v[136:137], s[16:17], 0, v[134:135]
	s_add_i32 m0, s30, 0xe000
	s_nop 0
	global_load_lds_dwordx4 v[136:137], off
	s_waitcnt lgkmcnt(8)
	s_barrier
	s_waitcnt lgkmcnt(0)
	s_waitcnt lgkmcnt(0)
	v_mfma_f32_16x16x32_bf16 v[120:123], v[142:145], v[158:161], v[120:123]
	v_mfma_f32_16x16x32_bf16 v[124:127], v[150:153], v[158:161], v[124:127]
	v_mfma_f32_16x16x32_bf16 v[104:107], v[142:145], v[166:169], v[104:107]
	v_mfma_f32_16x16x32_bf16 v[108:111], v[150:153], v[166:169], v[108:111]
	v_mfma_f32_16x16x32_bf16 v[88:91], v[142:145], v[182:185], v[88:91]
	v_mfma_f32_16x16x32_bf16 v[92:95], v[150:153], v[182:185], v[92:95]
	v_mfma_f32_16x16x32_bf16 v[72:75], v[142:145], v[214:217], v[72:75]
	v_mfma_f32_16x16x32_bf16 v[76:79], v[150:153], v[214:217], v[76:79]
	v_mfma_f32_16x16x32_bf16 v[120:123], v[146:149], v[162:165], v[120:123]
	v_mfma_f32_16x16x32_bf16 v[124:127], v[154:157], v[162:165], v[124:127]
	v_mfma_f32_16x16x32_bf16 v[104:107], v[146:149], v[170:173], v[104:107]
	v_mfma_f32_16x16x32_bf16 v[108:111], v[154:157], v[170:173], v[108:111]
	v_mfma_f32_16x16x32_bf16 v[88:91], v[146:149], v[186:189], v[88:91]
	v_mfma_f32_16x16x32_bf16 v[92:95], v[154:157], v[186:189], v[92:95]
	v_mfma_f32_16x16x32_bf16 v[72:75], v[146:149], v[218:221], v[72:75]
	v_mfma_f32_16x16x32_bf16 v[76:79], v[154:157], v[218:221], v[76:79]
	s_barrier
	s_add_i32 s25, 0, 0x14000
	v_add_u32_e32 v136, s25, v139
	s_add_i32 s16, s24, s58
	ds_read_b128 v[222:225], v136
	ds_read_b128 v[226:229], v136 offset:1024
	ds_read_b128 v[230:233], v136 offset:2048
	ds_read_b128 v[234:237], v136 offset:3072
	v_lshl_add_u64 v[136:137], s[14:15], 0, v[176:177]
	s_mov_b32 m0, s16
	v_lshl_add_u64 v[174:175], s[14:15], 0, v[128:129]
	global_load_lds_dwordx4 v[136:137], off
	s_add_i32 m0, s16, 0x2000
	s_nop 0
	global_load_lds_dwordx4 v[174:175], off
	s_barrier
	s_waitcnt lgkmcnt(0)
	s_waitcnt lgkmcnt(0)
	v_mfma_f32_16x16x32_bf16 v[112:115], v[222:225], v[158:161], v[112:115]
	v_mfma_f32_16x16x32_bf16 v[116:119], v[230:233], v[158:161], v[116:119]
	v_mfma_f32_16x16x32_bf16 v[96:99], v[222:225], v[166:169], v[96:99]
	v_mfma_f32_16x16x32_bf16 v[100:103], v[230:233], v[166:169], v[100:103]
	v_mfma_f32_16x16x32_bf16 v[80:83], v[222:225], v[182:185], v[80:83]
	v_mfma_f32_16x16x32_bf16 v[84:87], v[230:233], v[182:185], v[84:87]
	v_mfma_f32_16x16x32_bf16 v[64:67], v[222:225], v[214:217], v[64:67]
	v_mfma_f32_16x16x32_bf16 v[68:71], v[230:233], v[214:217], v[68:71]
	v_mfma_f32_16x16x32_bf16 v[112:115], v[226:229], v[162:165], v[112:115]
	v_mfma_f32_16x16x32_bf16 v[116:119], v[234:237], v[162:165], v[116:119]
	v_mfma_f32_16x16x32_bf16 v[96:99], v[226:229], v[170:173], v[96:99]
	v_mfma_f32_16x16x32_bf16 v[100:103], v[234:237], v[170:173], v[100:103]
	v_mfma_f32_16x16x32_bf16 v[80:83], v[226:229], v[186:189], v[80:83]
	v_mfma_f32_16x16x32_bf16 v[84:87], v[234:237], v[186:189], v[84:87]
	v_mfma_f32_16x16x32_bf16 v[64:67], v[226:229], v[218:221], v[64:67]
	v_mfma_f32_16x16x32_bf16 v[68:71], v[234:237], v[218:221], v[68:71]
	s_mov_b32 m0, s30
	v_lshl_add_u64 v[190:191], s[28:29], 0, v[176:177]
	s_barrier
	ds_read_b128 v[158:161], v140 offset:16384
	ds_read_b128 v[162:165], v140 offset:17408
	ds_read_b128 v[166:169], v140 offset:18432
	ds_read_b128 v[170:173], v140 offset:19456
	ds_read_b128 v[182:185], v140 offset:20480
	ds_read_b128 v[186:189], v140 offset:21504
	ds_read_b128 v[214:217], v140 offset:22528
	ds_read_b128 v[218:221], v140 offset:23552
	global_load_lds_dwordx4 v[190:191], off
	v_lshl_add_u64 v[238:239], s[28:29], 0, v[128:129]
	s_mov_b32 m0, s31
	s_nop 0
	global_load_lds_dwordx4 v[238:239], off
	s_waitcnt vmcnt(10)
	s_barrier
	s_waitcnt lgkmcnt(0)
	s_waitcnt lgkmcnt(0)
	v_mfma_f32_16x16x32_bf16 v[56:59], v[142:145], v[158:161], v[56:59]
	v_mfma_f32_16x16x32_bf16 v[60:63], v[150:153], v[158:161], v[60:63]
	v_mfma_f32_16x16x32_bf16 v[40:43], v[142:145], v[166:169], v[40:43]
	v_mfma_f32_16x16x32_bf16 v[44:47], v[150:153], v[166:169], v[44:47]
	v_mfma_f32_16x16x32_bf16 v[24:27], v[142:145], v[182:185], v[24:27]
	v_mfma_f32_16x16x32_bf16 v[28:31], v[150:153], v[182:185], v[28:31]
	v_mfma_f32_16x16x32_bf16 v[8:11], v[142:145], v[214:217], v[8:11]
	v_mfma_f32_16x16x32_bf16 v[12:15], v[150:153], v[214:217], v[12:15]
	v_mfma_f32_16x16x32_bf16 v[56:59], v[146:149], v[162:165], v[56:59]
	v_mfma_f32_16x16x32_bf16 v[60:63], v[154:157], v[162:165], v[60:63]
	v_mfma_f32_16x16x32_bf16 v[40:43], v[146:149], v[170:173], v[40:43]
	v_mfma_f32_16x16x32_bf16 v[44:47], v[154:157], v[170:173], v[44:47]
	v_mfma_f32_16x16x32_bf16 v[24:27], v[146:149], v[186:189], v[24:27]
	v_mfma_f32_16x16x32_bf16 v[28:31], v[154:157], v[186:189], v[28:31]
	v_mfma_f32_16x16x32_bf16 v[8:11], v[146:149], v[218:221], v[8:11]
	v_mfma_f32_16x16x32_bf16 v[12:15], v[154:157], v[218:221], v[12:15]
	s_barrier
; #define G_STAGE(bufoff, gbase) do { _Pragma("unroll") for (int _i = 0; _i < 2; ++_i) \
;     __builtin_amdgcn_global_load_lds((const unsigned*)((const char*)(gbase) + voff[_i]), (GLAS unsigned*)(lds + (bufoff) + ldsw + _i * 8192), 16, 0, 0); } while (0)
; #define G_LDA(dst, b, h) do { _Pragma("unroll") for (int m = 0; m < 4; ++m) _Pragma("unroll") for (int k = 0; k < 2; ++k) \
;     dst[m][k] = *(const GLAS bf16x8*)(lds + G_SA(b, h) + aoff + m * 2048 + k * 1024); } while (0)
; #define G_LDB(dst, b, h) do { _Pragma("unroll") for (int n = 0; n < 2; ++n) _Pragma("unroll") for (int k = 0; k < 2; ++k) \
;     dst[n][k] = *(const GLAS bf16x8*)(lds + G_SB(b, h) + boff + n * 2048 + k * 1024); } while (0)
; #define G_MMA(ai, bj, At_, Bt_) do { __builtin_amdgcn_s_setprio(1); \
;     _Pragma("unroll") for (int m = 0; m < 4; ++m) _Pragma("unroll") for (int n = 0; n < 2; ++n) _Pragma("unroll") for (int k = 0; k < 2; ++k) \
;       acc[ai][bj][m][n] = __builtin_amdgcn_mfma_f32_16x16x32_bf16(Bt_[n][k], At_[m][k], acc[ai][bj][m][n], 0, 0, 0); \
;     __builtin_amdgcn_s_setprio(0); } while (0)
; #define G_WAIT_V(n) asm volatile("s_waitcnt vmcnt(" #n ")" ::: "memory")
; #define G_WAIT_L(n) asm volatile("s_waitcnt lgkmcnt(" #n ")" ::: "memory")
; #define G_BAR __builtin_amdgcn_s_barrier()
; #define G_SCHED __builtin_amdgcn_sched_barrier(0)
; __device__ __forceinline__ void gemm_phase(const Params& p, int l, const bf16_t* __restrict__ A, const bf16_t* __restrict__ Bt, int M, int N, int K,
;                            int epi, bf16_t* __restrict__ outp, char* smem, int wvi) {
;     ...
;         G_STAGE(G_SB(0, 1), b2 + hstep);
;         G_WAIT_V(6); G_BAR; G_MMA(1, 1, At, B1); G_BAR;
;         G_LDB(B0, 1, 0); G_SCHED; G_LDA(At, 1, 0); G_STAGE(G_SA(0, 1), a2 + hstep);
;         G_WAIT_L(8); G_BAR; G_WAIT_L(0); G_MMA(0, 0, At, B0); G_BAR; G_SCHED;
;         G_LDB(B1, 1, 1); G_STAGE(G_SB(1, 0), b3);
;         G_BAR; G_WAIT_L(0); G_MMA(0, 1, At, B1); G_BAR;
;         G_LDA(At, 1, 1); G_STAGE(G_SA(1, 0), a3);
;         G_BAR; G_WAIT_L(0); G_MMA(1, 0, At, B0); G_BAR; G_SCHED;
	s_add_u32 s16, s14, 0x40000
	s_addc_u32 s17, s15, 0
	s_add_i32 s24, s25, s58
	v_lshl_add_u64 v[142:143], s[16:17], 0, v[176:177]
	s_mov_b32 m0, s24
	s_nop 0
	global_load_lds_dwordx4 v[142:143], off
	v_lshl_add_u64 v[142:143], s[16:17], 0, v[128:129]
	s_add_i32 m0, s24, 0x2000
	s_nop 0
	global_load_lds_dwordx4 v[142:143], off
	v_add_u32_e32 v141, 0x18000, v139
	ds_read_b128 v[142:145], v141
	ds_read_b128 v[146:149], v141 offset:1024
	ds_read_b128 v[150:153], v141 offset:2048
	ds_read_b128 v[154:157], v141 offset:3072
	s_waitcnt vmcnt(10)
	s_barrier
	v_mfma_f32_16x16x32_bf16 v[48:51], v[222:225], v[158:161], v[48:51]
	v_mfma_f32_16x16x32_bf16 v[52:55], v[230:233], v[158:161], v[52:55]
	v_mfma_f32_16x16x32_bf16 v[32:35], v[222:225], v[166:169], v[32:35]
	v_mfma_f32_16x16x32_bf16 v[36:39], v[230:233], v[166:169], v[36:39]
	v_mfma_f32_16x16x32_bf16 v[16:19], v[222:225], v[182:185], v[16:19]
	v_mfma_f32_16x16x32_bf16 v[20:23], v[230:233], v[182:185], v[20:23]
	v_mfma_f32_16x16x32_bf16 v[0:3], v[222:225], v[214:217], v[0:3]
	v_mfma_f32_16x16x32_bf16 v[4:7], v[230:233], v[214:217], v[4:7]
	v_mfma_f32_16x16x32_bf16 v[48:51], v[226:229], v[162:165], v[48:51]
	v_mfma_f32_16x16x32_bf16 v[52:55], v[234:237], v[162:165], v[52:55]
	v_mfma_f32_16x16x32_bf16 v[32:35], v[226:229], v[170:173], v[32:35]
	v_mfma_f32_16x16x32_bf16 v[36:39], v[234:237], v[170:173], v[36:39]
	v_mfma_f32_16x16x32_bf16 v[16:19], v[226:229], v[186:189], v[16:19]
	v_mfma_f32_16x16x32_bf16 v[20:23], v[234:237], v[186:189], v[20:23]
	v_mfma_f32_16x16x32_bf16 v[0:3], v[226:229], v[218:221], v[0:3]
	v_mfma_f32_16x16x32_bf16 v[4:7], v[234:237], v[218:221], v[4:7]
	s_add_i32 s24, 0, 0x18000
	s_barrier
	s_add_u32 s16, s28, 0x40000
	s_addc_u32 s17, s29, 0
	s_mov_b32 m0, s55
	v_lshl_add_u64 v[222:223], s[16:17], 0, v[176:177]
	ds_read_b128 v[158:161], v140 offset:32768
	ds_read_b128 v[162:165], v140 offset:33792
	ds_read_b128 v[166:169], v140 offset:34816
	ds_read_b128 v[170:173], v140 offset:35840
	ds_read_b128 v[182:185], v140 offset:36864
	ds_read_b128 v[186:189], v140 offset:37888
	ds_read_b128 v[214:217], v140 offset:38912
	ds_read_b128 v[218:221], v140 offset:39936
	global_load_lds_dwordx4 v[222:223], off
	v_lshl_add_u64 v[222:223], s[16:17], 0, v[128:129]
	s_mov_b32 m0, s88
	s_nop 0
	global_load_lds_dwordx4 v[222:223], off
	s_waitcnt lgkmcnt(8)
	s_waitcnt vmcnt(10)
	s_barrier
	s_waitcnt lgkmcnt(0)
	s_waitcnt lgkmcnt(0)
	v_mfma_f32_16x16x32_bf16 v[120:123], v[142:145], v[158:161], v[120:123]
	v_mfma_f32_16x16x32_bf16 v[124:127], v[150:153], v[158:161], v[124:127]
	v_mfma_f32_16x16x32_bf16 v[104:107], v[142:145], v[166:169], v[104:107]
	v_mfma_f32_16x16x32_bf16 v[108:111], v[150:153], v[166:169], v[108:111]
	v_mfma_f32_16x16x32_bf16 v[88:91], v[142:145], v[182:185], v[88:91]
	v_mfma_f32_16x16x32_bf16 v[92:95], v[150:153], v[182:185], v[92:95]
	v_mfma_f32_16x16x32_bf16 v[72:75], v[142:145], v[214:217], v[72:75]
	v_mfma_f32_16x16x32_bf16 v[76:79], v[150:153], v[214:217], v[76:79]
	v_mfma_f32_16x16x32_bf16 v[120:123], v[146:149], v[162:165], v[120:123]
	v_mfma_f32_16x16x32_bf16 v[124:127], v[154:157], v[162:165], v[124:127]
	v_mfma_f32_16x16x32_bf16 v[104:107], v[146:149], v[170:173], v[104:107]
	v_mfma_f32_16x16x32_bf16 v[108:111], v[154:157], v[170:173], v[108:111]
	v_mfma_f32_16x16x32_bf16 v[88:91], v[146:149], v[186:189], v[88:91]
	v_mfma_f32_16x16x32_bf16 v[92:95], v[154:157], v[186:189], v[92:95]
	v_mfma_f32_16x16x32_bf16 v[72:75], v[146:149], v[218:221], v[72:75]
	v_mfma_f32_16x16x32_bf16 v[76:79], v[154:157], v[218:221], v[76:79]
	s_barrier
	s_add_i32 s16, 0, 0x1c000
	s_add_i32 s17, s24, s58
	v_add_u32_e32 v141, s16, v139
	v_lshl_add_u64 v[136:137], v[136:137], 0, s[64:65]
	s_mov_b32 m0, s17
	ds_read_b128 v[222:225], v141
	ds_read_b128 v[226:229], v141 offset:1024
	ds_read_b128 v[230:233], v141 offset:2048
	ds_read_b128 v[234:237], v141 offset:3072
	global_load_lds_dwordx4 v[136:137], off
	v_lshl_add_u64 v[136:137], v[174:175], 0, s[64:65]
	s_add_i32 m0, s17, 0x2000
	s_nop 0
	global_load_lds_dwordx4 v[136:137], off
	s_waitcnt vmcnt(10)
	s_barrier
	s_waitcnt lgkmcnt(0)
	s_waitcnt lgkmcnt(0)
	v_mfma_f32_16x16x32_bf16 v[112:115], v[222:225], v[158:161], v[112:115]
	v_mfma_f32_16x16x32_bf16 v[116:119], v[230:233], v[158:161], v[116:119]
	v_mfma_f32_16x16x32_bf16 v[96:99], v[222:225], v[166:169], v[96:99]
	v_mfma_f32_16x16x32_bf16 v[100:103], v[230:233], v[166:169], v[100:103]
	v_mfma_f32_16x16x32_bf16 v[80:83], v[222:225], v[182:185], v[80:83]
	v_mfma_f32_16x16x32_bf16 v[84:87], v[230:233], v[182:185], v[84:87]
	v_mfma_f32_16x16x32_bf16 v[64:67], v[222:225], v[214:217], v[64:67]
	v_mfma_f32_16x16x32_bf16 v[68:71], v[230:233], v[214:217], v[68:71]
	v_mfma_f32_16x16x32_bf16 v[112:115], v[226:229], v[162:165], v[112:115]
	v_mfma_f32_16x16x32_bf16 v[116:119], v[234:237], v[162:165], v[116:119]
	v_mfma_f32_16x16x32_bf16 v[96:99], v[226:229], v[170:173], v[96:99]
	v_mfma_f32_16x16x32_bf16 v[100:103], v[234:237], v[170:173], v[100:103]
	v_mfma_f32_16x16x32_bf16 v[80:83], v[226:229], v[186:189], v[80:83]
	v_mfma_f32_16x16x32_bf16 v[84:87], v[234:237], v[186:189], v[84:87]
	v_mfma_f32_16x16x32_bf16 v[64:67], v[226:229], v[218:221], v[64:67]
	v_mfma_f32_16x16x32_bf16 v[68:71], v[234:237], v[218:221], v[68:71]
	s_mov_b32 m0, s89
	v_lshl_add_u64 v[136:137], v[190:191], 0, s[64:65]
	s_barrier
	ds_read_b128 v[158:161], v140 offset:49152
	ds_read_b128 v[162:165], v140 offset:50176
	ds_read_b128 v[166:169], v140 offset:51200
	ds_read_b128 v[170:173], v140 offset:52224
	ds_read_b128 v[182:185], v140 offset:53248
	ds_read_b128 v[186:189], v140 offset:54272
	ds_read_b128 v[214:217], v140 offset:55296
	ds_read_b128 v[218:221], v140 offset:56320
	global_load_lds_dwordx4 v[136:137], off
	v_lshl_add_u64 v[136:137], v[238:239], 0, s[64:65]
	s_mov_b32 m0, s92
	s_nop 0
	global_load_lds_dwordx4 v[136:137], off
	s_waitcnt vmcnt(10)
	s_barrier
; __device__ __forceinline__ u32x4 mk4(unsigned a, unsigned b, unsigned c, unsigned d) { return (u32x4){a, b, c, d}; }
; __device__ __forceinline__ float silu_f(float x) { return x * __builtin_amdgcn_rcpf(1.f + __expf(-x)); }
; #define G_STAGE(bufoff, gbase) do { _Pragma("unroll") for (int _i = 0; _i < 2; ++_i) \
;     __builtin_amdgcn_global_load_lds((const unsigned*)((const char*)(gbase) + voff[_i]), (GLAS unsigned*)(lds + (bufoff) + ldsw + _i * 8192), 16, 0, 0); } while (0)
; #define G_MMA(ai, bj, At_, Bt_) do { __builtin_amdgcn_s_setprio(1); \
;     _Pragma("unroll") for (int m = 0; m < 4; ++m) _Pragma("unroll") for (int n = 0; n < 2; ++n) _Pragma("unroll") for (int k = 0; k < 2; ++k) \
;       acc[ai][bj][m][n] = __builtin_amdgcn_mfma_f32_16x16x32_bf16(Bt_[n][k], At_[m][k], acc[ai][bj][m][n], 0, 0, 0); \
;     __builtin_amdgcn_s_setprio(0); } while (0)
; #define G_WAIT_V(n) asm volatile("s_waitcnt vmcnt(" #n ")" ::: "memory")
; #define G_WAIT_L(n) asm volatile("s_waitcnt lgkmcnt(" #n ")" ::: "memory")
; #define G_BAR __builtin_amdgcn_s_barrier()
; #define G_SCHED __builtin_amdgcn_sched_barrier(0)
; __device__ __forceinline__ void gemm_phase(const Params& p, int l, const bf16_t* __restrict__ A, const bf16_t* __restrict__ Bt, int M, int N, int K,
;                            int epi, bf16_t* __restrict__ outp, char* smem, int wvi) {
;     ...
;         G_BAR; G_WAIT_L(0); G_MMA(1, 0, At, B0); G_BAR; G_SCHED;
;         G_STAGE(G_SB(1, 1), b3 + hstep);
;         G_WAIT_V(6); G_BAR; G_MMA(1, 1, At, B1); G_BAR;
;     ...
;     } else if (epi == EPI_SWIGLU) {
; #pragma unroll
;       for (int ai = 0; ai < 2; ++ai)
; #pragma unroll
;         for (int m = 0; m < 4; ++m) {
;           bf16_t* rp = outp + (size_t)(r0 + ai * GHALF + m * 16) * DFF + pn * 128 + wc * 32 + fq * 8;
;           unsigned pk[4];
; #pragma unroll
;           for (int bj = 0; bj < 2; ++bj) {
;             const f32x4 g = acc[ai][bj][m][0], u = acc[ai][bj][m][1];
;             const float o0 = silu_f(g[0]) * u[0], o1 = silu_f(g[1]) * u[1], o2 = silu_f(g[2]) * u[2], o3 = silu_f(g[3]) * u[3];
;             pk[2 * bj] = pk2(o0, o1); pk[2 * bj + 1] = pk2(o2, o3);
;           }
;           *reinterpret_cast<u32x4*>(rp) = mk4(pk[0], pk[1], pk[2], pk[3]);
;         }
	s_waitcnt lgkmcnt(0)
	s_waitcnt lgkmcnt(0)
	v_mfma_f32_16x16x32_bf16 v[56:59], v[142:145], v[158:161], v[56:59]
	v_mfma_f32_16x16x32_bf16 v[60:63], v[150:153], v[158:161], v[60:63]
	v_mfma_f32_16x16x32_bf16 v[40:43], v[142:145], v[166:169], v[40:43]
	v_mfma_f32_16x16x32_bf16 v[44:47], v[150:153], v[166:169], v[44:47]
	v_mfma_f32_16x16x32_bf16 v[24:27], v[142:145], v[182:185], v[24:27]
	v_mfma_f32_16x16x32_bf16 v[28:31], v[150:153], v[182:185], v[28:31]
	v_mfma_f32_16x16x32_bf16 v[8:11], v[142:145], v[214:217], v[8:11]
	v_mfma_f32_16x16x32_bf16 v[12:15], v[150:153], v[214:217], v[12:15]
	v_mfma_f32_16x16x32_bf16 v[56:59], v[146:149], v[162:165], v[56:59]
	v_mfma_f32_16x16x32_bf16 v[60:63], v[154:157], v[162:165], v[60:63]
	v_mfma_f32_16x16x32_bf16 v[40:43], v[146:149], v[170:173], v[40:43]
	v_mfma_f32_16x16x32_bf16 v[44:47], v[154:157], v[170:173], v[44:47]
	v_mfma_f32_16x16x32_bf16 v[24:27], v[146:149], v[186:189], v[24:27]
	v_mfma_f32_16x16x32_bf16 v[28:31], v[154:157], v[186:189], v[28:31]
	v_mfma_f32_16x16x32_bf16 v[8:11], v[146:149], v[218:221], v[8:11]
	v_mfma_f32_16x16x32_bf16 v[12:15], v[154:157], v[218:221], v[12:15]
	s_barrier
	s_add_u32 s14, s14, 0x40080
	s_addc_u32 s15, s15, 0
	s_add_i32 s16, s16, s58
	v_lshl_add_u64 v[136:137], s[14:15], 0, v[176:177]
	s_mov_b32 m0, s16
	s_nop 0
	global_load_lds_dwordx4 v[136:137], off
	v_lshl_add_u64 v[136:137], s[14:15], 0, v[128:129]
	s_add_i32 m0, s16, 0x2000
	s_nop 0
	global_load_lds_dwordx4 v[136:137], off
	v_add_u32_e32 v136, 0x10000, v139
	ds_read_b128 v[142:145], v136
	ds_read_b128 v[146:149], v136 offset:1024
	ds_read_b128 v[150:153], v136 offset:2048
	ds_read_b128 v[154:157], v136 offset:3072
	s_waitcnt vmcnt(6)
	s_barrier
	v_mfma_f32_16x16x32_bf16 v[48:51], v[222:225], v[158:161], v[48:51]
	v_mfma_f32_16x16x32_bf16 v[52:55], v[230:233], v[158:161], v[52:55]
	v_mfma_f32_16x16x32_bf16 v[32:35], v[222:225], v[166:169], v[32:35]
	v_mfma_f32_16x16x32_bf16 v[36:39], v[230:233], v[166:169], v[36:39]
	v_mfma_f32_16x16x32_bf16 v[16:19], v[222:225], v[182:185], v[16:19]
	v_mfma_f32_16x16x32_bf16 v[20:23], v[230:233], v[182:185], v[20:23]
	v_mfma_f32_16x16x32_bf16 v[0:3], v[222:225], v[214:217], v[0:3]
	v_mfma_f32_16x16x32_bf16 v[4:7], v[230:233], v[214:217], v[4:7]
	v_mfma_f32_16x16x32_bf16 v[48:51], v[226:229], v[162:165], v[48:51]
	v_mfma_f32_16x16x32_bf16 v[52:55], v[234:237], v[162:165], v[52:55]
	v_mfma_f32_16x16x32_bf16 v[32:35], v[226:229], v[170:173], v[32:35]
	v_mfma_f32_16x16x32_bf16 v[36:39], v[234:237], v[170:173], v[36:39]
	v_mfma_f32_16x16x32_bf16 v[16:19], v[226:229], v[186:189], v[16:19]
	v_mfma_f32_16x16x32_bf16 v[20:23], v[234:237], v[186:189], v[20:23]
	v_mfma_f32_16x16x32_bf16 v[0:3], v[226:229], v[218:221], v[0:3]
	v_mfma_f32_16x16x32_bf16 v[4:7], v[234:237], v[218:221], v[4:7]
	s_add_i32 s23, s23, 2
	s_add_u32 s21, s21, 0x100
	s_addc_u32 s22, s22, 0
	s_cmp_gt_u32 s23, 13
	s_mov_b64 s[16:17], s[2:3]
	s_barrier
	s_cbranch_scc0 .LBB0_1199
	v_mul_f32_e32 v252, 0xbfb8aa3b, v120
	v_mul_f32_e32 v253, 0xbfb8aa3b, v121
	v_exp_f32_e32 v252, v252
	v_exp_f32_e32 v253, v253
	v_lshl_add_u32 v141, s0, 8, v138
	s_lshl_b32 s0, s1, 7
	v_add_f32_e32 v252, 1.0, v252
	v_add_f32_e32 v253, 1.0, v253
	v_rcp_f32_e32 v252, v252
	v_rcp_f32_e32 v253, v253
	s_ashr_i32 s1, s0, 31
	v_lshl_add_u64 v[136:137], s[0:1], 1, v[130:131]
	s_movk_i32 s2, 0x1600
	v_pk_mul_f32 v[120:121], v[120:121], v[252:253]
	s_and_b64 vcc, exec, s[12:13]
	v_pk_mul_f32 v[120:121], v[124:125], v[120:121]
	v_mul_f32_e32 v124, 0xbfb8aa3b, v122
	v_mul_f32_e32 v125, 0xbfb8aa3b, v123
	v_exp_f32_e32 v124, v124
	v_exp_f32_e32 v125, v125
	v_cvt_pk_bf16_f32 v120, v120, v121
	v_add_f32_e32 v124, 1.0, v124
	v_add_f32_e32 v125, 1.0, v125
	v_rcp_f32_e32 v124, v124
	v_rcp_f32_e32 v125, v125
	s_nop 0
	v_pk_mul_f32 v[122:123], v[122:123], v[124:125]
	s_nop 0
	v_pk_mul_f32 v[122:123], v[126:127], v[122:123]
	s_nop 0
	v_cvt_pk_bf16_f32 v121, v122, v123
	v_mul_f32_e32 v122, 0xbfb8aa3b, v112
	v_mul_f32_e32 v123, 0xbfb8aa3b, v113
	v_exp_f32_e32 v122, v122
	v_exp_f32_e32 v123, v123
	v_add_f32_e32 v122, 1.0, v122
	v_add_f32_e32 v123, 1.0, v123
	v_rcp_f32_e32 v122, v122
	v_rcp_f32_e32 v123, v123
	s_nop 0
	v_pk_mul_f32 v[112:113], v[112:113], v[122:123]
	s_nop 0
	v_pk_mul_f32 v[112:113], v[116:117], v[112:113]
	v_mul_f32_e32 v116, 0xbfb8aa3b, v114
	v_mul_f32_e32 v117, 0xbfb8aa3b, v115
	v_exp_f32_e32 v116, v116
	v_exp_f32_e32 v117, v117
	v_cvt_pk_bf16_f32 v122, v112, v113
	v_mad_i64_i32 v[112:113], s[0:1], v141, s2, v[136:137]
	v_add_f32_e32 v116, 1.0, v116
	v_add_f32_e32 v117, 1.0, v117
	v_rcp_f32_e32 v116, v116
	v_rcp_f32_e32 v117, v117
	s_nop 0
	v_pk_mul_f32 v[114:115], v[114:115], v[116:117]
	s_nop 0
	v_pk_mul_f32 v[114:115], v[118:119], v[114:115]
	s_nop 0
	v_cvt_pk_bf16_f32 v123, v114, v115
	global_store_dwordx4 v[112:113], v[120:123], off
	v_mul_f32_e32 v112, 0xbfb8aa3b, v104
	v_mul_f32_e32 v113, 0xbfb8aa3b, v105
	v_exp_f32_e32 v112, v112
	v_exp_f32_e32 v113, v113
	v_or_b32_e32 v114, 16, v141
	v_add_f32_e32 v112, 1.0, v112
	v_add_f32_e32 v113, 1.0, v113
	v_rcp_f32_e32 v112, v112
	v_rcp_f32_e32 v113, v113
	s_nop 0
	v_pk_mul_f32 v[104:105], v[104:105], v[112:113]
	s_nop 0
	v_pk_mul_f32 v[104:105], v[108:109], v[104:105]
	v_mul_f32_e32 v108, 0xbfb8aa3b, v106
	v_mul_f32_e32 v109, 0xbfb8aa3b, v107
	v_exp_f32_e32 v108, v108
	v_exp_f32_e32 v109, v109
	v_cvt_pk_bf16_f32 v104, v104, v105
	v_add_f32_e32 v108, 1.0, v108
	v_add_f32_e32 v109, 1.0, v109
	v_rcp_f32_e32 v108, v108
	v_rcp_f32_e32 v109, v109
	s_nop 0
	v_pk_mul_f32 v[106:107], v[106:107], v[108:109]
	s_nop 0
	v_pk_mul_f32 v[106:107], v[110:111], v[106:107]
	s_nop 0
	v_cvt_pk_bf16_f32 v105, v106, v107
; __device__ __forceinline__ u32x4 mk4(unsigned a, unsigned b, unsigned c, unsigned d) { return (u32x4){a, b, c, d}; }
; __device__ __forceinline__ float silu_f(float x) { return x * __builtin_amdgcn_rcpf(1.f + __expf(-x)); }
; __device__ __forceinline__ void gemm_phase(const Params& p, int l, const bf16_t* __restrict__ A, const bf16_t* __restrict__ Bt, int M, int N, int K,
;                            int epi, bf16_t* __restrict__ outp, char* smem, int wvi) {
;     ...
;       for (int ai = 0; ai < 2; ++ai)
; #pragma unroll
;         for (int m = 0; m < 4; ++m) {
;           bf16_t* rp = outp + (size_t)(r0 + ai * GHALF + m * 16) * DFF + pn * 128 + wc * 32 + fq * 8;
;           unsigned pk[4];
; #pragma unroll
;           for (int bj = 0; bj < 2; ++bj) {
;             const f32x4 g = acc[ai][bj][m][0], u = acc[ai][bj][m][1];
;             const float o0 = silu_f(g[0]) * u[0], o1 = silu_f(g[1]) * u[1], o2 = silu_f(g[2]) * u[2], o3 = silu_f(g[3]) * u[3];
;             pk[2 * bj] = pk2(o0, o1); pk[2 * bj + 1] = pk2(o2, o3);
;           }
;           *reinterpret_cast<u32x4*>(rp) = mk4(pk[0], pk[1], pk[2], pk[3]);
	v_mul_f32_e32 v106, 0xbfb8aa3b, v96
	v_mul_f32_e32 v107, 0xbfb8aa3b, v97
	v_exp_f32_e32 v106, v106
	v_exp_f32_e32 v107, v107
	v_add_f32_e32 v106, 1.0, v106
	v_add_f32_e32 v107, 1.0, v107
	v_rcp_f32_e32 v106, v106
	v_rcp_f32_e32 v107, v107
	s_nop 0
	v_pk_mul_f32 v[96:97], v[96:97], v[106:107]
	s_nop 0
	v_pk_mul_f32 v[96:97], v[100:101], v[96:97]
	v_mul_f32_e32 v100, 0xbfb8aa3b, v98
	v_mul_f32_e32 v101, 0xbfb8aa3b, v99
	v_exp_f32_e32 v100, v100
	v_exp_f32_e32 v101, v101
	v_cvt_pk_bf16_f32 v106, v96, v97
	v_mad_i64_i32 v[96:97], s[0:1], v114, s2, v[136:137]
	v_add_f32_e32 v100, 1.0, v100
	v_add_f32_e32 v101, 1.0, v101
	v_rcp_f32_e32 v100, v100
	v_rcp_f32_e32 v101, v101
	s_nop 0
	v_pk_mul_f32 v[98:99], v[98:99], v[100:101]
	s_nop 0
	v_pk_mul_f32 v[98:99], v[102:103], v[98:99]
	s_nop 0
	v_cvt_pk_bf16_f32 v107, v98, v99
	global_store_dwordx4 v[96:97], v[104:107], off
	v_mul_f32_e32 v96, 0xbfb8aa3b, v88
	v_mul_f32_e32 v97, 0xbfb8aa3b, v89
	v_exp_f32_e32 v96, v96
	v_exp_f32_e32 v97, v97
	v_or_b32_e32 v98, 32, v141
	v_add_f32_e32 v96, 1.0, v96
	v_add_f32_e32 v97, 1.0, v97
	v_rcp_f32_e32 v96, v96
	v_rcp_f32_e32 v97, v97
	s_nop 0
	v_pk_mul_f32 v[88:89], v[88:89], v[96:97]
	s_nop 0
	v_pk_mul_f32 v[88:89], v[92:93], v[88:89]
	v_mul_f32_e32 v92, 0xbfb8aa3b, v90
	v_mul_f32_e32 v93, 0xbfb8aa3b, v91
	v_exp_f32_e32 v92, v92
	v_exp_f32_e32 v93, v93
	v_cvt_pk_bf16_f32 v88, v88, v89
	v_add_f32_e32 v92, 1.0, v92
	v_add_f32_e32 v93, 1.0, v93
	v_rcp_f32_e32 v92, v92
	v_rcp_f32_e32 v93, v93
	s_nop 0
	v_pk_mul_f32 v[90:91], v[90:91], v[92:93]
	s_nop 0
	v_pk_mul_f32 v[90:91], v[94:95], v[90:91]
	s_nop 0
	v_cvt_pk_bf16_f32 v89, v90, v91
	v_mul_f32_e32 v90, 0xbfb8aa3b, v80
	v_mul_f32_e32 v91, 0xbfb8aa3b, v81
	v_exp_f32_e32 v90, v90
	v_exp_f32_e32 v91, v91
	v_add_f32_e32 v90, 1.0, v90
	v_add_f32_e32 v91, 1.0, v91
	v_rcp_f32_e32 v90, v90
	v_rcp_f32_e32 v91, v91
	s_nop 0
	v_pk_mul_f32 v[80:81], v[80:81], v[90:91]
	s_nop 0
	v_pk_mul_f32 v[80:81], v[84:85], v[80:81]
	v_mul_f32_e32 v84, 0xbfb8aa3b, v82
	v_mul_f32_e32 v85, 0xbfb8aa3b, v83
	v_exp_f32_e32 v84, v84
	v_exp_f32_e32 v85, v85
	v_cvt_pk_bf16_f32 v90, v80, v81
	v_mad_i64_i32 v[80:81], s[0:1], v98, s2, v[136:137]
	v_add_f32_e32 v84, 1.0, v84
	v_add_f32_e32 v85, 1.0, v85
	v_rcp_f32_e32 v84, v84
	v_rcp_f32_e32 v85, v85
	s_nop 0
	v_pk_mul_f32 v[82:83], v[82:83], v[84:85]
	s_nop 0
	v_pk_mul_f32 v[82:83], v[86:87], v[82:83]
	s_nop 0
	v_cvt_pk_bf16_f32 v91, v82, v83
	global_store_dwordx4 v[80:81], v[88:91], off
	v_mul_f32_e32 v80, 0xbfb8aa3b, v72
	v_mul_f32_e32 v81, 0xbfb8aa3b, v73
	v_exp_f32_e32 v80, v80
	v_exp_f32_e32 v81, v81
	v_or_b32_e32 v82, 48, v141
	v_add_f32_e32 v80, 1.0, v80
	v_add_f32_e32 v81, 1.0, v81
	v_rcp_f32_e32 v80, v80
	v_rcp_f32_e32 v81, v81
	s_nop 0
	v_pk_mul_f32 v[72:73], v[72:73], v[80:81]
	s_nop 0
	v_pk_mul_f32 v[72:73], v[76:77], v[72:73]
	v_mul_f32_e32 v76, 0xbfb8aa3b, v74
	v_mul_f32_e32 v77, 0xbfb8aa3b, v75
	v_exp_f32_e32 v76, v76
	v_exp_f32_e32 v77, v77
	v_cvt_pk_bf16_f32 v72, v72, v73
	v_add_f32_e32 v76, 1.0, v76
	v_add_f32_e32 v77, 1.0, v77
	v_rcp_f32_e32 v76, v76
	v_rcp_f32_e32 v77, v77
	s_nop 0
	v_pk_mul_f32 v[74:75], v[74:75], v[76:77]
	s_nop 0
	v_pk_mul_f32 v[74:75], v[78:79], v[74:75]
	s_nop 0
	v_cvt_pk_bf16_f32 v73, v74, v75
	v_mul_f32_e32 v74, 0xbfb8aa3b, v64
	v_mul_f32_e32 v75, 0xbfb8aa3b, v65
	v_exp_f32_e32 v74, v74
	v_exp_f32_e32 v75, v75
	v_add_f32_e32 v74, 1.0, v74
	v_add_f32_e32 v75, 1.0, v75
	v_rcp_f32_e32 v74, v74
	v_rcp_f32_e32 v75, v75
	s_nop 0
	v_pk_mul_f32 v[64:65], v[64:65], v[74:75]
	s_nop 0
	v_pk_mul_f32 v[64:65], v[68:69], v[64:65]
	v_mul_f32_e32 v68, 0xbfb8aa3b, v66
	v_mul_f32_e32 v69, 0xbfb8aa3b, v67
	v_exp_f32_e32 v68, v68
	v_exp_f32_e32 v69, v69
	v_cvt_pk_bf16_f32 v74, v64, v65
	v_mad_i64_i32 v[64:65], s[0:1], v82, s2, v[136:137]
	v_add_f32_e32 v68, 1.0, v68
	v_add_f32_e32 v69, 1.0, v69
	v_rcp_f32_e32 v68, v68
	v_rcp_f32_e32 v69, v69
	s_nop 0
	v_pk_mul_f32 v[66:67], v[66:67], v[68:69]
	s_nop 0
	v_pk_mul_f32 v[66:67], v[70:71], v[66:67]
	s_nop 0
	v_cvt_pk_bf16_f32 v75, v66, v67
	global_store_dwordx4 v[64:65], v[72:75], off
	v_mul_f32_e32 v64, 0xbfb8aa3b, v56
	v_mul_f32_e32 v65, 0xbfb8aa3b, v57
	v_exp_f32_e32 v64, v64
	v_exp_f32_e32 v65, v65
	v_add_u32_e32 v66, 0x80, v141
	v_add_f32_e32 v64, 1.0, v64
	v_add_f32_e32 v65, 1.0, v65
	v_rcp_f32_e32 v64, v64
	v_rcp_f32_e32 v65, v65
	s_nop 0
	v_pk_mul_f32 v[56:57], v[56:57], v[64:65]
	s_nop 0
	v_pk_mul_f32 v[56:57], v[60:61], v[56:57]
	v_mul_f32_e32 v60, 0xbfb8aa3b, v58
	v_mul_f32_e32 v61, 0xbfb8aa3b, v59
	v_exp_f32_e32 v60, v60
	v_exp_f32_e32 v61, v61
	v_cvt_pk_bf16_f32 v56, v56, v57
	v_add_f32_e32 v60, 1.0, v60
	v_add_f32_e32 v61, 1.0, v61
	v_rcp_f32_e32 v60, v60
	v_rcp_f32_e32 v61, v61
	s_nop 0
	v_pk_mul_f32 v[58:59], v[58:59], v[60:61]
	s_nop 0
	v_pk_mul_f32 v[58:59], v[62:63], v[58:59]
	s_nop 0
	v_cvt_pk_bf16_f32 v57, v58, v59
	v_mul_f32_e32 v58, 0xbfb8aa3b, v48
	v_mul_f32_e32 v59, 0xbfb8aa3b, v49
	v_exp_f32_e32 v58, v58
	v_exp_f32_e32 v59, v59
	v_add_f32_e32 v58, 1.0, v58
	v_add_f32_e32 v59, 1.0, v59
	v_rcp_f32_e32 v58, v58
	v_rcp_f32_e32 v59, v59
	s_nop 0
	v_pk_mul_f32 v[48:49], v[48:49], v[58:59]
	s_nop 0
	v_pk_mul_f32 v[48:49], v[52:53], v[48:49]
	v_mul_f32_e32 v52, 0xbfb8aa3b, v50
	v_mul_f32_e32 v53, 0xbfb8aa3b, v51
	v_exp_f32_e32 v52, v52
	v_exp_f32_e32 v53, v53
	v_cvt_pk_bf16_f32 v58, v48, v49
	v_mad_i64_i32 v[48:49], s[0:1], v66, s2, v[136:137]
	v_add_f32_e32 v52, 1.0, v52
	v_add_f32_e32 v53, 1.0, v53
	v_rcp_f32_e32 v52, v52
	v_rcp_f32_e32 v53, v53
	s_nop 0
	v_pk_mul_f32 v[50:51], v[50:51], v[52:53]
	s_nop 0
	v_pk_mul_f32 v[50:51], v[54:55], v[50:51]
	s_nop 0
	v_cvt_pk_bf16_f32 v59, v50, v51
; __device__ __forceinline__ u32x4 mk4(unsigned a, unsigned b, unsigned c, unsigned d) { return (u32x4){a, b, c, d}; }
; __device__ __forceinline__ float silu_f(float x) { return x * __builtin_amdgcn_rcpf(1.f + __expf(-x)); }
; __device__ __forceinline__ void gemm_phase(const Params& p, int l, const bf16_t* __restrict__ A, const bf16_t* __restrict__ Bt, int M, int N, int K,
;                            int epi, bf16_t* __restrict__ outp, char* smem, int wvi) {
;     ...
;       for (int ai = 0; ai < 2; ++ai)
; #pragma unroll
;         for (int m = 0; m < 4; ++m) {
;           bf16_t* rp = outp + (size_t)(r0 + ai * GHALF + m * 16) * DFF + pn * 128 + wc * 32 + fq * 8;
;           unsigned pk[4];
; #pragma unroll
;           for (int bj = 0; bj < 2; ++bj) {
;             const f32x4 g = acc[ai][bj][m][0], u = acc[ai][bj][m][1];
;             const float o0 = silu_f(g[0]) * u[0], o1 = silu_f(g[1]) * u[1], o2 = silu_f(g[2]) * u[2], o3 = silu_f(g[3]) * u[3];
;             pk[2 * bj] = pk2(o0, o1); pk[2 * bj + 1] = pk2(o2, o3);
;           }
;           *reinterpret_cast<u32x4*>(rp) = mk4(pk[0], pk[1], pk[2], pk[3]);
;         }
	global_store_dwordx4 v[48:49], v[56:59], off
	v_mul_f32_e32 v48, 0xbfb8aa3b, v40
	v_mul_f32_e32 v49, 0xbfb8aa3b, v41
	v_exp_f32_e32 v48, v48
	v_exp_f32_e32 v49, v49
	v_add_u32_e32 v50, 0x90, v141
	v_add_f32_e32 v48, 1.0, v48
	v_add_f32_e32 v49, 1.0, v49
	v_rcp_f32_e32 v48, v48
	v_rcp_f32_e32 v49, v49
	s_nop 0
	v_pk_mul_f32 v[40:41], v[40:41], v[48:49]
	s_nop 0
	v_pk_mul_f32 v[40:41], v[44:45], v[40:41]
	v_mul_f32_e32 v44, 0xbfb8aa3b, v42
	v_mul_f32_e32 v45, 0xbfb8aa3b, v43
	v_exp_f32_e32 v44, v44
	v_exp_f32_e32 v45, v45
	v_cvt_pk_bf16_f32 v40, v40, v41
	v_add_f32_e32 v44, 1.0, v44
	v_add_f32_e32 v45, 1.0, v45
	v_rcp_f32_e32 v44, v44
	v_rcp_f32_e32 v45, v45
	s_nop 0
	v_pk_mul_f32 v[42:43], v[42:43], v[44:45]
	s_nop 0
	v_pk_mul_f32 v[42:43], v[46:47], v[42:43]
	s_nop 0
	v_cvt_pk_bf16_f32 v41, v42, v43
	v_mul_f32_e32 v42, 0xbfb8aa3b, v32
	v_mul_f32_e32 v43, 0xbfb8aa3b, v33
	v_exp_f32_e32 v42, v42
	v_exp_f32_e32 v43, v43
	v_add_f32_e32 v42, 1.0, v42
	v_add_f32_e32 v43, 1.0, v43
	v_rcp_f32_e32 v42, v42
	v_rcp_f32_e32 v43, v43
	s_nop 0
	v_pk_mul_f32 v[32:33], v[32:33], v[42:43]
	s_nop 0
	v_pk_mul_f32 v[32:33], v[36:37], v[32:33]
	v_mul_f32_e32 v36, 0xbfb8aa3b, v34
	v_mul_f32_e32 v37, 0xbfb8aa3b, v35
	v_exp_f32_e32 v36, v36
	v_exp_f32_e32 v37, v37
	v_cvt_pk_bf16_f32 v42, v32, v33
	v_mad_i64_i32 v[32:33], s[0:1], v50, s2, v[136:137]
	v_add_f32_e32 v36, 1.0, v36
	v_add_f32_e32 v37, 1.0, v37
	v_rcp_f32_e32 v36, v36
	v_rcp_f32_e32 v37, v37
	s_nop 0
	v_pk_mul_f32 v[34:35], v[34:35], v[36:37]
	s_nop 0
	v_pk_mul_f32 v[34:35], v[38:39], v[34:35]
	s_nop 0
	v_cvt_pk_bf16_f32 v43, v34, v35
	global_store_dwordx4 v[32:33], v[40:43], off
	v_mul_f32_e32 v32, 0xbfb8aa3b, v24
	v_mul_f32_e32 v33, 0xbfb8aa3b, v25
	v_exp_f32_e32 v32, v32
	v_exp_f32_e32 v33, v33
	v_add_u32_e32 v34, 0xa0, v141
	v_add_f32_e32 v32, 1.0, v32
	v_add_f32_e32 v33, 1.0, v33
	v_rcp_f32_e32 v32, v32
	v_rcp_f32_e32 v33, v33
	s_nop 0
	v_pk_mul_f32 v[24:25], v[24:25], v[32:33]
	s_nop 0
	v_pk_mul_f32 v[24:25], v[28:29], v[24:25]
	v_mul_f32_e32 v28, 0xbfb8aa3b, v26
	v_mul_f32_e32 v29, 0xbfb8aa3b, v27
	v_exp_f32_e32 v28, v28
	v_exp_f32_e32 v29, v29
	v_cvt_pk_bf16_f32 v24, v24, v25
	v_add_f32_e32 v28, 1.0, v28
	v_add_f32_e32 v29, 1.0, v29
	v_rcp_f32_e32 v28, v28
	v_rcp_f32_e32 v29, v29
	s_nop 0
	v_pk_mul_f32 v[26:27], v[26:27], v[28:29]
	s_nop 0
	v_pk_mul_f32 v[26:27], v[30:31], v[26:27]
	s_nop 0
	v_cvt_pk_bf16_f32 v25, v26, v27
	v_mul_f32_e32 v26, 0xbfb8aa3b, v16
	v_mul_f32_e32 v27, 0xbfb8aa3b, v17
	v_exp_f32_e32 v26, v26
	v_exp_f32_e32 v27, v27
	v_add_f32_e32 v26, 1.0, v26
	v_add_f32_e32 v27, 1.0, v27
	v_rcp_f32_e32 v26, v26
	v_rcp_f32_e32 v27, v27
	s_nop 0
	v_pk_mul_f32 v[16:17], v[16:17], v[26:27]
	s_nop 0
	v_pk_mul_f32 v[16:17], v[20:21], v[16:17]
	v_mul_f32_e32 v20, 0xbfb8aa3b, v18
	v_mul_f32_e32 v21, 0xbfb8aa3b, v19
	v_exp_f32_e32 v20, v20
	v_exp_f32_e32 v21, v21
	v_cvt_pk_bf16_f32 v26, v16, v17
	v_mad_i64_i32 v[16:17], s[0:1], v34, s2, v[136:137]
	v_add_f32_e32 v20, 1.0, v20
	v_add_f32_e32 v21, 1.0, v21
	v_rcp_f32_e32 v20, v20
	v_rcp_f32_e32 v21, v21
	s_nop 0
	v_pk_mul_f32 v[18:19], v[18:19], v[20:21]
	s_nop 0
	v_pk_mul_f32 v[18:19], v[22:23], v[18:19]
	s_nop 0
	v_cvt_pk_bf16_f32 v27, v18, v19
	global_store_dwordx4 v[16:17], v[24:27], off
	v_mul_f32_e32 v16, 0xbfb8aa3b, v8
	v_mul_f32_e32 v17, 0xbfb8aa3b, v9
	v_exp_f32_e32 v16, v16
	v_exp_f32_e32 v17, v17
	v_add_u32_e32 v18, 0xb0, v141
	v_add_f32_e32 v16, 1.0, v16
	v_add_f32_e32 v17, 1.0, v17
	v_rcp_f32_e32 v16, v16
	v_rcp_f32_e32 v17, v17
	s_nop 0
	v_pk_mul_f32 v[8:9], v[8:9], v[16:17]
	s_nop 0
	v_pk_mul_f32 v[8:9], v[12:13], v[8:9]
	v_mul_f32_e32 v12, 0xbfb8aa3b, v10
	v_mul_f32_e32 v13, 0xbfb8aa3b, v11
	v_exp_f32_e32 v12, v12
	v_exp_f32_e32 v13, v13
	v_cvt_pk_bf16_f32 v8, v8, v9
	v_add_f32_e32 v12, 1.0, v12
	v_add_f32_e32 v13, 1.0, v13
	v_rcp_f32_e32 v12, v12
	v_rcp_f32_e32 v13, v13
	s_nop 0
	v_pk_mul_f32 v[10:11], v[10:11], v[12:13]
	s_nop 0
	v_pk_mul_f32 v[10:11], v[14:15], v[10:11]
	s_nop 0
	v_cvt_pk_bf16_f32 v9, v10, v11
	v_mul_f32_e32 v10, 0xbfb8aa3b, v0
	v_mul_f32_e32 v11, 0xbfb8aa3b, v1
	v_exp_f32_e32 v10, v10
	v_exp_f32_e32 v11, v11
	v_add_f32_e32 v10, 1.0, v10
	v_add_f32_e32 v11, 1.0, v11
	v_rcp_f32_e32 v10, v10
	v_rcp_f32_e32 v11, v11
	s_nop 0
	v_pk_mul_f32 v[0:1], v[0:1], v[10:11]
	s_nop 0
	v_pk_mul_f32 v[0:1], v[4:5], v[0:1]
	v_mul_f32_e32 v4, 0xbfb8aa3b, v2
	v_mul_f32_e32 v5, 0xbfb8aa3b, v3
	v_exp_f32_e32 v4, v4
	v_exp_f32_e32 v5, v5
	v_cvt_pk_bf16_f32 v10, v0, v1
	v_mad_i64_i32 v[0:1], s[0:1], v18, s2, v[136:137]
	v_add_f32_e32 v4, 1.0, v4
	v_add_f32_e32 v5, 1.0, v5
	v_rcp_f32_e32 v4, v4
	v_rcp_f32_e32 v5, v5
	s_mov_b64 s[2:3], -1
	v_pk_mul_f32 v[2:3], v[2:3], v[4:5]
	s_nop 0
	v_pk_mul_f32 v[2:3], v[6:7], v[2:3]
	s_nop 0
	v_cvt_pk_bf16_f32 v11, v2, v3
	global_store_dwordx4 v[0:1], v[8:11], off
	s_cbranch_vccz .LBB0_1195
; __device__ __forceinline__ f32x4 zero4() { float z = 0.f; asm volatile("" : "+v"(z)); return (f32x4){z, z, z, z}; }
; __device__ __forceinline__ void gemm_phase(const Params& p, int l, const bf16_t* __restrict__ A, const bf16_t* __restrict__ Bt, int M, int N, int K,
;                            int epi, bf16_t* __restrict__ outp, char* smem, int wvi) {
;     ...
;       if (!has_next) break;
; #pragma unroll
;       for (int a = 0; a < 2; ++a)
; #pragma unroll
;         for (int b = 0; b < 2; ++b)
; #pragma unroll
;           for (int m = 0; m < 4; ++m)
; #pragma unroll
;             for (int n = 0; n < 2; ++n) acc[a][b][m][n] = zero4();
;       Lw = Ln; pm = npm; pn = npn; cA = nA; cB = nB;
	v_mov_b32_e32 v120, v177
	v_mov_b32_e32 v124, v177
	v_mov_b32_e32 v104, v177
	v_mov_b32_e32 v108, v177
	v_mov_b32_e32 v88, v177
	v_mov_b32_e32 v92, v177
	v_mov_b32_e32 v72, v177
	v_mov_b32_e32 v76, v177
	v_mov_b32_e32 v112, v177
	v_mov_b32_e32 v116, v177
	v_mov_b32_e32 v96, v177
	v_mov_b32_e32 v100, v177
	v_mov_b32_e32 v80, v177
	v_mov_b32_e32 v84, v177
	v_mov_b32_e32 v64, v177
	v_mov_b32_e32 v68, v177
	v_mov_b32_e32 v56, v177
	v_mov_b32_e32 v60, v177
	v_mov_b32_e32 v40, v177
	v_mov_b32_e32 v44, v177
	v_mov_b32_e32 v24, v177
	v_mov_b32_e32 v28, v177
	v_mov_b32_e32 v8, v177
	v_mov_b32_e32 v12, v177
	v_mov_b32_e32 v48, v177
	v_mov_b32_e32 v52, v177
	v_mov_b32_e32 v32, v177
	v_mov_b32_e32 v36, v177
	v_mov_b32_e32 v16, v177
	v_mov_b32_e32 v20, v177
	v_mov_b32_e32 v0, v177
	v_mov_b32_e32 v4, v177
	s_nop 0
	v_mov_b32_e32 v121, v120
	v_mov_b32_e32 v122, v120
	v_mov_b32_e32 v123, v120
	v_mov_b32_e32 v125, v124
	v_mov_b32_e32 v126, v124
	v_mov_b32_e32 v127, v124
	v_mov_b32_e32 v105, v104
	v_mov_b32_e32 v106, v104
	v_mov_b32_e32 v107, v104
	v_mov_b32_e32 v109, v108
	v_mov_b32_e32 v110, v108
	v_mov_b32_e32 v111, v108
	v_mov_b32_e32 v89, v88
	v_mov_b32_e32 v90, v88
	v_mov_b32_e32 v91, v88
	v_mov_b32_e32 v93, v92
	v_mov_b32_e32 v94, v92
	v_mov_b32_e32 v95, v92
	s_nop 0
	v_mov_b32_e32 v73, v72
	v_mov_b32_e32 v74, v72
	v_mov_b32_e32 v75, v72
	v_mov_b32_e32 v77, v76
	v_mov_b32_e32 v78, v76
	v_mov_b32_e32 v79, v76
	v_mov_b32_e32 v113, v112
	v_mov_b32_e32 v114, v112
	v_mov_b32_e32 v115, v112
	v_mov_b32_e32 v117, v116
	v_mov_b32_e32 v118, v116
	v_mov_b32_e32 v119, v116
	v_mov_b32_e32 v97, v96
	v_mov_b32_e32 v98, v96
	v_mov_b32_e32 v99, v96
	v_mov_b32_e32 v101, v100
	v_mov_b32_e32 v102, v100
	v_mov_b32_e32 v103, v100
	s_nop 0
	v_mov_b32_e32 v81, v80
	v_mov_b32_e32 v82, v80
	v_mov_b32_e32 v83, v80
	v_mov_b32_e32 v85, v84
	v_mov_b32_e32 v86, v84
	v_mov_b32_e32 v87, v84
	v_mov_b32_e32 v65, v64
	v_mov_b32_e32 v66, v64
	v_mov_b32_e32 v67, v64
	v_mov_b32_e32 v69, v68
	v_mov_b32_e32 v70, v68
	v_mov_b32_e32 v71, v68
	v_mov_b32_e32 v57, v56
	v_mov_b32_e32 v58, v56
	v_mov_b32_e32 v59, v56
	v_mov_b32_e32 v61, v60
	v_mov_b32_e32 v62, v60
	v_mov_b32_e32 v63, v60
	s_nop 0
	v_mov_b32_e32 v41, v40
	v_mov_b32_e32 v42, v40
	v_mov_b32_e32 v43, v40
	v_mov_b32_e32 v45, v44
	v_mov_b32_e32 v46, v44
	v_mov_b32_e32 v47, v44
	v_mov_b32_e32 v25, v24
	v_mov_b32_e32 v26, v24
	v_mov_b32_e32 v27, v24
	v_mov_b32_e32 v29, v28
	v_mov_b32_e32 v30, v28
	v_mov_b32_e32 v31, v28
	v_mov_b32_e32 v9, v8
	v_mov_b32_e32 v10, v8
	v_mov_b32_e32 v11, v8
	v_mov_b32_e32 v13, v12
	v_mov_b32_e32 v14, v12
	v_mov_b32_e32 v15, v12
	s_nop 0
	v_mov_b32_e32 v49, v48
	v_mov_b32_e32 v50, v48
	v_mov_b32_e32 v51, v48
	v_mov_b32_e32 v53, v52
	v_mov_b32_e32 v54, v52
	v_mov_b32_e32 v55, v52
	v_mov_b32_e32 v33, v32
	v_mov_b32_e32 v34, v32
	v_mov_b32_e32 v35, v32
	v_mov_b32_e32 v37, v36
	v_mov_b32_e32 v38, v36
	v_mov_b32_e32 v39, v36
	v_mov_b32_e32 v17, v16
	v_mov_b32_e32 v18, v16
	v_mov_b32_e32 v19, v16
	v_mov_b32_e32 v21, v20
	v_mov_b32_e32 v22, v20
	v_mov_b32_e32 v23, v20
	s_mov_b64 s[2:3], 0
	v_mov_b32_e32 v1, v0
	v_mov_b32_e32 v2, v0
	v_mov_b32_e32 v3, v0
	v_mov_b32_e32 v5, v4
	v_mov_b32_e32 v6, v4
	v_mov_b32_e32 v7, v4
	s_branch .LBB0_1195
